# k20: GEMM K-loops issue their LDS-DMA with the uniform SGPR pointer + 32-bit lane offset (saddr) instead of a 64-bit VALU add per load; the two pointer+stride bases per trip are formed by SALU
# baseline (speedup 1.0000x reference)
.LBB0_135:
	ds_read_b128 v[160:163], v156
	ds_read_b128 v[164:167], v156 offset:1024
	ds_read_b128 v[168:171], v156 offset:2048
	ds_read_b128 v[172:175], v156 offset:3072
	ds_read_b128 v[176:179], v157
	ds_read_b128 v[180:183], v157 offset:1024
	ds_read_b128 v[184:187], v157 offset:2048
	ds_read_b128 v[188:191], v157 offset:3072
	s_add_u32 s30, s28, 0xfffc0080
	s_addc_u32 s31, s29, -1
	s_cmp_eq_u32 s59, 12
	s_cselect_b32 s35, s0, s31
	s_cselect_b32 s34, s1, s30
	s_cselect_b32 s31, s19, s58
	s_cselect_b32 s30, s21, s53
	s_add_i32 m0, s27, 0xc000
	ds_read_b128 v[192:195], v158
	ds_read_b128 v[196:199], v158 offset:1024
	ds_read_b128 v[200:203], v158 offset:2048
	ds_read_b128 v[204:207], v158 offset:3072
	ds_read_b128 v[208:211], v158 offset:4096
	ds_read_b128 v[212:215], v158 offset:5120
	ds_read_b128 v[216:219], v158 offset:6144
	ds_read_b128 v[220:223], v158 offset:7168
	global_load_lds_dwordx4 v136, s[28:29]
	s_add_i32 m0, s27, 0xe000
	s_nop 0
	global_load_lds_dwordx4 v138, s[28:29]
	s_waitcnt vmcnt(8)
	s_waitcnt lgkmcnt(0)
	s_barrier
	s_setprio 1
	s_waitcnt lgkmcnt(0)
	v_mfma_f32_16x16x32_bf16 v[124:127], v[160:163], v[192:195], v[124:127]
	v_mfma_f32_16x16x32_bf16 v[120:123], v[168:171], v[192:195], v[120:123]
	v_mfma_f32_16x16x32_bf16 v[116:119], v[160:163], v[200:203], v[116:119]
	v_mfma_f32_16x16x32_bf16 v[108:111], v[168:171], v[200:203], v[108:111]
	v_mfma_f32_16x16x32_bf16 v[100:103], v[160:163], v[208:211], v[100:103]
	v_mfma_f32_16x16x32_bf16 v[92:95], v[168:171], v[208:211], v[92:95]
	v_mfma_f32_16x16x32_bf16 v[84:87], v[160:163], v[216:219], v[84:87]
	v_mfma_f32_16x16x32_bf16 v[76:79], v[168:171], v[216:219], v[76:79]
	v_mfma_f32_16x16x32_bf16 v[124:127], v[164:167], v[196:199], v[124:127]
	v_mfma_f32_16x16x32_bf16 v[120:123], v[172:175], v[196:199], v[120:123]
	v_mfma_f32_16x16x32_bf16 v[116:119], v[164:167], v[204:207], v[116:119]
	v_mfma_f32_16x16x32_bf16 v[108:111], v[172:175], v[204:207], v[108:111]
	v_mfma_f32_16x16x32_bf16 v[100:103], v[164:167], v[212:215], v[100:103]
	v_mfma_f32_16x16x32_bf16 v[92:95], v[172:175], v[212:215], v[92:95]
	v_mfma_f32_16x16x32_bf16 v[84:87], v[164:167], v[220:223], v[84:87]
	v_mfma_f32_16x16x32_bf16 v[76:79], v[172:175], v[220:223], v[76:79]
	s_setprio 0
	s_setprio 1
	v_mfma_f32_16x16x32_bf16 v[112:115], v[176:179], v[192:195], v[112:115]
	v_mfma_f32_16x16x32_bf16 v[104:107], v[184:187], v[192:195], v[104:107]
	v_mfma_f32_16x16x32_bf16 v[96:99], v[176:179], v[200:203], v[96:99]
	v_mfma_f32_16x16x32_bf16 v[88:91], v[184:187], v[200:203], v[88:91]
	v_mfma_f32_16x16x32_bf16 v[80:83], v[176:179], v[208:211], v[80:83]
	v_mfma_f32_16x16x32_bf16 v[72:75], v[184:187], v[208:211], v[72:75]
	v_mfma_f32_16x16x32_bf16 v[68:71], v[176:179], v[216:219], v[68:71]
	v_mfma_f32_16x16x32_bf16 v[64:67], v[184:187], v[216:219], v[64:67]
	v_mfma_f32_16x16x32_bf16 v[112:115], v[180:183], v[196:199], v[112:115]
	v_mfma_f32_16x16x32_bf16 v[104:107], v[188:191], v[196:199], v[104:107]
	v_mfma_f32_16x16x32_bf16 v[96:99], v[180:183], v[204:207], v[96:99]
	v_mfma_f32_16x16x32_bf16 v[88:91], v[188:191], v[204:207], v[88:91]
	v_mfma_f32_16x16x32_bf16 v[80:83], v[180:183], v[212:215], v[80:83]
	v_mfma_f32_16x16x32_bf16 v[72:75], v[188:191], v[212:215], v[72:75]
	v_mfma_f32_16x16x32_bf16 v[68:71], v[180:183], v[220:223], v[68:71]
	v_mfma_f32_16x16x32_bf16 v[64:67], v[188:191], v[220:223], v[64:67]
	s_setprio 0
	s_barrier
	s_add_i32 s44, s42, s33
	s_add_u32 s98, s30, s14
	s_addc_u32 s99, s31, s15
	s_mov_b32 m0, s44
	ds_read_b128 v[192:195], v158 offset:16384
	ds_read_b128 v[196:199], v158 offset:17408
	ds_read_b128 v[200:203], v158 offset:18432
	ds_read_b128 v[204:207], v158 offset:19456
	ds_read_b128 v[208:211], v158 offset:20480
	ds_read_b128 v[212:215], v158 offset:21504
	ds_read_b128 v[216:219], v158 offset:22528
	ds_read_b128 v[220:223], v158 offset:23552
	global_load_lds_dwordx4 v132, s[30:31]
	s_add_i32 m0, s44, 0x2000
	s_add_u32 s44, s30, 0x40000
	s_addc_u32 s45, s31, 0
	s_add_i32 s46, s43, s33
	global_load_lds_dwordx4 v128, s[30:31]
	s_mov_b32 m0, s46
	s_add_u32 s100, s34, s14
	s_addc_u32 s101, s35, s15
	global_load_lds_dwordx4 v132, s[44:45]
	s_add_i32 m0, s46, 0x2000
	s_nop 0
	global_load_lds_dwordx4 v128, s[44:45]
	s_mov_b32 m0, s27
	s_nop 0
	global_load_lds_dwordx4 v134, s[34:35]
	s_mov_b32 m0, s36
	s_nop 0
	global_load_lds_dwordx4 v130, s[34:35]
	s_waitcnt vmcnt(8)
	s_waitcnt lgkmcnt(0)
	s_barrier
	s_setprio 1
	s_waitcnt lgkmcnt(0)
	v_mfma_f32_16x16x32_bf16 v[60:63], v[160:163], v[192:195], v[60:63]
	v_mfma_f32_16x16x32_bf16 v[56:59], v[168:171], v[192:195], v[56:59]
	v_mfma_f32_16x16x32_bf16 v[52:55], v[160:163], v[200:203], v[52:55]
	v_mfma_f32_16x16x32_bf16 v[44:47], v[168:171], v[200:203], v[44:47]
	v_mfma_f32_16x16x32_bf16 v[36:39], v[160:163], v[208:211], v[36:39]
	v_mfma_f32_16x16x32_bf16 v[28:31], v[168:171], v[208:211], v[28:31]
	v_mfma_f32_16x16x32_bf16 v[20:23], v[160:163], v[216:219], v[20:23]
	v_mfma_f32_16x16x32_bf16 v[12:15], v[168:171], v[216:219], v[12:15]
	v_mfma_f32_16x16x32_bf16 v[60:63], v[164:167], v[196:199], v[60:63]
	v_mfma_f32_16x16x32_bf16 v[56:59], v[172:175], v[196:199], v[56:59]
	v_mfma_f32_16x16x32_bf16 v[52:55], v[164:167], v[204:207], v[52:55]
	v_mfma_f32_16x16x32_bf16 v[44:47], v[172:175], v[204:207], v[44:47]
	v_mfma_f32_16x16x32_bf16 v[36:39], v[164:167], v[212:215], v[36:39]
	v_mfma_f32_16x16x32_bf16 v[28:31], v[172:175], v[212:215], v[28:31]
	v_mfma_f32_16x16x32_bf16 v[20:23], v[164:167], v[220:223], v[20:23]
	v_mfma_f32_16x16x32_bf16 v[12:15], v[172:175], v[220:223], v[12:15]
	s_setprio 0
	s_setprio 1
	v_mfma_f32_16x16x32_bf16 v[48:51], v[176:179], v[192:195], v[48:51]
	v_mfma_f32_16x16x32_bf16 v[40:43], v[184:187], v[192:195], v[40:43]
	v_mfma_f32_16x16x32_bf16 v[32:35], v[176:179], v[200:203], v[32:35]
	v_mfma_f32_16x16x32_bf16 v[24:27], v[184:187], v[200:203], v[24:27]
	v_mfma_f32_16x16x32_bf16 v[16:19], v[176:179], v[208:211], v[16:19]
	v_mfma_f32_16x16x32_bf16 v[8:11], v[184:187], v[208:211], v[8:11]
	v_mfma_f32_16x16x32_bf16 v[4:7], v[176:179], v[216:219], v[4:7]
	v_mfma_f32_16x16x32_bf16 v[0:3], v[184:187], v[216:219], v[0:3]
	v_mfma_f32_16x16x32_bf16 v[48:51], v[180:183], v[196:199], v[48:51]
	v_mfma_f32_16x16x32_bf16 v[40:43], v[188:191], v[196:199], v[40:43]
	v_mfma_f32_16x16x32_bf16 v[32:35], v[180:183], v[204:207], v[32:35]
	v_mfma_f32_16x16x32_bf16 v[24:27], v[188:191], v[204:207], v[24:27]
	v_mfma_f32_16x16x32_bf16 v[16:19], v[180:183], v[212:215], v[16:19]
	v_mfma_f32_16x16x32_bf16 v[8:11], v[188:191], v[212:215], v[8:11]
	v_mfma_f32_16x16x32_bf16 v[4:7], v[180:183], v[220:223], v[4:7]
	v_mfma_f32_16x16x32_bf16 v[0:3], v[188:191], v[220:223], v[0:3]
	s_setprio 0
	s_barrier
	s_add_i32 s44, 0, 0x18000
	v_add_u32_e32 v159, s44, v147
	s_add_i32 s45, 0, 0x1c000
	ds_read_b128 v[160:163], v159
	ds_read_b128 v[164:167], v159 offset:1024
	ds_read_b128 v[168:171], v159 offset:2048
	ds_read_b128 v[172:175], v159 offset:3072
	v_add_u32_e32 v159, s45, v147
	ds_read_b128 v[176:179], v159
	ds_read_b128 v[180:183], v159 offset:1024
	ds_read_b128 v[184:187], v159 offset:2048
	ds_read_b128 v[188:191], v159 offset:3072
	s_add_u32 s34, s34, 0x40000
	s_addc_u32 s35, s35, 0
	s_mov_b32 m0, s37
	ds_read_b128 v[192:195], v158 offset:32768
	ds_read_b128 v[196:199], v158 offset:33792
	ds_read_b128 v[200:203], v158 offset:34816
	ds_read_b128 v[204:207], v158 offset:35840
	ds_read_b128 v[208:211], v158 offset:36864
	ds_read_b128 v[212:215], v158 offset:37888
	ds_read_b128 v[216:219], v158 offset:38912
	ds_read_b128 v[220:223], v158 offset:39936
	global_load_lds_dwordx4 v134, s[34:35]
	s_mov_b32 m0, s38
	s_nop 0
	global_load_lds_dwordx4 v130, s[34:35]
	s_waitcnt vmcnt(8)
	s_waitcnt lgkmcnt(0)
	s_barrier
	s_setprio 1
	s_waitcnt lgkmcnt(0)
	v_mfma_f32_16x16x32_bf16 v[124:127], v[160:163], v[192:195], v[124:127]
	v_mfma_f32_16x16x32_bf16 v[120:123], v[168:171], v[192:195], v[120:123]
	v_mfma_f32_16x16x32_bf16 v[116:119], v[160:163], v[200:203], v[116:119]
	v_mfma_f32_16x16x32_bf16 v[108:111], v[168:171], v[200:203], v[108:111]
	v_mfma_f32_16x16x32_bf16 v[100:103], v[160:163], v[208:211], v[100:103]
	v_mfma_f32_16x16x32_bf16 v[92:95], v[168:171], v[208:211], v[92:95]
	v_mfma_f32_16x16x32_bf16 v[84:87], v[160:163], v[216:219], v[84:87]
	v_mfma_f32_16x16x32_bf16 v[76:79], v[168:171], v[216:219], v[76:79]
	v_mfma_f32_16x16x32_bf16 v[124:127], v[164:167], v[196:199], v[124:127]
	v_mfma_f32_16x16x32_bf16 v[120:123], v[172:175], v[196:199], v[120:123]
	v_mfma_f32_16x16x32_bf16 v[116:119], v[164:167], v[204:207], v[116:119]
	v_mfma_f32_16x16x32_bf16 v[108:111], v[172:175], v[204:207], v[108:111]
	v_mfma_f32_16x16x32_bf16 v[100:103], v[164:167], v[212:215], v[100:103]
	v_mfma_f32_16x16x32_bf16 v[92:95], v[172:175], v[212:215], v[92:95]
	v_mfma_f32_16x16x32_bf16 v[84:87], v[164:167], v[220:223], v[84:87]
	v_mfma_f32_16x16x32_bf16 v[76:79], v[172:175], v[220:223], v[76:79]
	s_setprio 0
	s_setprio 1
	v_mfma_f32_16x16x32_bf16 v[112:115], v[176:179], v[192:195], v[112:115]
	v_mfma_f32_16x16x32_bf16 v[104:107], v[184:187], v[192:195], v[104:107]
	v_mfma_f32_16x16x32_bf16 v[96:99], v[176:179], v[200:203], v[96:99]
	v_mfma_f32_16x16x32_bf16 v[88:91], v[184:187], v[200:203], v[88:91]
	v_mfma_f32_16x16x32_bf16 v[80:83], v[176:179], v[208:211], v[80:83]
	v_mfma_f32_16x16x32_bf16 v[72:75], v[184:187], v[208:211], v[72:75]
	v_mfma_f32_16x16x32_bf16 v[68:71], v[176:179], v[216:219], v[68:71]
	v_mfma_f32_16x16x32_bf16 v[64:67], v[184:187], v[216:219], v[64:67]
	v_mfma_f32_16x16x32_bf16 v[112:115], v[180:183], v[196:199], v[112:115]
	v_mfma_f32_16x16x32_bf16 v[104:107], v[188:191], v[196:199], v[104:107]
	v_mfma_f32_16x16x32_bf16 v[96:99], v[180:183], v[204:207], v[96:99]
	v_mfma_f32_16x16x32_bf16 v[88:91], v[188:191], v[204:207], v[88:91]
	v_mfma_f32_16x16x32_bf16 v[80:83], v[180:183], v[212:215], v[80:83]
	v_mfma_f32_16x16x32_bf16 v[72:75], v[188:191], v[212:215], v[72:75]
	v_mfma_f32_16x16x32_bf16 v[68:71], v[180:183], v[220:223], v[68:71]
	v_mfma_f32_16x16x32_bf16 v[64:67], v[188:191], v[220:223], v[64:67]
	s_setprio 0
	s_barrier
	s_add_i32 s34, s44, s33
	s_mov_b32 m0, s34
	ds_read_b128 v[192:195], v158 offset:49152
	ds_read_b128 v[196:199], v158 offset:50176
	ds_read_b128 v[200:203], v158 offset:51200
	ds_read_b128 v[204:207], v158 offset:52224
	ds_read_b128 v[208:211], v158 offset:53248
	ds_read_b128 v[212:215], v158 offset:54272
	ds_read_b128 v[216:219], v158 offset:55296
	ds_read_b128 v[220:223], v158 offset:56320
	global_load_lds_dwordx4 v132, s[98:99]
	s_add_i32 m0, s34, 0x2000
	s_add_u32 s30, s30, 0x40080
	s_addc_u32 s31, s31, 0
	s_add_i32 s34, s45, s33
	global_load_lds_dwordx4 v128, s[98:99]
	s_mov_b32 m0, s34
	s_nop 0
	global_load_lds_dwordx4 v132, s[30:31]
	s_add_i32 m0, s34, 0x2000
	s_nop 0
	global_load_lds_dwordx4 v128, s[30:31]
	s_mov_b32 m0, s39
	s_nop 0
	global_load_lds_dwordx4 v134, s[100:101]
	s_mov_b32 m0, s40
	s_nop 0
	global_load_lds_dwordx4 v130, s[100:101]
	s_waitcnt vmcnt(8)
	s_waitcnt lgkmcnt(0)
	s_barrier
	s_setprio 1
	s_waitcnt lgkmcnt(0)
	v_mfma_f32_16x16x32_bf16 v[60:63], v[160:163], v[192:195], v[60:63]
	v_mfma_f32_16x16x32_bf16 v[56:59], v[168:171], v[192:195], v[56:59]
	v_mfma_f32_16x16x32_bf16 v[52:55], v[160:163], v[200:203], v[52:55]
	v_mfma_f32_16x16x32_bf16 v[44:47], v[168:171], v[200:203], v[44:47]
	v_mfma_f32_16x16x32_bf16 v[36:39], v[160:163], v[208:211], v[36:39]
	v_mfma_f32_16x16x32_bf16 v[28:31], v[168:171], v[208:211], v[28:31]
	v_mfma_f32_16x16x32_bf16 v[20:23], v[160:163], v[216:219], v[20:23]
	v_mfma_f32_16x16x32_bf16 v[12:15], v[168:171], v[216:219], v[12:15]
	v_mfma_f32_16x16x32_bf16 v[60:63], v[164:167], v[196:199], v[60:63]
	v_mfma_f32_16x16x32_bf16 v[56:59], v[172:175], v[196:199], v[56:59]
	v_mfma_f32_16x16x32_bf16 v[52:55], v[164:167], v[204:207], v[52:55]
	v_mfma_f32_16x16x32_bf16 v[44:47], v[172:175], v[204:207], v[44:47]
	v_mfma_f32_16x16x32_bf16 v[36:39], v[164:167], v[212:215], v[36:39]
	v_mfma_f32_16x16x32_bf16 v[28:31], v[172:175], v[212:215], v[28:31]
	v_mfma_f32_16x16x32_bf16 v[20:23], v[164:167], v[220:223], v[20:23]
	v_mfma_f32_16x16x32_bf16 v[12:15], v[172:175], v[220:223], v[12:15]
	s_setprio 0
	s_setprio 1
	v_mfma_f32_16x16x32_bf16 v[48:51], v[176:179], v[192:195], v[48:51]
	v_mfma_f32_16x16x32_bf16 v[40:43], v[184:187], v[192:195], v[40:43]
	v_mfma_f32_16x16x32_bf16 v[32:35], v[176:179], v[200:203], v[32:35]
	v_mfma_f32_16x16x32_bf16 v[24:27], v[184:187], v[200:203], v[24:27]
	v_mfma_f32_16x16x32_bf16 v[16:19], v[176:179], v[208:211], v[16:19]
	v_mfma_f32_16x16x32_bf16 v[8:11], v[184:187], v[208:211], v[8:11]
	v_mfma_f32_16x16x32_bf16 v[4:7], v[176:179], v[216:219], v[4:7]
	v_mfma_f32_16x16x32_bf16 v[0:3], v[184:187], v[216:219], v[0:3]
	v_mfma_f32_16x16x32_bf16 v[48:51], v[180:183], v[196:199], v[48:51]
	v_mfma_f32_16x16x32_bf16 v[40:43], v[188:191], v[196:199], v[40:43]
	v_mfma_f32_16x16x32_bf16 v[32:35], v[180:183], v[204:207], v[32:35]
	v_mfma_f32_16x16x32_bf16 v[24:27], v[188:191], v[204:207], v[24:27]
	v_mfma_f32_16x16x32_bf16 v[16:19], v[180:183], v[212:215], v[16:19]
	v_mfma_f32_16x16x32_bf16 v[8:11], v[188:191], v[212:215], v[8:11]
	v_mfma_f32_16x16x32_bf16 v[4:7], v[180:183], v[220:223], v[4:7]
	v_mfma_f32_16x16x32_bf16 v[0:3], v[188:191], v[220:223], v[0:3]
	s_setprio 0
	s_barrier
	s_add_i32 s59, s59, 2
	s_add_u32 s28, s28, 0x100
	s_addc_u32 s29, s29, 0
	s_add_u32 s53, s53, 0x100
	s_addc_u32 s58, s58, 0
	s_cmp_gt_u32 s59, 13
	s_cbranch_scc0 .LBB0_135
	s_and_b64 vcc, exec, s[16:17]
	s_cbranch_vccz .LBB0_138
	s_barrier

.LBB0_155:
	ds_read_b128 v[160:163], v156
	ds_read_b128 v[164:167], v156 offset:1024
	ds_read_b128 v[168:171], v156 offset:2048
	ds_read_b128 v[172:175], v156 offset:3072
	ds_read_b128 v[176:179], v157
	ds_read_b128 v[180:183], v157 offset:1024
	ds_read_b128 v[184:187], v157 offset:2048
	ds_read_b128 v[188:191], v157 offset:3072
	s_add_u32 s30, s28, 0xfffc0080
	s_addc_u32 s31, s29, -1
	s_cmp_eq_u32 s59, 12
	s_cselect_b32 s35, s0, s31
	s_cselect_b32 s34, s1, s30
	s_cselect_b32 s31, s19, s58
	s_cselect_b32 s30, s21, s43
	s_add_i32 m0, s25, 0xc000
	ds_read_b128 v[192:195], v158
	ds_read_b128 v[196:199], v158 offset:1024
	ds_read_b128 v[200:203], v158 offset:2048
	ds_read_b128 v[204:207], v158 offset:3072
	ds_read_b128 v[208:211], v158 offset:4096
	ds_read_b128 v[212:215], v158 offset:5120
	ds_read_b128 v[216:219], v158 offset:6144
	ds_read_b128 v[220:223], v158 offset:7168
	global_load_lds_dwordx4 v136, s[28:29]
	s_add_i32 m0, s25, 0xe000
	s_nop 0
	global_load_lds_dwordx4 v138, s[28:29]
	s_waitcnt vmcnt(8)
	s_waitcnt lgkmcnt(0)
	s_barrier
	s_setprio 1
	s_waitcnt lgkmcnt(0)
	v_mfma_f32_16x16x32_bf16 v[124:127], v[160:163], v[192:195], v[124:127]
	v_mfma_f32_16x16x32_bf16 v[120:123], v[168:171], v[192:195], v[120:123]
	v_mfma_f32_16x16x32_bf16 v[116:119], v[160:163], v[200:203], v[116:119]
	v_mfma_f32_16x16x32_bf16 v[108:111], v[168:171], v[200:203], v[108:111]
	v_mfma_f32_16x16x32_bf16 v[100:103], v[160:163], v[208:211], v[100:103]
	v_mfma_f32_16x16x32_bf16 v[92:95], v[168:171], v[208:211], v[92:95]
	v_mfma_f32_16x16x32_bf16 v[84:87], v[160:163], v[216:219], v[84:87]
	v_mfma_f32_16x16x32_bf16 v[76:79], v[168:171], v[216:219], v[76:79]
	v_mfma_f32_16x16x32_bf16 v[124:127], v[164:167], v[196:199], v[124:127]
	v_mfma_f32_16x16x32_bf16 v[120:123], v[172:175], v[196:199], v[120:123]
	v_mfma_f32_16x16x32_bf16 v[116:119], v[164:167], v[204:207], v[116:119]
	v_mfma_f32_16x16x32_bf16 v[108:111], v[172:175], v[204:207], v[108:111]
	v_mfma_f32_16x16x32_bf16 v[100:103], v[164:167], v[212:215], v[100:103]
	v_mfma_f32_16x16x32_bf16 v[92:95], v[172:175], v[212:215], v[92:95]
	v_mfma_f32_16x16x32_bf16 v[84:87], v[164:167], v[220:223], v[84:87]
	v_mfma_f32_16x16x32_bf16 v[76:79], v[172:175], v[220:223], v[76:79]
	s_setprio 0
	s_setprio 1
	v_mfma_f32_16x16x32_bf16 v[112:115], v[176:179], v[192:195], v[112:115]
	v_mfma_f32_16x16x32_bf16 v[104:107], v[184:187], v[192:195], v[104:107]
	v_mfma_f32_16x16x32_bf16 v[96:99], v[176:179], v[200:203], v[96:99]
	v_mfma_f32_16x16x32_bf16 v[88:91], v[184:187], v[200:203], v[88:91]
	v_mfma_f32_16x16x32_bf16 v[80:83], v[176:179], v[208:211], v[80:83]
	v_mfma_f32_16x16x32_bf16 v[72:75], v[184:187], v[208:211], v[72:75]
	v_mfma_f32_16x16x32_bf16 v[68:71], v[176:179], v[216:219], v[68:71]
	v_mfma_f32_16x16x32_bf16 v[64:67], v[184:187], v[216:219], v[64:67]
	v_mfma_f32_16x16x32_bf16 v[112:115], v[180:183], v[196:199], v[112:115]
	v_mfma_f32_16x16x32_bf16 v[104:107], v[188:191], v[196:199], v[104:107]
	v_mfma_f32_16x16x32_bf16 v[96:99], v[180:183], v[204:207], v[96:99]
	v_mfma_f32_16x16x32_bf16 v[88:91], v[188:191], v[204:207], v[88:91]
	v_mfma_f32_16x16x32_bf16 v[80:83], v[180:183], v[212:215], v[80:83]
	v_mfma_f32_16x16x32_bf16 v[72:75], v[188:191], v[212:215], v[72:75]
	v_mfma_f32_16x16x32_bf16 v[68:71], v[180:183], v[220:223], v[68:71]
	v_mfma_f32_16x16x32_bf16 v[64:67], v[188:191], v[220:223], v[64:67]
	s_setprio 0
	s_barrier
	s_add_i32 s44, s40, s5
	s_add_u32 s98, s30, s14
	s_addc_u32 s99, s31, s15
	s_mov_b32 m0, s44
	ds_read_b128 v[192:195], v158 offset:16384
	ds_read_b128 v[196:199], v158 offset:17408
	ds_read_b128 v[200:203], v158 offset:18432
	ds_read_b128 v[204:207], v158 offset:19456
	ds_read_b128 v[208:211], v158 offset:20480
	ds_read_b128 v[212:215], v158 offset:21504
	ds_read_b128 v[216:219], v158 offset:22528
	ds_read_b128 v[220:223], v158 offset:23552
	global_load_lds_dwordx4 v132, s[30:31]
	s_add_i32 m0, s44, 0x2000
	s_add_u32 s44, s30, 0x40000
	s_addc_u32 s45, s31, 0
	s_add_i32 s46, s41, s5
	global_load_lds_dwordx4 v128, s[30:31]
	s_mov_b32 m0, s46
	s_add_u32 s100, s34, s14
	s_addc_u32 s101, s35, s15
	global_load_lds_dwordx4 v132, s[44:45]
	s_add_i32 m0, s46, 0x2000
	s_nop 0
	global_load_lds_dwordx4 v128, s[44:45]
	s_mov_b32 m0, s25
	s_nop 0
	global_load_lds_dwordx4 v134, s[34:35]
	s_mov_b32 m0, s33
	s_nop 0
	global_load_lds_dwordx4 v130, s[34:35]
	s_waitcnt vmcnt(8)
	s_waitcnt lgkmcnt(0)
	s_barrier
	s_setprio 1
	s_waitcnt lgkmcnt(0)
	v_mfma_f32_16x16x32_bf16 v[60:63], v[160:163], v[192:195], v[60:63]
	v_mfma_f32_16x16x32_bf16 v[56:59], v[168:171], v[192:195], v[56:59]
	v_mfma_f32_16x16x32_bf16 v[52:55], v[160:163], v[200:203], v[52:55]
	v_mfma_f32_16x16x32_bf16 v[44:47], v[168:171], v[200:203], v[44:47]
	v_mfma_f32_16x16x32_bf16 v[36:39], v[160:163], v[208:211], v[36:39]
	v_mfma_f32_16x16x32_bf16 v[28:31], v[168:171], v[208:211], v[28:31]
	v_mfma_f32_16x16x32_bf16 v[16:19], v[160:163], v[216:219], v[16:19]
	v_mfma_f32_16x16x32_bf16 v[8:11], v[168:171], v[216:219], v[8:11]
	v_mfma_f32_16x16x32_bf16 v[60:63], v[164:167], v[196:199], v[60:63]
	v_mfma_f32_16x16x32_bf16 v[56:59], v[172:175], v[196:199], v[56:59]
	v_mfma_f32_16x16x32_bf16 v[52:55], v[164:167], v[204:207], v[52:55]
	v_mfma_f32_16x16x32_bf16 v[44:47], v[172:175], v[204:207], v[44:47]
	v_mfma_f32_16x16x32_bf16 v[36:39], v[164:167], v[212:215], v[36:39]
	v_mfma_f32_16x16x32_bf16 v[28:31], v[172:175], v[212:215], v[28:31]
	v_mfma_f32_16x16x32_bf16 v[16:19], v[164:167], v[220:223], v[16:19]
	v_mfma_f32_16x16x32_bf16 v[8:11], v[172:175], v[220:223], v[8:11]
	s_setprio 0
	s_setprio 1
	v_mfma_f32_16x16x32_bf16 v[48:51], v[176:179], v[192:195], v[48:51]
	v_mfma_f32_16x16x32_bf16 v[40:43], v[184:187], v[192:195], v[40:43]
	v_mfma_f32_16x16x32_bf16 v[32:35], v[176:179], v[200:203], v[32:35]
	v_mfma_f32_16x16x32_bf16 v[24:27], v[184:187], v[200:203], v[24:27]
	v_mfma_f32_16x16x32_bf16 v[20:23], v[176:179], v[208:211], v[20:23]
	v_mfma_f32_16x16x32_bf16 v[12:15], v[184:187], v[208:211], v[12:15]
	v_mfma_f32_16x16x32_bf16 v[4:7], v[176:179], v[216:219], v[4:7]
	v_mfma_f32_16x16x32_bf16 v[0:3], v[184:187], v[216:219], v[0:3]
	v_mfma_f32_16x16x32_bf16 v[48:51], v[180:183], v[196:199], v[48:51]
	v_mfma_f32_16x16x32_bf16 v[40:43], v[188:191], v[196:199], v[40:43]
	v_mfma_f32_16x16x32_bf16 v[32:35], v[180:183], v[204:207], v[32:35]
	v_mfma_f32_16x16x32_bf16 v[24:27], v[188:191], v[204:207], v[24:27]
	v_mfma_f32_16x16x32_bf16 v[20:23], v[180:183], v[212:215], v[20:23]
	v_mfma_f32_16x16x32_bf16 v[12:15], v[188:191], v[212:215], v[12:15]
	v_mfma_f32_16x16x32_bf16 v[4:7], v[180:183], v[220:223], v[4:7]
	v_mfma_f32_16x16x32_bf16 v[0:3], v[188:191], v[220:223], v[0:3]
	s_setprio 0
	s_barrier
	s_add_i32 s44, 0, 0x18000
	v_add_u32_e32 v159, s44, v147
	s_add_i32 s45, 0, 0x1c000
	ds_read_b128 v[160:163], v159
	ds_read_b128 v[164:167], v159 offset:1024
	ds_read_b128 v[168:171], v159 offset:2048
	ds_read_b128 v[172:175], v159 offset:3072
	v_add_u32_e32 v159, s45, v147
	ds_read_b128 v[176:179], v159
	ds_read_b128 v[180:183], v159 offset:1024
	ds_read_b128 v[184:187], v159 offset:2048
	ds_read_b128 v[188:191], v159 offset:3072
	s_add_u32 s34, s34, 0x40000
	s_addc_u32 s35, s35, 0
	s_mov_b32 m0, s36
	ds_read_b128 v[192:195], v158 offset:32768
	ds_read_b128 v[196:199], v158 offset:33792
	ds_read_b128 v[200:203], v158 offset:34816
	ds_read_b128 v[204:207], v158 offset:35840
	ds_read_b128 v[208:211], v158 offset:36864
	ds_read_b128 v[212:215], v158 offset:37888
	ds_read_b128 v[216:219], v158 offset:38912
	ds_read_b128 v[220:223], v158 offset:39936
	global_load_lds_dwordx4 v134, s[34:35]
	s_mov_b32 m0, s37
	s_nop 0
	global_load_lds_dwordx4 v130, s[34:35]
	s_waitcnt vmcnt(8)
	s_waitcnt lgkmcnt(0)
	s_barrier
	s_setprio 1
	s_waitcnt lgkmcnt(0)
	v_mfma_f32_16x16x32_bf16 v[124:127], v[160:163], v[192:195], v[124:127]
	v_mfma_f32_16x16x32_bf16 v[120:123], v[168:171], v[192:195], v[120:123]
	v_mfma_f32_16x16x32_bf16 v[116:119], v[160:163], v[200:203], v[116:119]
	v_mfma_f32_16x16x32_bf16 v[108:111], v[168:171], v[200:203], v[108:111]
	v_mfma_f32_16x16x32_bf16 v[100:103], v[160:163], v[208:211], v[100:103]
	v_mfma_f32_16x16x32_bf16 v[92:95], v[168:171], v[208:211], v[92:95]
	v_mfma_f32_16x16x32_bf16 v[84:87], v[160:163], v[216:219], v[84:87]
	v_mfma_f32_16x16x32_bf16 v[76:79], v[168:171], v[216:219], v[76:79]
	v_mfma_f32_16x16x32_bf16 v[124:127], v[164:167], v[196:199], v[124:127]
	v_mfma_f32_16x16x32_bf16 v[120:123], v[172:175], v[196:199], v[120:123]
	v_mfma_f32_16x16x32_bf16 v[116:119], v[164:167], v[204:207], v[116:119]
	v_mfma_f32_16x16x32_bf16 v[108:111], v[172:175], v[204:207], v[108:111]
	v_mfma_f32_16x16x32_bf16 v[100:103], v[164:167], v[212:215], v[100:103]
	v_mfma_f32_16x16x32_bf16 v[92:95], v[172:175], v[212:215], v[92:95]
	v_mfma_f32_16x16x32_bf16 v[84:87], v[164:167], v[220:223], v[84:87]
	v_mfma_f32_16x16x32_bf16 v[76:79], v[172:175], v[220:223], v[76:79]
	s_setprio 0
	s_setprio 1
	v_mfma_f32_16x16x32_bf16 v[112:115], v[176:179], v[192:195], v[112:115]
	v_mfma_f32_16x16x32_bf16 v[104:107], v[184:187], v[192:195], v[104:107]
	v_mfma_f32_16x16x32_bf16 v[96:99], v[176:179], v[200:203], v[96:99]
	v_mfma_f32_16x16x32_bf16 v[88:91], v[184:187], v[200:203], v[88:91]
	v_mfma_f32_16x16x32_bf16 v[80:83], v[176:179], v[208:211], v[80:83]
	v_mfma_f32_16x16x32_bf16 v[72:75], v[184:187], v[208:211], v[72:75]
	v_mfma_f32_16x16x32_bf16 v[68:71], v[176:179], v[216:219], v[68:71]
	v_mfma_f32_16x16x32_bf16 v[64:67], v[184:187], v[216:219], v[64:67]
	v_mfma_f32_16x16x32_bf16 v[112:115], v[180:183], v[196:199], v[112:115]
	v_mfma_f32_16x16x32_bf16 v[104:107], v[188:191], v[196:199], v[104:107]
	v_mfma_f32_16x16x32_bf16 v[96:99], v[180:183], v[204:207], v[96:99]
	v_mfma_f32_16x16x32_bf16 v[88:91], v[188:191], v[204:207], v[88:91]
	v_mfma_f32_16x16x32_bf16 v[80:83], v[180:183], v[212:215], v[80:83]
	v_mfma_f32_16x16x32_bf16 v[72:75], v[188:191], v[212:215], v[72:75]
	v_mfma_f32_16x16x32_bf16 v[68:71], v[180:183], v[220:223], v[68:71]
	v_mfma_f32_16x16x32_bf16 v[64:67], v[188:191], v[220:223], v[64:67]
	s_setprio 0
	s_barrier
	s_add_i32 s34, s44, s5
	s_mov_b32 m0, s34
	ds_read_b128 v[192:195], v158 offset:49152
	ds_read_b128 v[196:199], v158 offset:50176
	ds_read_b128 v[200:203], v158 offset:51200
	ds_read_b128 v[204:207], v158 offset:52224
	ds_read_b128 v[208:211], v158 offset:53248
	ds_read_b128 v[212:215], v158 offset:54272
	ds_read_b128 v[216:219], v158 offset:55296
	ds_read_b128 v[220:223], v158 offset:56320
	global_load_lds_dwordx4 v132, s[98:99]
	s_add_i32 m0, s34, 0x2000
	s_add_u32 s30, s30, 0x40080
	s_addc_u32 s31, s31, 0
	s_add_i32 s34, s45, s5
	global_load_lds_dwordx4 v128, s[98:99]
	s_mov_b32 m0, s34
	s_nop 0
	global_load_lds_dwordx4 v132, s[30:31]
	s_add_i32 m0, s34, 0x2000
	s_nop 0
	global_load_lds_dwordx4 v128, s[30:31]
	s_mov_b32 m0, s4
	s_nop 0
	global_load_lds_dwordx4 v134, s[100:101]
	s_mov_b32 m0, s39
	s_nop 0
	global_load_lds_dwordx4 v130, s[100:101]
	s_waitcnt vmcnt(8)
	s_waitcnt lgkmcnt(0)
	s_barrier
	s_setprio 1
	s_waitcnt lgkmcnt(0)
	v_mfma_f32_16x16x32_bf16 v[60:63], v[160:163], v[192:195], v[60:63]
	v_mfma_f32_16x16x32_bf16 v[56:59], v[168:171], v[192:195], v[56:59]
	v_mfma_f32_16x16x32_bf16 v[52:55], v[160:163], v[200:203], v[52:55]
	v_mfma_f32_16x16x32_bf16 v[44:47], v[168:171], v[200:203], v[44:47]
	v_mfma_f32_16x16x32_bf16 v[36:39], v[160:163], v[208:211], v[36:39]
	v_mfma_f32_16x16x32_bf16 v[28:31], v[168:171], v[208:211], v[28:31]
	v_mfma_f32_16x16x32_bf16 v[16:19], v[160:163], v[216:219], v[16:19]
	v_mfma_f32_16x16x32_bf16 v[8:11], v[168:171], v[216:219], v[8:11]
	v_mfma_f32_16x16x32_bf16 v[60:63], v[164:167], v[196:199], v[60:63]
	v_mfma_f32_16x16x32_bf16 v[56:59], v[172:175], v[196:199], v[56:59]
	v_mfma_f32_16x16x32_bf16 v[52:55], v[164:167], v[204:207], v[52:55]
	v_mfma_f32_16x16x32_bf16 v[44:47], v[172:175], v[204:207], v[44:47]
	v_mfma_f32_16x16x32_bf16 v[36:39], v[164:167], v[212:215], v[36:39]
	v_mfma_f32_16x16x32_bf16 v[28:31], v[172:175], v[212:215], v[28:31]
	v_mfma_f32_16x16x32_bf16 v[16:19], v[164:167], v[220:223], v[16:19]
	v_mfma_f32_16x16x32_bf16 v[8:11], v[172:175], v[220:223], v[8:11]
	s_setprio 0
	s_setprio 1
	v_mfma_f32_16x16x32_bf16 v[48:51], v[176:179], v[192:195], v[48:51]
	v_mfma_f32_16x16x32_bf16 v[40:43], v[184:187], v[192:195], v[40:43]
	v_mfma_f32_16x16x32_bf16 v[32:35], v[176:179], v[200:203], v[32:35]
	v_mfma_f32_16x16x32_bf16 v[24:27], v[184:187], v[200:203], v[24:27]
	v_mfma_f32_16x16x32_bf16 v[20:23], v[176:179], v[208:211], v[20:23]
	v_mfma_f32_16x16x32_bf16 v[12:15], v[184:187], v[208:211], v[12:15]
	v_mfma_f32_16x16x32_bf16 v[4:7], v[176:179], v[216:219], v[4:7]
	v_mfma_f32_16x16x32_bf16 v[0:3], v[184:187], v[216:219], v[0:3]
	v_mfma_f32_16x16x32_bf16 v[48:51], v[180:183], v[196:199], v[48:51]
	v_mfma_f32_16x16x32_bf16 v[40:43], v[188:191], v[196:199], v[40:43]
	v_mfma_f32_16x16x32_bf16 v[32:35], v[180:183], v[204:207], v[32:35]
	v_mfma_f32_16x16x32_bf16 v[24:27], v[188:191], v[204:207], v[24:27]
	v_mfma_f32_16x16x32_bf16 v[20:23], v[180:183], v[212:215], v[20:23]
	v_mfma_f32_16x16x32_bf16 v[12:15], v[188:191], v[212:215], v[12:15]
	v_mfma_f32_16x16x32_bf16 v[4:7], v[180:183], v[220:223], v[4:7]
	v_mfma_f32_16x16x32_bf16 v[0:3], v[188:191], v[220:223], v[0:3]
	s_setprio 0
	s_barrier
	s_add_i32 s59, s59, 2
	s_add_u32 s28, s28, 0x100
	s_addc_u32 s29, s29, 0
	s_add_u32 s43, s43, 0x100
	s_addc_u32 s58, s58, 0
	s_cmp_gt_u32 s59, 13
	s_cbranch_scc0 .LBB0_155
	s_and_b64 vcc, exec, s[16:17]
	s_cbranch_vccz .LBB0_158
	s_barrier

.LBB0_175:
	ds_read_b128 v[160:163], v156
	ds_read_b128 v[164:167], v156 offset:1024
	ds_read_b128 v[168:171], v156 offset:2048
	ds_read_b128 v[172:175], v156 offset:3072
	ds_read_b128 v[176:179], v157
	ds_read_b128 v[180:183], v157 offset:1024
	ds_read_b128 v[184:187], v157 offset:2048
	ds_read_b128 v[188:191], v157 offset:3072
	s_add_u32 s34, s30, 0xfffc0080
	s_addc_u32 s35, s31, -1
	s_cmp_eq_u32 s77, 12
	s_cselect_b32 s37, s0, s35
	s_cselect_b32 s36, s1, s34
	s_cselect_b32 s35, s21, s76
	s_cselect_b32 s34, s23, s59
	s_add_i32 m0, s27, 0xc000
	ds_read_b128 v[192:195], v158
	ds_read_b128 v[196:199], v158 offset:1024
	ds_read_b128 v[200:203], v158 offset:2048
	ds_read_b128 v[204:207], v158 offset:3072
	ds_read_b128 v[208:211], v158 offset:4096
	ds_read_b128 v[212:215], v158 offset:5120
	ds_read_b128 v[216:219], v158 offset:6144
	ds_read_b128 v[220:223], v158 offset:7168
	global_load_lds_dwordx4 v136, s[30:31]
	s_add_i32 m0, s27, 0xe000
	s_nop 0
	global_load_lds_dwordx4 v138, s[30:31]
	s_waitcnt vmcnt(8)
	s_waitcnt lgkmcnt(0)
	s_barrier
	s_setprio 1
	s_waitcnt lgkmcnt(0)
	v_mfma_f32_16x16x32_bf16 v[124:127], v[160:163], v[192:195], v[124:127]
	v_mfma_f32_16x16x32_bf16 v[120:123], v[168:171], v[192:195], v[120:123]
	v_mfma_f32_16x16x32_bf16 v[116:119], v[160:163], v[200:203], v[116:119]
	v_mfma_f32_16x16x32_bf16 v[108:111], v[168:171], v[200:203], v[108:111]
	v_mfma_f32_16x16x32_bf16 v[100:103], v[160:163], v[208:211], v[100:103]
	v_mfma_f32_16x16x32_bf16 v[92:95], v[168:171], v[208:211], v[92:95]
	v_mfma_f32_16x16x32_bf16 v[84:87], v[160:163], v[216:219], v[84:87]
	v_mfma_f32_16x16x32_bf16 v[76:79], v[168:171], v[216:219], v[76:79]
	v_mfma_f32_16x16x32_bf16 v[124:127], v[164:167], v[196:199], v[124:127]
	v_mfma_f32_16x16x32_bf16 v[120:123], v[172:175], v[196:199], v[120:123]
	v_mfma_f32_16x16x32_bf16 v[116:119], v[164:167], v[204:207], v[116:119]
	v_mfma_f32_16x16x32_bf16 v[108:111], v[172:175], v[204:207], v[108:111]
	v_mfma_f32_16x16x32_bf16 v[100:103], v[164:167], v[212:215], v[100:103]
	v_mfma_f32_16x16x32_bf16 v[92:95], v[172:175], v[212:215], v[92:95]
	v_mfma_f32_16x16x32_bf16 v[84:87], v[164:167], v[220:223], v[84:87]
	v_mfma_f32_16x16x32_bf16 v[76:79], v[172:175], v[220:223], v[76:79]
	s_setprio 0
	s_setprio 1
	v_mfma_f32_16x16x32_bf16 v[112:115], v[176:179], v[192:195], v[112:115]
	v_mfma_f32_16x16x32_bf16 v[104:107], v[184:187], v[192:195], v[104:107]
	v_mfma_f32_16x16x32_bf16 v[96:99], v[176:179], v[200:203], v[96:99]
	v_mfma_f32_16x16x32_bf16 v[88:91], v[184:187], v[200:203], v[88:91]
	v_mfma_f32_16x16x32_bf16 v[80:83], v[176:179], v[208:211], v[80:83]
	v_mfma_f32_16x16x32_bf16 v[72:75], v[184:187], v[208:211], v[72:75]
	v_mfma_f32_16x16x32_bf16 v[68:71], v[176:179], v[216:219], v[68:71]
	v_mfma_f32_16x16x32_bf16 v[64:67], v[184:187], v[216:219], v[64:67]
	v_mfma_f32_16x16x32_bf16 v[112:115], v[180:183], v[196:199], v[112:115]
	v_mfma_f32_16x16x32_bf16 v[104:107], v[188:191], v[196:199], v[104:107]
	v_mfma_f32_16x16x32_bf16 v[96:99], v[180:183], v[204:207], v[96:99]
	v_mfma_f32_16x16x32_bf16 v[88:91], v[188:191], v[204:207], v[88:91]
	v_mfma_f32_16x16x32_bf16 v[80:83], v[180:183], v[212:215], v[80:83]
	v_mfma_f32_16x16x32_bf16 v[72:75], v[188:191], v[212:215], v[72:75]
	v_mfma_f32_16x16x32_bf16 v[68:71], v[180:183], v[220:223], v[68:71]
	v_mfma_f32_16x16x32_bf16 v[64:67], v[188:191], v[220:223], v[64:67]
	s_setprio 0
	s_barrier
	s_add_i32 s44, s42, s5
	s_add_u32 s98, s34, s16
	s_addc_u32 s99, s35, s17
	s_mov_b32 m0, s44
	ds_read_b128 v[192:195], v158 offset:16384
	ds_read_b128 v[196:199], v158 offset:17408
	ds_read_b128 v[200:203], v158 offset:18432
	ds_read_b128 v[204:207], v158 offset:19456
	ds_read_b128 v[208:211], v158 offset:20480
	ds_read_b128 v[212:215], v158 offset:21504
	ds_read_b128 v[216:219], v158 offset:22528
	ds_read_b128 v[220:223], v158 offset:23552
	global_load_lds_dwordx4 v132, s[34:35]
	s_add_i32 m0, s44, 0x2000
	s_add_u32 s44, s34, 0x40000
	s_addc_u32 s45, s35, 0
	s_add_i32 s46, s43, s5
	global_load_lds_dwordx4 v128, s[34:35]
	s_mov_b32 m0, s46
	s_add_u32 s100, s36, s16
	s_addc_u32 s101, s37, s17
	global_load_lds_dwordx4 v132, s[44:45]
	s_add_i32 m0, s46, 0x2000
	s_nop 0
	global_load_lds_dwordx4 v128, s[44:45]
	s_mov_b32 m0, s27
	s_nop 0
	global_load_lds_dwordx4 v134, s[36:37]
	s_mov_b32 m0, s33
	s_nop 0
	global_load_lds_dwordx4 v130, s[36:37]
	s_waitcnt vmcnt(8)
	s_waitcnt lgkmcnt(0)
	s_barrier
	s_setprio 1
	s_waitcnt lgkmcnt(0)
	v_mfma_f32_16x16x32_bf16 v[60:63], v[160:163], v[192:195], v[60:63]
	v_mfma_f32_16x16x32_bf16 v[56:59], v[168:171], v[192:195], v[56:59]
	v_mfma_f32_16x16x32_bf16 v[52:55], v[160:163], v[200:203], v[52:55]
	v_mfma_f32_16x16x32_bf16 v[44:47], v[168:171], v[200:203], v[44:47]
	v_mfma_f32_16x16x32_bf16 v[36:39], v[160:163], v[208:211], v[36:39]
	v_mfma_f32_16x16x32_bf16 v[28:31], v[168:171], v[208:211], v[28:31]
	v_mfma_f32_16x16x32_bf16 v[20:23], v[160:163], v[216:219], v[20:23]
	v_mfma_f32_16x16x32_bf16 v[12:15], v[168:171], v[216:219], v[12:15]
	v_mfma_f32_16x16x32_bf16 v[60:63], v[164:167], v[196:199], v[60:63]
	v_mfma_f32_16x16x32_bf16 v[56:59], v[172:175], v[196:199], v[56:59]
	v_mfma_f32_16x16x32_bf16 v[52:55], v[164:167], v[204:207], v[52:55]
	v_mfma_f32_16x16x32_bf16 v[44:47], v[172:175], v[204:207], v[44:47]
	v_mfma_f32_16x16x32_bf16 v[36:39], v[164:167], v[212:215], v[36:39]
	v_mfma_f32_16x16x32_bf16 v[28:31], v[172:175], v[212:215], v[28:31]
	v_mfma_f32_16x16x32_bf16 v[20:23], v[164:167], v[220:223], v[20:23]
	v_mfma_f32_16x16x32_bf16 v[12:15], v[172:175], v[220:223], v[12:15]
	s_setprio 0
	s_setprio 1
	v_mfma_f32_16x16x32_bf16 v[48:51], v[176:179], v[192:195], v[48:51]
	v_mfma_f32_16x16x32_bf16 v[40:43], v[184:187], v[192:195], v[40:43]
	v_mfma_f32_16x16x32_bf16 v[32:35], v[176:179], v[200:203], v[32:35]
	v_mfma_f32_16x16x32_bf16 v[24:27], v[184:187], v[200:203], v[24:27]
	v_mfma_f32_16x16x32_bf16 v[16:19], v[176:179], v[208:211], v[16:19]
	v_mfma_f32_16x16x32_bf16 v[8:11], v[184:187], v[208:211], v[8:11]
	v_mfma_f32_16x16x32_bf16 v[4:7], v[176:179], v[216:219], v[4:7]
	v_mfma_f32_16x16x32_bf16 v[0:3], v[184:187], v[216:219], v[0:3]
	v_mfma_f32_16x16x32_bf16 v[48:51], v[180:183], v[196:199], v[48:51]
	v_mfma_f32_16x16x32_bf16 v[40:43], v[188:191], v[196:199], v[40:43]
	v_mfma_f32_16x16x32_bf16 v[32:35], v[180:183], v[204:207], v[32:35]
	v_mfma_f32_16x16x32_bf16 v[24:27], v[188:191], v[204:207], v[24:27]
	v_mfma_f32_16x16x32_bf16 v[16:19], v[180:183], v[212:215], v[16:19]
	v_mfma_f32_16x16x32_bf16 v[8:11], v[188:191], v[212:215], v[8:11]
	v_mfma_f32_16x16x32_bf16 v[4:7], v[180:183], v[220:223], v[4:7]
	v_mfma_f32_16x16x32_bf16 v[0:3], v[188:191], v[220:223], v[0:3]
	s_setprio 0
	s_barrier
	s_add_i32 s44, 0, 0x18000
	v_add_u32_e32 v159, s44, v147
	s_add_i32 s45, 0, 0x1c000
	ds_read_b128 v[160:163], v159
	ds_read_b128 v[164:167], v159 offset:1024
	ds_read_b128 v[168:171], v159 offset:2048
	ds_read_b128 v[172:175], v159 offset:3072
	v_add_u32_e32 v159, s45, v147
	ds_read_b128 v[176:179], v159
	ds_read_b128 v[180:183], v159 offset:1024
	ds_read_b128 v[184:187], v159 offset:2048
	ds_read_b128 v[188:191], v159 offset:3072
	s_add_u32 s36, s36, 0x40000
	s_addc_u32 s37, s37, 0
	s_mov_b32 m0, s38
	ds_read_b128 v[192:195], v158 offset:32768
	ds_read_b128 v[196:199], v158 offset:33792
	ds_read_b128 v[200:203], v158 offset:34816
	ds_read_b128 v[204:207], v158 offset:35840
	ds_read_b128 v[208:211], v158 offset:36864
	ds_read_b128 v[212:215], v158 offset:37888
	ds_read_b128 v[216:219], v158 offset:38912
	ds_read_b128 v[220:223], v158 offset:39936
	global_load_lds_dwordx4 v134, s[36:37]
	s_mov_b32 m0, s39
	s_nop 0
	global_load_lds_dwordx4 v130, s[36:37]
	s_waitcnt vmcnt(8)
	s_waitcnt lgkmcnt(0)
	s_barrier
	s_setprio 1
	s_waitcnt lgkmcnt(0)
	v_mfma_f32_16x16x32_bf16 v[124:127], v[160:163], v[192:195], v[124:127]
	v_mfma_f32_16x16x32_bf16 v[120:123], v[168:171], v[192:195], v[120:123]
	v_mfma_f32_16x16x32_bf16 v[116:119], v[160:163], v[200:203], v[116:119]
	v_mfma_f32_16x16x32_bf16 v[108:111], v[168:171], v[200:203], v[108:111]
	v_mfma_f32_16x16x32_bf16 v[100:103], v[160:163], v[208:211], v[100:103]
	v_mfma_f32_16x16x32_bf16 v[92:95], v[168:171], v[208:211], v[92:95]
	v_mfma_f32_16x16x32_bf16 v[84:87], v[160:163], v[216:219], v[84:87]
	v_mfma_f32_16x16x32_bf16 v[76:79], v[168:171], v[216:219], v[76:79]
	v_mfma_f32_16x16x32_bf16 v[124:127], v[164:167], v[196:199], v[124:127]
	v_mfma_f32_16x16x32_bf16 v[120:123], v[172:175], v[196:199], v[120:123]
	v_mfma_f32_16x16x32_bf16 v[116:119], v[164:167], v[204:207], v[116:119]
	v_mfma_f32_16x16x32_bf16 v[108:111], v[172:175], v[204:207], v[108:111]
	v_mfma_f32_16x16x32_bf16 v[100:103], v[164:167], v[212:215], v[100:103]
	v_mfma_f32_16x16x32_bf16 v[92:95], v[172:175], v[212:215], v[92:95]
	v_mfma_f32_16x16x32_bf16 v[84:87], v[164:167], v[220:223], v[84:87]
	v_mfma_f32_16x16x32_bf16 v[76:79], v[172:175], v[220:223], v[76:79]
	s_setprio 0
	s_setprio 1
	v_mfma_f32_16x16x32_bf16 v[112:115], v[176:179], v[192:195], v[112:115]
	v_mfma_f32_16x16x32_bf16 v[104:107], v[184:187], v[192:195], v[104:107]
	v_mfma_f32_16x16x32_bf16 v[96:99], v[176:179], v[200:203], v[96:99]
	v_mfma_f32_16x16x32_bf16 v[88:91], v[184:187], v[200:203], v[88:91]
	v_mfma_f32_16x16x32_bf16 v[80:83], v[176:179], v[208:211], v[80:83]
	v_mfma_f32_16x16x32_bf16 v[72:75], v[184:187], v[208:211], v[72:75]
	v_mfma_f32_16x16x32_bf16 v[68:71], v[176:179], v[216:219], v[68:71]
	v_mfma_f32_16x16x32_bf16 v[64:67], v[184:187], v[216:219], v[64:67]
	v_mfma_f32_16x16x32_bf16 v[112:115], v[180:183], v[196:199], v[112:115]
	v_mfma_f32_16x16x32_bf16 v[104:107], v[188:191], v[196:199], v[104:107]
	v_mfma_f32_16x16x32_bf16 v[96:99], v[180:183], v[204:207], v[96:99]
	v_mfma_f32_16x16x32_bf16 v[88:91], v[188:191], v[204:207], v[88:91]
	v_mfma_f32_16x16x32_bf16 v[80:83], v[180:183], v[212:215], v[80:83]
	v_mfma_f32_16x16x32_bf16 v[72:75], v[188:191], v[212:215], v[72:75]
	v_mfma_f32_16x16x32_bf16 v[68:71], v[180:183], v[220:223], v[68:71]
	v_mfma_f32_16x16x32_bf16 v[64:67], v[188:191], v[220:223], v[64:67]
	s_setprio 0
	s_barrier
	s_add_i32 s36, s44, s5
	s_mov_b32 m0, s36
	ds_read_b128 v[192:195], v158 offset:49152
	ds_read_b128 v[196:199], v158 offset:50176
	ds_read_b128 v[200:203], v158 offset:51200
	ds_read_b128 v[204:207], v158 offset:52224
	ds_read_b128 v[208:211], v158 offset:53248
	ds_read_b128 v[212:215], v158 offset:54272
	ds_read_b128 v[216:219], v158 offset:55296
	ds_read_b128 v[220:223], v158 offset:56320
	global_load_lds_dwordx4 v132, s[98:99]
	s_add_i32 m0, s36, 0x2000
	s_add_u32 s34, s34, 0x40080
	s_addc_u32 s35, s35, 0
	s_add_i32 s36, s45, s5
	global_load_lds_dwordx4 v128, s[98:99]
	s_mov_b32 m0, s36
	s_nop 0
	global_load_lds_dwordx4 v132, s[34:35]
	s_add_i32 m0, s36, 0x2000
	s_nop 0
	global_load_lds_dwordx4 v128, s[34:35]
	s_mov_b32 m0, s4
	s_nop 0
	global_load_lds_dwordx4 v134, s[100:101]
	s_mov_b32 m0, s41
	s_nop 0
	global_load_lds_dwordx4 v130, s[100:101]
	s_waitcnt vmcnt(8)
	s_waitcnt lgkmcnt(0)
	s_barrier
	s_setprio 1
	s_waitcnt lgkmcnt(0)
	v_mfma_f32_16x16x32_bf16 v[60:63], v[160:163], v[192:195], v[60:63]
	v_mfma_f32_16x16x32_bf16 v[56:59], v[168:171], v[192:195], v[56:59]
	v_mfma_f32_16x16x32_bf16 v[52:55], v[160:163], v[200:203], v[52:55]
	v_mfma_f32_16x16x32_bf16 v[44:47], v[168:171], v[200:203], v[44:47]
	v_mfma_f32_16x16x32_bf16 v[36:39], v[160:163], v[208:211], v[36:39]
	v_mfma_f32_16x16x32_bf16 v[28:31], v[168:171], v[208:211], v[28:31]
	v_mfma_f32_16x16x32_bf16 v[20:23], v[160:163], v[216:219], v[20:23]
	v_mfma_f32_16x16x32_bf16 v[12:15], v[168:171], v[216:219], v[12:15]
	v_mfma_f32_16x16x32_bf16 v[60:63], v[164:167], v[196:199], v[60:63]
	v_mfma_f32_16x16x32_bf16 v[56:59], v[172:175], v[196:199], v[56:59]
	v_mfma_f32_16x16x32_bf16 v[52:55], v[164:167], v[204:207], v[52:55]
	v_mfma_f32_16x16x32_bf16 v[44:47], v[172:175], v[204:207], v[44:47]
	v_mfma_f32_16x16x32_bf16 v[36:39], v[164:167], v[212:215], v[36:39]
	v_mfma_f32_16x16x32_bf16 v[28:31], v[172:175], v[212:215], v[28:31]
	v_mfma_f32_16x16x32_bf16 v[20:23], v[164:167], v[220:223], v[20:23]
	v_mfma_f32_16x16x32_bf16 v[12:15], v[172:175], v[220:223], v[12:15]
	s_setprio 0
	s_setprio 1
	v_mfma_f32_16x16x32_bf16 v[48:51], v[176:179], v[192:195], v[48:51]
	v_mfma_f32_16x16x32_bf16 v[40:43], v[184:187], v[192:195], v[40:43]
	v_mfma_f32_16x16x32_bf16 v[32:35], v[176:179], v[200:203], v[32:35]
	v_mfma_f32_16x16x32_bf16 v[24:27], v[184:187], v[200:203], v[24:27]
	v_mfma_f32_16x16x32_bf16 v[16:19], v[176:179], v[208:211], v[16:19]
	v_mfma_f32_16x16x32_bf16 v[8:11], v[184:187], v[208:211], v[8:11]
	v_mfma_f32_16x16x32_bf16 v[4:7], v[176:179], v[216:219], v[4:7]
	v_mfma_f32_16x16x32_bf16 v[0:3], v[184:187], v[216:219], v[0:3]
	v_mfma_f32_16x16x32_bf16 v[48:51], v[180:183], v[196:199], v[48:51]
	v_mfma_f32_16x16x32_bf16 v[40:43], v[188:191], v[196:199], v[40:43]
	v_mfma_f32_16x16x32_bf16 v[32:35], v[180:183], v[204:207], v[32:35]
	v_mfma_f32_16x16x32_bf16 v[24:27], v[188:191], v[204:207], v[24:27]
	v_mfma_f32_16x16x32_bf16 v[16:19], v[180:183], v[212:215], v[16:19]
	v_mfma_f32_16x16x32_bf16 v[8:11], v[188:191], v[212:215], v[8:11]
	v_mfma_f32_16x16x32_bf16 v[4:7], v[180:183], v[220:223], v[4:7]
	v_mfma_f32_16x16x32_bf16 v[0:3], v[188:191], v[220:223], v[0:3]
	s_setprio 0
	s_barrier
	s_add_i32 s77, s77, 2
	s_add_u32 s30, s30, 0x100
	s_addc_u32 s31, s31, 0
	s_add_u32 s59, s59, 0x100
	s_addc_u32 s76, s76, 0
	s_cmp_gt_u32 s77, 13
	s_cbranch_scc0 .LBB0_175
	s_and_b64 vcc, exec, s[18:19]
	s_cbranch_vccz .LBB0_178
	s_barrier

.LBB0_195:
	ds_read_b128 v[160:163], v156
	ds_read_b128 v[164:167], v156 offset:1024
	ds_read_b128 v[168:171], v156 offset:2048
	ds_read_b128 v[172:175], v156 offset:3072
	ds_read_b128 v[176:179], v157
	ds_read_b128 v[180:183], v157 offset:1024
	ds_read_b128 v[184:187], v157 offset:2048
	ds_read_b128 v[188:191], v157 offset:3072
	s_add_u32 s38, s36, 0xfffc0080
	s_addc_u32 s39, s37, -1
	s_cmp_eq_u32 s97, 12
	s_cselect_b32 s59, s0, s39
	s_cselect_b32 s58, s1, s38
	s_cselect_b32 s39, s25, s96
	s_cselect_b32 s38, s27, s77
	s_add_i32 m0, s5, 0xc000
	ds_read_b128 v[192:195], v158
	ds_read_b128 v[196:199], v158 offset:1024
	ds_read_b128 v[200:203], v158 offset:2048
	ds_read_b128 v[204:207], v158 offset:3072
	ds_read_b128 v[208:211], v158 offset:4096
	ds_read_b128 v[212:215], v158 offset:5120
	ds_read_b128 v[216:219], v158 offset:6144
	ds_read_b128 v[220:223], v158 offset:7168
	global_load_lds_dwordx4 v136, s[36:37]
	s_add_i32 m0, s5, 0xe000
	s_nop 0
	global_load_lds_dwordx4 v138, s[36:37]
	s_waitcnt vmcnt(8)
	s_waitcnt lgkmcnt(0)
	s_barrier
	s_setprio 1
	s_waitcnt lgkmcnt(0)
	v_mfma_f32_16x16x32_bf16 v[124:127], v[160:163], v[192:195], v[124:127]
	v_mfma_f32_16x16x32_bf16 v[120:123], v[168:171], v[192:195], v[120:123]
	v_mfma_f32_16x16x32_bf16 v[116:119], v[160:163], v[200:203], v[116:119]
	v_mfma_f32_16x16x32_bf16 v[108:111], v[168:171], v[200:203], v[108:111]
	v_mfma_f32_16x16x32_bf16 v[100:103], v[160:163], v[208:211], v[100:103]
	v_mfma_f32_16x16x32_bf16 v[92:95], v[168:171], v[208:211], v[92:95]
	v_mfma_f32_16x16x32_bf16 v[84:87], v[160:163], v[216:219], v[84:87]
	v_mfma_f32_16x16x32_bf16 v[76:79], v[168:171], v[216:219], v[76:79]
	v_mfma_f32_16x16x32_bf16 v[124:127], v[164:167], v[196:199], v[124:127]
	v_mfma_f32_16x16x32_bf16 v[120:123], v[172:175], v[196:199], v[120:123]
	v_mfma_f32_16x16x32_bf16 v[116:119], v[164:167], v[204:207], v[116:119]
	v_mfma_f32_16x16x32_bf16 v[108:111], v[172:175], v[204:207], v[108:111]
	v_mfma_f32_16x16x32_bf16 v[100:103], v[164:167], v[212:215], v[100:103]
	v_mfma_f32_16x16x32_bf16 v[92:95], v[172:175], v[212:215], v[92:95]
	v_mfma_f32_16x16x32_bf16 v[84:87], v[164:167], v[220:223], v[84:87]
	v_mfma_f32_16x16x32_bf16 v[76:79], v[172:175], v[220:223], v[76:79]
	s_setprio 0
	s_setprio 1
	v_mfma_f32_16x16x32_bf16 v[112:115], v[176:179], v[192:195], v[112:115]
	v_mfma_f32_16x16x32_bf16 v[104:107], v[184:187], v[192:195], v[104:107]
	v_mfma_f32_16x16x32_bf16 v[96:99], v[176:179], v[200:203], v[96:99]
	v_mfma_f32_16x16x32_bf16 v[88:91], v[184:187], v[200:203], v[88:91]
	v_mfma_f32_16x16x32_bf16 v[80:83], v[176:179], v[208:211], v[80:83]
	v_mfma_f32_16x16x32_bf16 v[72:75], v[184:187], v[208:211], v[72:75]
	v_mfma_f32_16x16x32_bf16 v[68:71], v[176:179], v[216:219], v[68:71]
	v_mfma_f32_16x16x32_bf16 v[64:67], v[184:187], v[216:219], v[64:67]
	v_mfma_f32_16x16x32_bf16 v[112:115], v[180:183], v[196:199], v[112:115]
	v_mfma_f32_16x16x32_bf16 v[104:107], v[188:191], v[196:199], v[104:107]
	v_mfma_f32_16x16x32_bf16 v[96:99], v[180:183], v[204:207], v[96:99]
	v_mfma_f32_16x16x32_bf16 v[88:91], v[188:191], v[204:207], v[88:91]
	v_mfma_f32_16x16x32_bf16 v[80:83], v[180:183], v[212:215], v[80:83]
	v_mfma_f32_16x16x32_bf16 v[72:75], v[188:191], v[212:215], v[72:75]
	v_mfma_f32_16x16x32_bf16 v[68:71], v[180:183], v[220:223], v[68:71]
	v_mfma_f32_16x16x32_bf16 v[64:67], v[188:191], v[220:223], v[64:67]
	s_setprio 0
	s_barrier
	s_add_i32 s44, s41, s4
	s_add_u32 s98, s38, s20
	s_addc_u32 s99, s39, s21
	s_mov_b32 m0, s44
	ds_read_b128 v[192:195], v158 offset:16384
	ds_read_b128 v[196:199], v158 offset:17408
	ds_read_b128 v[200:203], v158 offset:18432
	ds_read_b128 v[204:207], v158 offset:19456
	ds_read_b128 v[208:211], v158 offset:20480
	ds_read_b128 v[212:215], v158 offset:21504
	ds_read_b128 v[216:219], v158 offset:22528
	ds_read_b128 v[220:223], v158 offset:23552
	global_load_lds_dwordx4 v132, s[38:39]
	s_add_i32 m0, s44, 0x2000
	s_add_u32 s44, s38, 0x40000
	s_addc_u32 s45, s39, 0
	s_add_i32 s46, s42, s4
	global_load_lds_dwordx4 v128, s[38:39]
	s_mov_b32 m0, s46
	s_add_u32 s100, s58, s20
	s_addc_u32 s101, s59, s21
	global_load_lds_dwordx4 v132, s[44:45]
	s_add_i32 m0, s46, 0x2000
	s_nop 0
	global_load_lds_dwordx4 v128, s[44:45]
	s_mov_b32 m0, s5
	s_nop 0
	global_load_lds_dwordx4 v134, s[58:59]
	s_mov_b32 m0, s8
	s_nop 0
	global_load_lds_dwordx4 v130, s[58:59]
	s_waitcnt vmcnt(8)
	s_waitcnt lgkmcnt(0)
	s_barrier
	s_setprio 1
	s_waitcnt lgkmcnt(0)
	v_mfma_f32_16x16x32_bf16 v[60:63], v[160:163], v[192:195], v[60:63]
	v_mfma_f32_16x16x32_bf16 v[56:59], v[168:171], v[192:195], v[56:59]
	v_mfma_f32_16x16x32_bf16 v[52:55], v[160:163], v[200:203], v[52:55]
	v_mfma_f32_16x16x32_bf16 v[44:47], v[168:171], v[200:203], v[44:47]
	v_mfma_f32_16x16x32_bf16 v[36:39], v[160:163], v[208:211], v[36:39]
	v_mfma_f32_16x16x32_bf16 v[28:31], v[168:171], v[208:211], v[28:31]
	v_mfma_f32_16x16x32_bf16 v[20:23], v[160:163], v[216:219], v[20:23]
	v_mfma_f32_16x16x32_bf16 v[12:15], v[168:171], v[216:219], v[12:15]
	v_mfma_f32_16x16x32_bf16 v[60:63], v[164:167], v[196:199], v[60:63]
	v_mfma_f32_16x16x32_bf16 v[56:59], v[172:175], v[196:199], v[56:59]
	v_mfma_f32_16x16x32_bf16 v[52:55], v[164:167], v[204:207], v[52:55]
	v_mfma_f32_16x16x32_bf16 v[44:47], v[172:175], v[204:207], v[44:47]
	v_mfma_f32_16x16x32_bf16 v[36:39], v[164:167], v[212:215], v[36:39]
	v_mfma_f32_16x16x32_bf16 v[28:31], v[172:175], v[212:215], v[28:31]
	v_mfma_f32_16x16x32_bf16 v[20:23], v[164:167], v[220:223], v[20:23]
	v_mfma_f32_16x16x32_bf16 v[12:15], v[172:175], v[220:223], v[12:15]
	s_setprio 0
	s_setprio 1
	v_mfma_f32_16x16x32_bf16 v[48:51], v[176:179], v[192:195], v[48:51]
	v_mfma_f32_16x16x32_bf16 v[40:43], v[184:187], v[192:195], v[40:43]
	v_mfma_f32_16x16x32_bf16 v[32:35], v[176:179], v[200:203], v[32:35]
	v_mfma_f32_16x16x32_bf16 v[24:27], v[184:187], v[200:203], v[24:27]
	v_mfma_f32_16x16x32_bf16 v[16:19], v[176:179], v[208:211], v[16:19]
	v_mfma_f32_16x16x32_bf16 v[8:11], v[184:187], v[208:211], v[8:11]
	v_mfma_f32_16x16x32_bf16 v[4:7], v[176:179], v[216:219], v[4:7]
	v_mfma_f32_16x16x32_bf16 v[0:3], v[184:187], v[216:219], v[0:3]
	v_mfma_f32_16x16x32_bf16 v[48:51], v[180:183], v[196:199], v[48:51]
	v_mfma_f32_16x16x32_bf16 v[40:43], v[188:191], v[196:199], v[40:43]
	v_mfma_f32_16x16x32_bf16 v[32:35], v[180:183], v[204:207], v[32:35]
	v_mfma_f32_16x16x32_bf16 v[24:27], v[188:191], v[204:207], v[24:27]
	v_mfma_f32_16x16x32_bf16 v[16:19], v[180:183], v[212:215], v[16:19]
	v_mfma_f32_16x16x32_bf16 v[8:11], v[188:191], v[212:215], v[8:11]
	v_mfma_f32_16x16x32_bf16 v[4:7], v[180:183], v[220:223], v[4:7]
	v_mfma_f32_16x16x32_bf16 v[0:3], v[188:191], v[220:223], v[0:3]
	s_setprio 0
	s_barrier
	s_add_i32 s46, 0, 0x18000
	v_add_u32_e32 v159, s46, v147
	s_add_i32 s47, 0, 0x1c000
	ds_read_b128 v[160:163], v159
	ds_read_b128 v[164:167], v159 offset:1024
	ds_read_b128 v[168:171], v159 offset:2048
	ds_read_b128 v[172:175], v159 offset:3072
	v_add_u32_e32 v159, s47, v147
	ds_read_b128 v[176:179], v159
	ds_read_b128 v[180:183], v159 offset:1024
	ds_read_b128 v[184:187], v159 offset:2048
	ds_read_b128 v[188:191], v159 offset:3072
	s_add_u32 s44, s58, 0x40000
	s_addc_u32 s45, s59, 0
	s_mov_b32 m0, s9
	ds_read_b128 v[192:195], v158 offset:32768
	ds_read_b128 v[196:199], v158 offset:33792
	ds_read_b128 v[200:203], v158 offset:34816
	ds_read_b128 v[204:207], v158 offset:35840
	ds_read_b128 v[208:211], v158 offset:36864
	ds_read_b128 v[212:215], v158 offset:37888
	ds_read_b128 v[216:219], v158 offset:38912
	ds_read_b128 v[220:223], v158 offset:39936
	global_load_lds_dwordx4 v134, s[44:45]
	s_mov_b32 m0, s33
	s_nop 0
	global_load_lds_dwordx4 v130, s[44:45]
	s_waitcnt vmcnt(8)
	s_waitcnt lgkmcnt(0)
	s_barrier
	s_setprio 1
	s_waitcnt lgkmcnt(0)
	v_mfma_f32_16x16x32_bf16 v[124:127], v[160:163], v[192:195], v[124:127]
	v_mfma_f32_16x16x32_bf16 v[120:123], v[168:171], v[192:195], v[120:123]
	v_mfma_f32_16x16x32_bf16 v[116:119], v[160:163], v[200:203], v[116:119]
	v_mfma_f32_16x16x32_bf16 v[108:111], v[168:171], v[200:203], v[108:111]
	v_mfma_f32_16x16x32_bf16 v[100:103], v[160:163], v[208:211], v[100:103]
	v_mfma_f32_16x16x32_bf16 v[92:95], v[168:171], v[208:211], v[92:95]
	v_mfma_f32_16x16x32_bf16 v[84:87], v[160:163], v[216:219], v[84:87]
	v_mfma_f32_16x16x32_bf16 v[76:79], v[168:171], v[216:219], v[76:79]
	v_mfma_f32_16x16x32_bf16 v[124:127], v[164:167], v[196:199], v[124:127]
	v_mfma_f32_16x16x32_bf16 v[120:123], v[172:175], v[196:199], v[120:123]
	v_mfma_f32_16x16x32_bf16 v[116:119], v[164:167], v[204:207], v[116:119]
	v_mfma_f32_16x16x32_bf16 v[108:111], v[172:175], v[204:207], v[108:111]
	v_mfma_f32_16x16x32_bf16 v[100:103], v[164:167], v[212:215], v[100:103]
	v_mfma_f32_16x16x32_bf16 v[92:95], v[172:175], v[212:215], v[92:95]
	v_mfma_f32_16x16x32_bf16 v[84:87], v[164:167], v[220:223], v[84:87]
	v_mfma_f32_16x16x32_bf16 v[76:79], v[172:175], v[220:223], v[76:79]
	s_setprio 0
	s_setprio 1
	v_mfma_f32_16x16x32_bf16 v[112:115], v[176:179], v[192:195], v[112:115]
	v_mfma_f32_16x16x32_bf16 v[104:107], v[184:187], v[192:195], v[104:107]
	v_mfma_f32_16x16x32_bf16 v[96:99], v[176:179], v[200:203], v[96:99]
	v_mfma_f32_16x16x32_bf16 v[88:91], v[184:187], v[200:203], v[88:91]
	v_mfma_f32_16x16x32_bf16 v[80:83], v[176:179], v[208:211], v[80:83]
	v_mfma_f32_16x16x32_bf16 v[72:75], v[184:187], v[208:211], v[72:75]
	v_mfma_f32_16x16x32_bf16 v[68:71], v[176:179], v[216:219], v[68:71]
	v_mfma_f32_16x16x32_bf16 v[64:67], v[184:187], v[216:219], v[64:67]
	v_mfma_f32_16x16x32_bf16 v[112:115], v[180:183], v[196:199], v[112:115]
	v_mfma_f32_16x16x32_bf16 v[104:107], v[188:191], v[196:199], v[104:107]
	v_mfma_f32_16x16x32_bf16 v[96:99], v[180:183], v[204:207], v[96:99]
	v_mfma_f32_16x16x32_bf16 v[88:91], v[188:191], v[204:207], v[88:91]
	v_mfma_f32_16x16x32_bf16 v[80:83], v[180:183], v[212:215], v[80:83]
	v_mfma_f32_16x16x32_bf16 v[72:75], v[188:191], v[212:215], v[72:75]
	v_mfma_f32_16x16x32_bf16 v[68:71], v[180:183], v[220:223], v[68:71]
	v_mfma_f32_16x16x32_bf16 v[64:67], v[188:191], v[220:223], v[64:67]
	s_setprio 0
	s_barrier
	s_add_i32 s44, s46, s4
	s_mov_b32 m0, s44
	ds_read_b128 v[192:195], v158 offset:49152
	ds_read_b128 v[196:199], v158 offset:50176
	ds_read_b128 v[200:203], v158 offset:51200
	ds_read_b128 v[204:207], v158 offset:52224
	ds_read_b128 v[208:211], v158 offset:53248
	ds_read_b128 v[212:215], v158 offset:54272
	ds_read_b128 v[216:219], v158 offset:55296
	ds_read_b128 v[220:223], v158 offset:56320
	global_load_lds_dwordx4 v132, s[98:99]
	s_add_i32 m0, s44, 0x2000
	s_add_u32 s38, s38, 0x40080
	s_addc_u32 s39, s39, 0
	s_add_i32 s44, s47, s4
	global_load_lds_dwordx4 v128, s[98:99]
	s_mov_b32 m0, s44
	s_nop 0
	global_load_lds_dwordx4 v132, s[38:39]
	s_add_i32 m0, s44, 0x2000
	s_nop 0
	global_load_lds_dwordx4 v128, s[38:39]
	s_mov_b32 m0, s35
	s_nop 0
	global_load_lds_dwordx4 v134, s[100:101]
	s_mov_b32 m0, s40
	s_nop 0
	global_load_lds_dwordx4 v130, s[100:101]
	s_waitcnt vmcnt(8)
	s_waitcnt lgkmcnt(0)
	s_barrier
	s_setprio 1
	s_waitcnt lgkmcnt(0)
	v_mfma_f32_16x16x32_bf16 v[60:63], v[160:163], v[192:195], v[60:63]
	v_mfma_f32_16x16x32_bf16 v[56:59], v[168:171], v[192:195], v[56:59]
	v_mfma_f32_16x16x32_bf16 v[52:55], v[160:163], v[200:203], v[52:55]
	v_mfma_f32_16x16x32_bf16 v[44:47], v[168:171], v[200:203], v[44:47]
	v_mfma_f32_16x16x32_bf16 v[36:39], v[160:163], v[208:211], v[36:39]
	v_mfma_f32_16x16x32_bf16 v[28:31], v[168:171], v[208:211], v[28:31]
	v_mfma_f32_16x16x32_bf16 v[20:23], v[160:163], v[216:219], v[20:23]
	v_mfma_f32_16x16x32_bf16 v[12:15], v[168:171], v[216:219], v[12:15]
	v_mfma_f32_16x16x32_bf16 v[60:63], v[164:167], v[196:199], v[60:63]
	v_mfma_f32_16x16x32_bf16 v[56:59], v[172:175], v[196:199], v[56:59]
	v_mfma_f32_16x16x32_bf16 v[52:55], v[164:167], v[204:207], v[52:55]
	v_mfma_f32_16x16x32_bf16 v[44:47], v[172:175], v[204:207], v[44:47]
	v_mfma_f32_16x16x32_bf16 v[36:39], v[164:167], v[212:215], v[36:39]
	v_mfma_f32_16x16x32_bf16 v[28:31], v[172:175], v[212:215], v[28:31]
	v_mfma_f32_16x16x32_bf16 v[20:23], v[164:167], v[220:223], v[20:23]
	v_mfma_f32_16x16x32_bf16 v[12:15], v[172:175], v[220:223], v[12:15]
	s_setprio 0
	s_setprio 1
	v_mfma_f32_16x16x32_bf16 v[48:51], v[176:179], v[192:195], v[48:51]
	v_mfma_f32_16x16x32_bf16 v[40:43], v[184:187], v[192:195], v[40:43]
	v_mfma_f32_16x16x32_bf16 v[32:35], v[176:179], v[200:203], v[32:35]
	v_mfma_f32_16x16x32_bf16 v[24:27], v[184:187], v[200:203], v[24:27]
	v_mfma_f32_16x16x32_bf16 v[16:19], v[176:179], v[208:211], v[16:19]
	v_mfma_f32_16x16x32_bf16 v[8:11], v[184:187], v[208:211], v[8:11]
	v_mfma_f32_16x16x32_bf16 v[4:7], v[176:179], v[216:219], v[4:7]
	v_mfma_f32_16x16x32_bf16 v[0:3], v[184:187], v[216:219], v[0:3]
	v_mfma_f32_16x16x32_bf16 v[48:51], v[180:183], v[196:199], v[48:51]
	v_mfma_f32_16x16x32_bf16 v[40:43], v[188:191], v[196:199], v[40:43]
	v_mfma_f32_16x16x32_bf16 v[32:35], v[180:183], v[204:207], v[32:35]
	v_mfma_f32_16x16x32_bf16 v[24:27], v[188:191], v[204:207], v[24:27]
	v_mfma_f32_16x16x32_bf16 v[16:19], v[180:183], v[212:215], v[16:19]
	v_mfma_f32_16x16x32_bf16 v[8:11], v[188:191], v[212:215], v[8:11]
	v_mfma_f32_16x16x32_bf16 v[4:7], v[180:183], v[220:223], v[4:7]
	v_mfma_f32_16x16x32_bf16 v[0:3], v[188:191], v[220:223], v[0:3]
	s_setprio 0
	s_barrier
	s_add_i32 s97, s97, 2
	s_add_u32 s36, s36, 0x100
	s_addc_u32 s37, s37, 0
	s_add_u32 s77, s77, 0x100
	s_addc_u32 s96, s96, 0
	s_cmp_gt_u32 s97, 13
	s_cbranch_scc0 .LBB0_195
	s_and_b64 vcc, exec, s[22:23]
	s_cbranch_vccz .LBB0_198
	s_barrier

.LBB0_664:
	ds_read_b128 v[162:165], v158
	ds_read_b128 v[166:169], v158 offset:1024
	ds_read_b128 v[170:173], v158 offset:2048
	ds_read_b128 v[174:177], v158 offset:3072
	ds_read_b128 v[178:181], v159
	ds_read_b128 v[182:185], v159 offset:1024
	ds_read_b128 v[186:189], v159 offset:2048
	ds_read_b128 v[190:193], v159 offset:3072
	s_add_u32 s18, s36, 0xfffc0080
	s_addc_u32 s19, s37, -1
	s_cmp_eq_u32 s74, 12
	s_cselect_b32 s47, s4, s19
	s_cselect_b32 s46, s5, s18
	s_cselect_b32 s39, s25, s69
	s_cselect_b32 s38, s27, s68
	s_add_i32 m0, s35, 0xc000
	ds_read_b128 v[194:197], v160
	ds_read_b128 v[198:201], v160 offset:1024
	ds_read_b128 v[202:205], v160 offset:2048
	ds_read_b128 v[206:209], v160 offset:3072
	ds_read_b128 v[210:213], v160 offset:4096
	ds_read_b128 v[214:217], v160 offset:5120
	ds_read_b128 v[218:221], v160 offset:6144
	ds_read_b128 v[222:225], v160 offset:7168
	global_load_lds_dwordx4 v138, s[36:37]
	s_add_i32 m0, s35, 0xe000
	s_nop 0
	global_load_lds_dwordx4 v140, s[36:37]
	s_waitcnt vmcnt(8)
	s_waitcnt lgkmcnt(0)
	s_barrier
	s_setprio 1
	s_waitcnt lgkmcnt(0)
	v_mfma_f32_16x16x32_bf16 v[124:127], v[162:165], v[194:197], v[124:127]
	v_mfma_f32_16x16x32_bf16 v[120:123], v[170:173], v[194:197], v[120:123]
	v_mfma_f32_16x16x32_bf16 v[116:119], v[162:165], v[202:205], v[116:119]
	v_mfma_f32_16x16x32_bf16 v[108:111], v[170:173], v[202:205], v[108:111]
	v_mfma_f32_16x16x32_bf16 v[100:103], v[162:165], v[210:213], v[100:103]
	v_mfma_f32_16x16x32_bf16 v[92:95], v[170:173], v[210:213], v[92:95]
	v_mfma_f32_16x16x32_bf16 v[84:87], v[162:165], v[218:221], v[84:87]
	v_mfma_f32_16x16x32_bf16 v[76:79], v[170:173], v[218:221], v[76:79]
	v_mfma_f32_16x16x32_bf16 v[124:127], v[166:169], v[198:201], v[124:127]
	v_mfma_f32_16x16x32_bf16 v[120:123], v[174:177], v[198:201], v[120:123]
	v_mfma_f32_16x16x32_bf16 v[116:119], v[166:169], v[206:209], v[116:119]
	v_mfma_f32_16x16x32_bf16 v[108:111], v[174:177], v[206:209], v[108:111]
	v_mfma_f32_16x16x32_bf16 v[100:103], v[166:169], v[214:217], v[100:103]
	v_mfma_f32_16x16x32_bf16 v[92:95], v[174:177], v[214:217], v[92:95]
	v_mfma_f32_16x16x32_bf16 v[84:87], v[166:169], v[222:225], v[84:87]
	v_mfma_f32_16x16x32_bf16 v[76:79], v[174:177], v[222:225], v[76:79]
	s_setprio 0
	s_setprio 1
	v_mfma_f32_16x16x32_bf16 v[112:115], v[178:181], v[194:197], v[112:115]
	v_mfma_f32_16x16x32_bf16 v[104:107], v[186:189], v[194:197], v[104:107]
	v_mfma_f32_16x16x32_bf16 v[96:99], v[178:181], v[202:205], v[96:99]
	v_mfma_f32_16x16x32_bf16 v[88:91], v[186:189], v[202:205], v[88:91]
	v_mfma_f32_16x16x32_bf16 v[80:83], v[178:181], v[210:213], v[80:83]
	v_mfma_f32_16x16x32_bf16 v[72:75], v[186:189], v[210:213], v[72:75]
	v_mfma_f32_16x16x32_bf16 v[68:71], v[178:181], v[218:221], v[68:71]
	v_mfma_f32_16x16x32_bf16 v[64:67], v[186:189], v[218:221], v[64:67]
	v_mfma_f32_16x16x32_bf16 v[112:115], v[182:185], v[198:201], v[112:115]
	v_mfma_f32_16x16x32_bf16 v[104:107], v[190:193], v[198:201], v[104:107]
	v_mfma_f32_16x16x32_bf16 v[96:99], v[182:185], v[206:209], v[96:99]
	v_mfma_f32_16x16x32_bf16 v[88:91], v[190:193], v[206:209], v[88:91]
	v_mfma_f32_16x16x32_bf16 v[80:83], v[182:185], v[214:217], v[80:83]
	v_mfma_f32_16x16x32_bf16 v[72:75], v[190:193], v[214:217], v[72:75]
	v_mfma_f32_16x16x32_bf16 v[68:71], v[182:185], v[222:225], v[68:71]
	v_mfma_f32_16x16x32_bf16 v[64:67], v[190:193], v[222:225], v[64:67]
	s_setprio 0
	s_barrier
	s_add_i32 s18, s66, s48
	s_add_u32 s98, s38, s20
	s_addc_u32 s99, s39, s21
	s_mov_b32 m0, s18
	ds_read_b128 v[194:197], v160 offset:16384
	ds_read_b128 v[198:201], v160 offset:17408
	ds_read_b128 v[202:205], v160 offset:18432
	ds_read_b128 v[206:209], v160 offset:19456
	ds_read_b128 v[210:213], v160 offset:20480
	ds_read_b128 v[214:217], v160 offset:21504
	ds_read_b128 v[218:221], v160 offset:22528
	ds_read_b128 v[222:225], v160 offset:23552
	global_load_lds_dwordx4 v132, s[38:39]
	s_add_i32 m0, s18, 0x2000
	s_add_u32 s18, s38, 0x40000
	s_addc_u32 s19, s39, 0
	s_add_i32 s40, s67, s48
	global_load_lds_dwordx4 v136, s[38:39]
	s_mov_b32 m0, s40
	s_add_u32 s100, s46, s20
	s_addc_u32 s101, s47, s21
	global_load_lds_dwordx4 v132, s[18:19]
	s_add_i32 m0, s40, 0x2000
	s_nop 0
	global_load_lds_dwordx4 v136, s[18:19]
	s_mov_b32 m0, s35
	s_nop 0
	global_load_lds_dwordx4 v130, s[46:47]
	s_mov_b32 m0, s49
	s_nop 0
	global_load_lds_dwordx4 v134, s[46:47]
	s_waitcnt vmcnt(8)
	s_waitcnt lgkmcnt(0)
	s_barrier
	s_setprio 1
	s_waitcnt lgkmcnt(0)
	v_mfma_f32_16x16x32_bf16 v[60:63], v[162:165], v[194:197], v[60:63]
	v_mfma_f32_16x16x32_bf16 v[56:59], v[170:173], v[194:197], v[56:59]
	v_mfma_f32_16x16x32_bf16 v[52:55], v[162:165], v[202:205], v[52:55]
	v_mfma_f32_16x16x32_bf16 v[44:47], v[170:173], v[202:205], v[44:47]
	v_mfma_f32_16x16x32_bf16 v[36:39], v[162:165], v[210:213], v[36:39]
	v_mfma_f32_16x16x32_bf16 v[28:31], v[170:173], v[210:213], v[28:31]
	v_mfma_f32_16x16x32_bf16 v[20:23], v[162:165], v[218:221], v[20:23]
	v_mfma_f32_16x16x32_bf16 v[12:15], v[170:173], v[218:221], v[12:15]
	v_mfma_f32_16x16x32_bf16 v[60:63], v[166:169], v[198:201], v[60:63]
	v_mfma_f32_16x16x32_bf16 v[56:59], v[174:177], v[198:201], v[56:59]
	v_mfma_f32_16x16x32_bf16 v[52:55], v[166:169], v[206:209], v[52:55]
	v_mfma_f32_16x16x32_bf16 v[44:47], v[174:177], v[206:209], v[44:47]
	v_mfma_f32_16x16x32_bf16 v[36:39], v[166:169], v[214:217], v[36:39]
	v_mfma_f32_16x16x32_bf16 v[28:31], v[174:177], v[214:217], v[28:31]
	v_mfma_f32_16x16x32_bf16 v[20:23], v[166:169], v[222:225], v[20:23]
	v_mfma_f32_16x16x32_bf16 v[12:15], v[174:177], v[222:225], v[12:15]
	s_setprio 0
	s_setprio 1
	v_mfma_f32_16x16x32_bf16 v[48:51], v[178:181], v[194:197], v[48:51]
	v_mfma_f32_16x16x32_bf16 v[40:43], v[186:189], v[194:197], v[40:43]
	v_mfma_f32_16x16x32_bf16 v[32:35], v[178:181], v[202:205], v[32:35]
	v_mfma_f32_16x16x32_bf16 v[24:27], v[186:189], v[202:205], v[24:27]
	v_mfma_f32_16x16x32_bf16 v[16:19], v[178:181], v[210:213], v[16:19]
	v_mfma_f32_16x16x32_bf16 v[8:11], v[186:189], v[210:213], v[8:11]
	v_mfma_f32_16x16x32_bf16 v[4:7], v[178:181], v[218:221], v[4:7]
	v_mfma_f32_16x16x32_bf16 v[0:3], v[186:189], v[218:221], v[0:3]
	v_mfma_f32_16x16x32_bf16 v[48:51], v[182:185], v[198:201], v[48:51]
	v_mfma_f32_16x16x32_bf16 v[40:43], v[190:193], v[198:201], v[40:43]
	v_mfma_f32_16x16x32_bf16 v[32:35], v[182:185], v[206:209], v[32:35]
	v_mfma_f32_16x16x32_bf16 v[24:27], v[190:193], v[206:209], v[24:27]
	v_mfma_f32_16x16x32_bf16 v[16:19], v[182:185], v[214:217], v[16:19]
	v_mfma_f32_16x16x32_bf16 v[8:11], v[190:193], v[214:217], v[8:11]
	v_mfma_f32_16x16x32_bf16 v[4:7], v[182:185], v[222:225], v[4:7]
	v_mfma_f32_16x16x32_bf16 v[0:3], v[190:193], v[222:225], v[0:3]
	s_setprio 0
	s_barrier
	s_add_i32 s40, 0, 0x18000
	v_add_u32_e32 v161, s40, v149
	s_add_i32 s41, 0, 0x1c000
	ds_read_b128 v[162:165], v161
	ds_read_b128 v[166:169], v161 offset:1024
	ds_read_b128 v[170:173], v161 offset:2048
	ds_read_b128 v[174:177], v161 offset:3072
	v_add_u32_e32 v161, s41, v149
	ds_read_b128 v[178:181], v161
	ds_read_b128 v[182:185], v161 offset:1024
	ds_read_b128 v[186:189], v161 offset:2048
	ds_read_b128 v[190:193], v161 offset:3072
	s_add_u32 s18, s46, 0x40000
	s_addc_u32 s19, s47, 0
	s_mov_b32 m0, s58
	ds_read_b128 v[194:197], v160 offset:32768
	ds_read_b128 v[198:201], v160 offset:33792
	ds_read_b128 v[202:205], v160 offset:34816
	ds_read_b128 v[206:209], v160 offset:35840
	ds_read_b128 v[210:213], v160 offset:36864
	ds_read_b128 v[214:217], v160 offset:37888
	ds_read_b128 v[218:221], v160 offset:38912
	ds_read_b128 v[222:225], v160 offset:39936
	global_load_lds_dwordx4 v130, s[18:19]
	s_mov_b32 m0, s59
	s_nop 0
	global_load_lds_dwordx4 v134, s[18:19]
	s_waitcnt vmcnt(8)
	s_waitcnt lgkmcnt(0)
	s_barrier
	s_setprio 1
	s_waitcnt lgkmcnt(0)
	v_mfma_f32_16x16x32_bf16 v[124:127], v[162:165], v[194:197], v[124:127]
	v_mfma_f32_16x16x32_bf16 v[120:123], v[170:173], v[194:197], v[120:123]
	v_mfma_f32_16x16x32_bf16 v[116:119], v[162:165], v[202:205], v[116:119]
	v_mfma_f32_16x16x32_bf16 v[108:111], v[170:173], v[202:205], v[108:111]
	v_mfma_f32_16x16x32_bf16 v[100:103], v[162:165], v[210:213], v[100:103]
	v_mfma_f32_16x16x32_bf16 v[92:95], v[170:173], v[210:213], v[92:95]
	v_mfma_f32_16x16x32_bf16 v[84:87], v[162:165], v[218:221], v[84:87]
	v_mfma_f32_16x16x32_bf16 v[76:79], v[170:173], v[218:221], v[76:79]
	v_mfma_f32_16x16x32_bf16 v[124:127], v[166:169], v[198:201], v[124:127]
	v_mfma_f32_16x16x32_bf16 v[120:123], v[174:177], v[198:201], v[120:123]
	v_mfma_f32_16x16x32_bf16 v[116:119], v[166:169], v[206:209], v[116:119]
	v_mfma_f32_16x16x32_bf16 v[108:111], v[174:177], v[206:209], v[108:111]
	v_mfma_f32_16x16x32_bf16 v[100:103], v[166:169], v[214:217], v[100:103]
	v_mfma_f32_16x16x32_bf16 v[92:95], v[174:177], v[214:217], v[92:95]
	v_mfma_f32_16x16x32_bf16 v[84:87], v[166:169], v[222:225], v[84:87]
	v_mfma_f32_16x16x32_bf16 v[76:79], v[174:177], v[222:225], v[76:79]
	s_setprio 0
	s_setprio 1
	v_mfma_f32_16x16x32_bf16 v[112:115], v[178:181], v[194:197], v[112:115]
	v_mfma_f32_16x16x32_bf16 v[104:107], v[186:189], v[194:197], v[104:107]
	v_mfma_f32_16x16x32_bf16 v[96:99], v[178:181], v[202:205], v[96:99]
	v_mfma_f32_16x16x32_bf16 v[88:91], v[186:189], v[202:205], v[88:91]
	v_mfma_f32_16x16x32_bf16 v[80:83], v[178:181], v[210:213], v[80:83]
	v_mfma_f32_16x16x32_bf16 v[72:75], v[186:189], v[210:213], v[72:75]
	v_mfma_f32_16x16x32_bf16 v[68:71], v[178:181], v[218:221], v[68:71]
	v_mfma_f32_16x16x32_bf16 v[64:67], v[186:189], v[218:221], v[64:67]
	v_mfma_f32_16x16x32_bf16 v[112:115], v[182:185], v[198:201], v[112:115]
	v_mfma_f32_16x16x32_bf16 v[104:107], v[190:193], v[198:201], v[104:107]
	v_mfma_f32_16x16x32_bf16 v[96:99], v[182:185], v[206:209], v[96:99]
	v_mfma_f32_16x16x32_bf16 v[88:91], v[190:193], v[206:209], v[88:91]
	v_mfma_f32_16x16x32_bf16 v[80:83], v[182:185], v[214:217], v[80:83]
	v_mfma_f32_16x16x32_bf16 v[72:75], v[190:193], v[214:217], v[72:75]
	v_mfma_f32_16x16x32_bf16 v[68:71], v[182:185], v[222:225], v[68:71]
	v_mfma_f32_16x16x32_bf16 v[64:67], v[190:193], v[222:225], v[64:67]
	s_setprio 0
	s_barrier
	s_add_i32 s18, s40, s48
	s_mov_b32 m0, s18
	ds_read_b128 v[194:197], v160 offset:49152
	ds_read_b128 v[198:201], v160 offset:50176
	ds_read_b128 v[202:205], v160 offset:51200
	ds_read_b128 v[206:209], v160 offset:52224
	ds_read_b128 v[210:213], v160 offset:53248
	ds_read_b128 v[214:217], v160 offset:54272
	ds_read_b128 v[218:221], v160 offset:55296
	ds_read_b128 v[222:225], v160 offset:56320
	global_load_lds_dwordx4 v132, s[98:99]
	s_add_i32 m0, s18, 0x2000
	s_add_u32 s18, s38, 0x40080
	s_addc_u32 s19, s39, 0
	s_add_i32 s38, s41, s48
	global_load_lds_dwordx4 v136, s[98:99]
	s_mov_b32 m0, s38
	s_nop 0
	global_load_lds_dwordx4 v132, s[18:19]
	s_add_i32 m0, s38, 0x2000
	s_nop 0
	global_load_lds_dwordx4 v136, s[18:19]
	s_mov_b32 m0, s64
	s_nop 0
	global_load_lds_dwordx4 v130, s[100:101]
	s_mov_b32 m0, s65
	s_nop 0
	global_load_lds_dwordx4 v134, s[100:101]
	s_waitcnt vmcnt(8)
	s_waitcnt lgkmcnt(0)
	s_barrier
	s_setprio 1
	s_waitcnt lgkmcnt(0)
	v_mfma_f32_16x16x32_bf16 v[60:63], v[162:165], v[194:197], v[60:63]
	v_mfma_f32_16x16x32_bf16 v[56:59], v[170:173], v[194:197], v[56:59]
	v_mfma_f32_16x16x32_bf16 v[52:55], v[162:165], v[202:205], v[52:55]
	v_mfma_f32_16x16x32_bf16 v[44:47], v[170:173], v[202:205], v[44:47]
	v_mfma_f32_16x16x32_bf16 v[36:39], v[162:165], v[210:213], v[36:39]
	v_mfma_f32_16x16x32_bf16 v[28:31], v[170:173], v[210:213], v[28:31]
	v_mfma_f32_16x16x32_bf16 v[20:23], v[162:165], v[218:221], v[20:23]
	v_mfma_f32_16x16x32_bf16 v[12:15], v[170:173], v[218:221], v[12:15]
	v_mfma_f32_16x16x32_bf16 v[60:63], v[166:169], v[198:201], v[60:63]
	v_mfma_f32_16x16x32_bf16 v[56:59], v[174:177], v[198:201], v[56:59]
	v_mfma_f32_16x16x32_bf16 v[52:55], v[166:169], v[206:209], v[52:55]
	v_mfma_f32_16x16x32_bf16 v[44:47], v[174:177], v[206:209], v[44:47]
	v_mfma_f32_16x16x32_bf16 v[36:39], v[166:169], v[214:217], v[36:39]
	v_mfma_f32_16x16x32_bf16 v[28:31], v[174:177], v[214:217], v[28:31]
	v_mfma_f32_16x16x32_bf16 v[20:23], v[166:169], v[222:225], v[20:23]
	v_mfma_f32_16x16x32_bf16 v[12:15], v[174:177], v[222:225], v[12:15]
	s_setprio 0
	s_setprio 1
	v_mfma_f32_16x16x32_bf16 v[48:51], v[178:181], v[194:197], v[48:51]
	v_mfma_f32_16x16x32_bf16 v[40:43], v[186:189], v[194:197], v[40:43]
	v_mfma_f32_16x16x32_bf16 v[32:35], v[178:181], v[202:205], v[32:35]
	v_mfma_f32_16x16x32_bf16 v[24:27], v[186:189], v[202:205], v[24:27]
	v_mfma_f32_16x16x32_bf16 v[16:19], v[178:181], v[210:213], v[16:19]
	v_mfma_f32_16x16x32_bf16 v[8:11], v[186:189], v[210:213], v[8:11]
	v_mfma_f32_16x16x32_bf16 v[4:7], v[178:181], v[218:221], v[4:7]
	v_mfma_f32_16x16x32_bf16 v[0:3], v[186:189], v[218:221], v[0:3]
	v_mfma_f32_16x16x32_bf16 v[48:51], v[182:185], v[198:201], v[48:51]
	v_mfma_f32_16x16x32_bf16 v[40:43], v[190:193], v[198:201], v[40:43]
	v_mfma_f32_16x16x32_bf16 v[32:35], v[182:185], v[206:209], v[32:35]
	v_mfma_f32_16x16x32_bf16 v[24:27], v[190:193], v[206:209], v[24:27]
	v_mfma_f32_16x16x32_bf16 v[16:19], v[182:185], v[214:217], v[16:19]
	v_mfma_f32_16x16x32_bf16 v[8:11], v[190:193], v[214:217], v[8:11]
	v_mfma_f32_16x16x32_bf16 v[4:7], v[182:185], v[222:225], v[4:7]
	v_mfma_f32_16x16x32_bf16 v[0:3], v[190:193], v[222:225], v[0:3]
	s_setprio 0
	s_barrier
	s_add_i32 s74, s74, 2
	s_add_u32 s36, s36, 0x100
	s_addc_u32 s37, s37, 0
	s_add_u32 s68, s68, 0x100
	s_addc_u32 s69, s69, 0
	s_cmp_gt_u32 s74, 13
	s_cbranch_scc0 .LBB0_664
	s_and_b64 vcc, exec, s[22:23]
	s_cbranch_vccz .LBB0_667
	s_barrier

.LBB0_688:
	s_add_u32 s40, s36, s48
	s_addc_u32 s41, s37, 0
	s_add_u32 s44, s40, 0x100
	s_addc_u32 s45, s41, 0
	s_and_b64 s[18:19], s[46:47], exec
	s_cselect_b32 s59, s4, s45
	s_cselect_b32 s58, s5, s44
	s_add_u32 s18, s34, s48
	s_addc_u32 s19, s35, 0
	s_add_u32 s44, s18, 0x100
	s_addc_u32 s45, s19, 0
	s_and_b64 s[18:19], s[46:47], exec
	s_cselect_b32 s65, s23, s45
	s_cselect_b32 s64, s25, s44
	s_add_u32 s68, s40, 0x10080
	ds_read_b128 v[158:161], v154
	ds_read_b128 v[162:165], v154 offset:1024
	ds_read_b128 v[166:169], v154 offset:2048
	ds_read_b128 v[170:173], v154 offset:3072
	ds_read_b128 v[174:177], v155
	ds_read_b128 v[178:181], v155 offset:1024
	ds_read_b128 v[182:185], v155 offset:2048
	ds_read_b128 v[186:189], v155 offset:3072
	s_addc_u32 s69, s41, 0
	s_add_i32 s51, s96, s74
	s_add_i32 m0, s52, 0xc000
	s_add_i32 s31, s52, 0xe000
	s_add_i32 s44, s51, 0x2000
	s_add_u32 s66, s64, 0x10000
	s_addc_u32 s67, s65, 0
	s_add_i32 s50, s97, s74
	s_add_i32 s45, s50, 0x2000
	s_add_i32 s19, 0, 0x18000
	s_add_i32 vcc_lo, 0, 0x1c000
	s_add_u32 s48, s58, 0x10000
	s_addc_u32 s49, s59, 0
	s_add_i32 vcc_hi, s19, s74
	s_add_i32 s41, vcc_hi, 0x2000
	s_add_u32 s46, s64, 0x10080
	s_addc_u32 s47, s65, 0
	s_add_i32 s40, vcc_lo, s74
	s_add_i32 s18, s40, 0x2000
	ds_read_b128 v[190:193], v156
	ds_read_b128 v[194:197], v156 offset:1024
	ds_read_b128 v[198:201], v156 offset:2048
	ds_read_b128 v[202:205], v156 offset:3072
	ds_read_b128 v[206:209], v156 offset:4096
	ds_read_b128 v[210:213], v156 offset:5120
	ds_read_b128 v[214:217], v156 offset:6144
	ds_read_b128 v[218:221], v156 offset:7168
	global_load_lds_dwordx4 v130, s[68:69]
	s_mov_b32 m0, s31
	s_nop 0
	global_load_lds_dwordx4 v134, s[68:69]
	s_waitcnt vmcnt(8)
	s_waitcnt lgkmcnt(0)
	s_barrier
	s_setprio 1
	s_waitcnt lgkmcnt(0)
	v_mfma_f32_16x16x32_bf16 v[124:127], v[158:161], v[190:193], v[124:127]
	v_mfma_f32_16x16x32_bf16 v[120:123], v[166:169], v[190:193], v[120:123]
	v_mfma_f32_16x16x32_bf16 v[116:119], v[158:161], v[198:201], v[116:119]
	v_mfma_f32_16x16x32_bf16 v[108:111], v[166:169], v[198:201], v[108:111]
	v_mfma_f32_16x16x32_bf16 v[100:103], v[158:161], v[206:209], v[100:103]
	v_mfma_f32_16x16x32_bf16 v[92:95], v[166:169], v[206:209], v[92:95]
	v_mfma_f32_16x16x32_bf16 v[84:87], v[158:161], v[214:217], v[84:87]
	v_mfma_f32_16x16x32_bf16 v[76:79], v[166:169], v[214:217], v[76:79]
	v_mfma_f32_16x16x32_bf16 v[124:127], v[162:165], v[194:197], v[124:127]
	v_mfma_f32_16x16x32_bf16 v[120:123], v[170:173], v[194:197], v[120:123]
	v_mfma_f32_16x16x32_bf16 v[116:119], v[162:165], v[202:205], v[116:119]
	v_mfma_f32_16x16x32_bf16 v[108:111], v[170:173], v[202:205], v[108:111]
	v_mfma_f32_16x16x32_bf16 v[100:103], v[162:165], v[210:213], v[100:103]
	v_mfma_f32_16x16x32_bf16 v[92:95], v[170:173], v[210:213], v[92:95]
	v_mfma_f32_16x16x32_bf16 v[84:87], v[162:165], v[218:221], v[84:87]
	v_mfma_f32_16x16x32_bf16 v[76:79], v[170:173], v[218:221], v[76:79]
	s_setprio 0
	s_setprio 1
	v_mfma_f32_16x16x32_bf16 v[112:115], v[174:177], v[190:193], v[112:115]
	v_mfma_f32_16x16x32_bf16 v[104:107], v[182:185], v[190:193], v[104:107]
	v_mfma_f32_16x16x32_bf16 v[96:99], v[174:177], v[198:201], v[96:99]
	v_mfma_f32_16x16x32_bf16 v[88:91], v[182:185], v[198:201], v[88:91]
	v_mfma_f32_16x16x32_bf16 v[80:83], v[174:177], v[206:209], v[80:83]
	v_mfma_f32_16x16x32_bf16 v[72:75], v[182:185], v[206:209], v[72:75]
	v_mfma_f32_16x16x32_bf16 v[68:71], v[174:177], v[214:217], v[68:71]
	v_mfma_f32_16x16x32_bf16 v[64:67], v[182:185], v[214:217], v[64:67]
	v_mfma_f32_16x16x32_bf16 v[112:115], v[178:181], v[194:197], v[112:115]
	v_mfma_f32_16x16x32_bf16 v[104:107], v[186:189], v[194:197], v[104:107]
	v_mfma_f32_16x16x32_bf16 v[96:99], v[178:181], v[202:205], v[96:99]
	v_mfma_f32_16x16x32_bf16 v[88:91], v[186:189], v[202:205], v[88:91]
	v_mfma_f32_16x16x32_bf16 v[80:83], v[178:181], v[210:213], v[80:83]
	v_mfma_f32_16x16x32_bf16 v[72:75], v[186:189], v[210:213], v[72:75]
	v_mfma_f32_16x16x32_bf16 v[68:71], v[178:181], v[218:221], v[68:71]
	v_mfma_f32_16x16x32_bf16 v[64:67], v[186:189], v[218:221], v[64:67]
	s_setprio 0
	s_barrier
	s_mov_b32 m0, s51
	s_add_u32 s98, s64, s12
	s_addc_u32 s99, s65, s13
	ds_read_b128 v[190:193], v156 offset:16384
	ds_read_b128 v[194:197], v156 offset:17408
	ds_read_b128 v[198:201], v156 offset:18432
	ds_read_b128 v[202:205], v156 offset:19456
	ds_read_b128 v[206:209], v156 offset:20480
	ds_read_b128 v[210:213], v156 offset:21504
	ds_read_b128 v[214:217], v156 offset:22528
	ds_read_b128 v[218:221], v156 offset:23552
	global_load_lds_dwordx4 v132, s[64:65]
	s_mov_b32 m0, s44
	s_nop 0
	global_load_lds_dwordx4 v136, s[64:65]
	s_mov_b32 m0, s50
	s_add_u32 s100, s58, s12
	s_addc_u32 s101, s59, s13
	global_load_lds_dwordx4 v132, s[66:67]
	s_mov_b32 m0, s45
	s_nop 0
	global_load_lds_dwordx4 v136, s[66:67]
	s_mov_b32 m0, s52
	s_nop 0
	global_load_lds_dwordx4 v130, s[58:59]
	s_mov_b32 m0, s77
	s_nop 0
	global_load_lds_dwordx4 v134, s[58:59]
	s_waitcnt vmcnt(8)
	s_waitcnt lgkmcnt(0)
	s_barrier
	s_setprio 1
	s_waitcnt lgkmcnt(0)
	v_mfma_f32_16x16x32_bf16 v[60:63], v[158:161], v[190:193], v[60:63]
	v_mfma_f32_16x16x32_bf16 v[56:59], v[166:169], v[190:193], v[56:59]
	v_mfma_f32_16x16x32_bf16 v[52:55], v[158:161], v[198:201], v[52:55]
	v_mfma_f32_16x16x32_bf16 v[44:47], v[166:169], v[198:201], v[44:47]
	v_mfma_f32_16x16x32_bf16 v[36:39], v[158:161], v[206:209], v[36:39]
	v_mfma_f32_16x16x32_bf16 v[28:31], v[166:169], v[206:209], v[28:31]
	v_mfma_f32_16x16x32_bf16 v[20:23], v[158:161], v[214:217], v[20:23]
	v_mfma_f32_16x16x32_bf16 v[12:15], v[166:169], v[214:217], v[12:15]
	v_mfma_f32_16x16x32_bf16 v[60:63], v[162:165], v[194:197], v[60:63]
	v_mfma_f32_16x16x32_bf16 v[56:59], v[170:173], v[194:197], v[56:59]
	v_mfma_f32_16x16x32_bf16 v[52:55], v[162:165], v[202:205], v[52:55]
	v_mfma_f32_16x16x32_bf16 v[44:47], v[170:173], v[202:205], v[44:47]
	v_mfma_f32_16x16x32_bf16 v[36:39], v[162:165], v[210:213], v[36:39]
	v_mfma_f32_16x16x32_bf16 v[28:31], v[170:173], v[210:213], v[28:31]
	v_mfma_f32_16x16x32_bf16 v[20:23], v[162:165], v[218:221], v[20:23]
	v_mfma_f32_16x16x32_bf16 v[12:15], v[170:173], v[218:221], v[12:15]
	s_setprio 0
	s_setprio 1
	v_mfma_f32_16x16x32_bf16 v[48:51], v[174:177], v[190:193], v[48:51]
	v_mfma_f32_16x16x32_bf16 v[40:43], v[182:185], v[190:193], v[40:43]
	v_mfma_f32_16x16x32_bf16 v[32:35], v[174:177], v[198:201], v[32:35]
	v_mfma_f32_16x16x32_bf16 v[24:27], v[182:185], v[198:201], v[24:27]
	v_mfma_f32_16x16x32_bf16 v[16:19], v[174:177], v[206:209], v[16:19]
	v_mfma_f32_16x16x32_bf16 v[8:11], v[182:185], v[206:209], v[8:11]
	v_mfma_f32_16x16x32_bf16 v[4:7], v[174:177], v[214:217], v[4:7]
	v_mfma_f32_16x16x32_bf16 v[0:3], v[182:185], v[214:217], v[0:3]
	v_mfma_f32_16x16x32_bf16 v[48:51], v[178:181], v[194:197], v[48:51]
	v_mfma_f32_16x16x32_bf16 v[40:43], v[186:189], v[194:197], v[40:43]
	v_mfma_f32_16x16x32_bf16 v[32:35], v[178:181], v[202:205], v[32:35]
	v_mfma_f32_16x16x32_bf16 v[24:27], v[186:189], v[202:205], v[24:27]
	v_mfma_f32_16x16x32_bf16 v[16:19], v[178:181], v[210:213], v[16:19]
	v_mfma_f32_16x16x32_bf16 v[8:11], v[186:189], v[210:213], v[8:11]
	v_mfma_f32_16x16x32_bf16 v[4:7], v[178:181], v[218:221], v[4:7]
	v_mfma_f32_16x16x32_bf16 v[0:3], v[186:189], v[218:221], v[0:3]
	s_setprio 0
	s_barrier
	v_add_u32_e32 v157, s19, v144
	ds_read_b128 v[158:161], v157
	ds_read_b128 v[162:165], v157 offset:1024
	ds_read_b128 v[166:169], v157 offset:2048
	ds_read_b128 v[170:173], v157 offset:3072
	v_add_u32_e32 v157, vcc_lo, v144
	ds_read_b128 v[174:177], v157
	ds_read_b128 v[178:181], v157 offset:1024
	ds_read_b128 v[182:185], v157 offset:2048
	ds_read_b128 v[186:189], v157 offset:3072
	s_mov_b32 m0, s78
	ds_read_b128 v[190:193], v156 offset:32768
	ds_read_b128 v[194:197], v156 offset:33792
	ds_read_b128 v[198:201], v156 offset:34816
	ds_read_b128 v[202:205], v156 offset:35840
	ds_read_b128 v[206:209], v156 offset:36864
	ds_read_b128 v[210:213], v156 offset:37888
	ds_read_b128 v[214:217], v156 offset:38912
	ds_read_b128 v[218:221], v156 offset:39936
	global_load_lds_dwordx4 v130, s[48:49]
	s_mov_b32 m0, s79
	s_nop 0
	global_load_lds_dwordx4 v134, s[48:49]
	s_waitcnt vmcnt(8)
	s_waitcnt lgkmcnt(0)
	s_barrier
	s_setprio 1
	s_waitcnt lgkmcnt(0)
	v_mfma_f32_16x16x32_bf16 v[124:127], v[158:161], v[190:193], v[124:127]
	v_mfma_f32_16x16x32_bf16 v[120:123], v[166:169], v[190:193], v[120:123]
	v_mfma_f32_16x16x32_bf16 v[116:119], v[158:161], v[198:201], v[116:119]
	v_mfma_f32_16x16x32_bf16 v[108:111], v[166:169], v[198:201], v[108:111]
	v_mfma_f32_16x16x32_bf16 v[100:103], v[158:161], v[206:209], v[100:103]
	v_mfma_f32_16x16x32_bf16 v[92:95], v[166:169], v[206:209], v[92:95]
	v_mfma_f32_16x16x32_bf16 v[84:87], v[158:161], v[214:217], v[84:87]
	v_mfma_f32_16x16x32_bf16 v[76:79], v[166:169], v[214:217], v[76:79]
	v_mfma_f32_16x16x32_bf16 v[124:127], v[162:165], v[194:197], v[124:127]
	v_mfma_f32_16x16x32_bf16 v[120:123], v[170:173], v[194:197], v[120:123]
	v_mfma_f32_16x16x32_bf16 v[116:119], v[162:165], v[202:205], v[116:119]
	v_mfma_f32_16x16x32_bf16 v[108:111], v[170:173], v[202:205], v[108:111]
	v_mfma_f32_16x16x32_bf16 v[100:103], v[162:165], v[210:213], v[100:103]
	v_mfma_f32_16x16x32_bf16 v[92:95], v[170:173], v[210:213], v[92:95]
	v_mfma_f32_16x16x32_bf16 v[84:87], v[162:165], v[218:221], v[84:87]
	v_mfma_f32_16x16x32_bf16 v[76:79], v[170:173], v[218:221], v[76:79]
	s_setprio 0
	s_setprio 1
	v_mfma_f32_16x16x32_bf16 v[112:115], v[174:177], v[190:193], v[112:115]
	v_mfma_f32_16x16x32_bf16 v[104:107], v[182:185], v[190:193], v[104:107]
	v_mfma_f32_16x16x32_bf16 v[96:99], v[174:177], v[198:201], v[96:99]
	v_mfma_f32_16x16x32_bf16 v[88:91], v[182:185], v[198:201], v[88:91]
	v_mfma_f32_16x16x32_bf16 v[80:83], v[174:177], v[206:209], v[80:83]
	v_mfma_f32_16x16x32_bf16 v[72:75], v[182:185], v[206:209], v[72:75]
	v_mfma_f32_16x16x32_bf16 v[68:71], v[174:177], v[214:217], v[68:71]
	v_mfma_f32_16x16x32_bf16 v[64:67], v[182:185], v[214:217], v[64:67]
	v_mfma_f32_16x16x32_bf16 v[112:115], v[178:181], v[194:197], v[112:115]
	v_mfma_f32_16x16x32_bf16 v[104:107], v[186:189], v[194:197], v[104:107]
	v_mfma_f32_16x16x32_bf16 v[96:99], v[178:181], v[202:205], v[96:99]
	v_mfma_f32_16x16x32_bf16 v[88:91], v[186:189], v[202:205], v[88:91]
	v_mfma_f32_16x16x32_bf16 v[80:83], v[178:181], v[210:213], v[80:83]
	v_mfma_f32_16x16x32_bf16 v[72:75], v[186:189], v[210:213], v[72:75]
	v_mfma_f32_16x16x32_bf16 v[68:71], v[178:181], v[218:221], v[68:71]
	v_mfma_f32_16x16x32_bf16 v[64:67], v[186:189], v[218:221], v[64:67]
	s_setprio 0
	s_barrier
	s_mov_b32 m0, vcc_hi
	ds_read_b128 v[190:193], v156 offset:49152
	ds_read_b128 v[194:197], v156 offset:50176
	ds_read_b128 v[198:201], v156 offset:51200
	ds_read_b128 v[202:205], v156 offset:52224
	ds_read_b128 v[206:209], v156 offset:53248
	ds_read_b128 v[210:213], v156 offset:54272
	ds_read_b128 v[214:217], v156 offset:55296
	ds_read_b128 v[218:221], v156 offset:56320
	global_load_lds_dwordx4 v132, s[98:99]
	s_mov_b32 m0, s41
	s_nop 0
	global_load_lds_dwordx4 v136, s[98:99]
	s_mov_b32 m0, s40
	s_nop 0
	global_load_lds_dwordx4 v132, s[46:47]
	s_mov_b32 m0, s18
	s_nop 0
	global_load_lds_dwordx4 v136, s[46:47]
	s_mov_b32 m0, s88
	s_nop 0
	global_load_lds_dwordx4 v130, s[100:101]
	s_mov_b32 m0, s89
	s_nop 0
	global_load_lds_dwordx4 v134, s[100:101]
	s_waitcnt vmcnt(8)
	s_waitcnt lgkmcnt(0)
	s_barrier
	s_setprio 1
	s_waitcnt lgkmcnt(0)
	v_mfma_f32_16x16x32_bf16 v[60:63], v[158:161], v[190:193], v[60:63]
	v_mfma_f32_16x16x32_bf16 v[56:59], v[166:169], v[190:193], v[56:59]
	v_mfma_f32_16x16x32_bf16 v[52:55], v[158:161], v[198:201], v[52:55]
	v_mfma_f32_16x16x32_bf16 v[44:47], v[166:169], v[198:201], v[44:47]
	v_mfma_f32_16x16x32_bf16 v[36:39], v[158:161], v[206:209], v[36:39]
	v_mfma_f32_16x16x32_bf16 v[28:31], v[166:169], v[206:209], v[28:31]
	v_mfma_f32_16x16x32_bf16 v[20:23], v[158:161], v[214:217], v[20:23]
	v_mfma_f32_16x16x32_bf16 v[12:15], v[166:169], v[214:217], v[12:15]
	v_mfma_f32_16x16x32_bf16 v[60:63], v[162:165], v[194:197], v[60:63]
	v_mfma_f32_16x16x32_bf16 v[56:59], v[170:173], v[194:197], v[56:59]
	v_mfma_f32_16x16x32_bf16 v[52:55], v[162:165], v[202:205], v[52:55]
	v_mfma_f32_16x16x32_bf16 v[44:47], v[170:173], v[202:205], v[44:47]
	v_mfma_f32_16x16x32_bf16 v[36:39], v[162:165], v[210:213], v[36:39]
	v_mfma_f32_16x16x32_bf16 v[28:31], v[170:173], v[210:213], v[28:31]
	v_mfma_f32_16x16x32_bf16 v[20:23], v[162:165], v[218:221], v[20:23]
	v_mfma_f32_16x16x32_bf16 v[12:15], v[170:173], v[218:221], v[12:15]
	s_setprio 0
	s_setprio 1
	v_mfma_f32_16x16x32_bf16 v[48:51], v[174:177], v[190:193], v[48:51]
	v_mfma_f32_16x16x32_bf16 v[40:43], v[182:185], v[190:193], v[40:43]
	v_mfma_f32_16x16x32_bf16 v[32:35], v[174:177], v[198:201], v[32:35]
	v_mfma_f32_16x16x32_bf16 v[24:27], v[182:185], v[198:201], v[24:27]
	v_mfma_f32_16x16x32_bf16 v[16:19], v[174:177], v[206:209], v[16:19]
	v_mfma_f32_16x16x32_bf16 v[8:11], v[182:185], v[206:209], v[8:11]
	v_mfma_f32_16x16x32_bf16 v[4:7], v[174:177], v[214:217], v[4:7]
	v_mfma_f32_16x16x32_bf16 v[0:3], v[182:185], v[214:217], v[0:3]
	v_mfma_f32_16x16x32_bf16 v[48:51], v[178:181], v[194:197], v[48:51]
	v_mfma_f32_16x16x32_bf16 v[40:43], v[186:189], v[194:197], v[40:43]
	v_mfma_f32_16x16x32_bf16 v[32:35], v[178:181], v[202:205], v[32:35]
	v_mfma_f32_16x16x32_bf16 v[24:27], v[186:189], v[202:205], v[24:27]
	v_mfma_f32_16x16x32_bf16 v[16:19], v[178:181], v[210:213], v[16:19]
	v_mfma_f32_16x16x32_bf16 v[8:11], v[186:189], v[210:213], v[8:11]
	v_mfma_f32_16x16x32_bf16 v[4:7], v[178:181], v[218:221], v[4:7]
	v_mfma_f32_16x16x32_bf16 v[0:3], v[186:189], v[218:221], v[0:3]
	s_setprio 0
	s_barrier
	s_movk_i32 s48, 0x100
	s_andn2_b64 vcc, exec, s[38:39]
	s_mov_b64 s[46:47], -1
	s_mov_b64 s[38:39], 0
	s_cbranch_vccz .LBB0_688
	s_and_b64 vcc, exec, s[20:21]
	s_cbranch_vccz .LBB0_691
	s_barrier

.LBB0_970:
	ds_read_b128 v[160:163], v156
	ds_read_b128 v[164:167], v156 offset:1024
	ds_read_b128 v[168:171], v156 offset:2048
	ds_read_b128 v[172:175], v156 offset:3072
	ds_read_b128 v[176:179], v157
	ds_read_b128 v[180:183], v157 offset:1024
	ds_read_b128 v[184:187], v157 offset:2048
	ds_read_b128 v[188:191], v157 offset:3072
	s_add_u32 s24, s22, 0xfffc0080
	s_addc_u32 s25, s23, -1
	s_cmp_eq_u32 s43, 12
	s_cselect_b32 s27, s4, s25
	s_cselect_b32 s26, s5, s24
	s_cselect_b32 s25, s13, s42
	s_cselect_b32 s24, s15, s41
	s_add_i32 m0, s21, 0xc000
	ds_read_b128 v[192:195], v158
	ds_read_b128 v[196:199], v158 offset:1024
	ds_read_b128 v[200:203], v158 offset:2048
	ds_read_b128 v[204:207], v158 offset:3072
	ds_read_b128 v[208:211], v158 offset:4096
	ds_read_b128 v[212:215], v158 offset:5120
	ds_read_b128 v[216:219], v158 offset:6144
	ds_read_b128 v[220:223], v158 offset:7168
	global_load_lds_dwordx4 v136, s[22:23]
	s_add_i32 m0, s21, 0xe000
	s_nop 0
	global_load_lds_dwordx4 v138, s[22:23]
	s_waitcnt vmcnt(8)
	s_waitcnt lgkmcnt(0)
	s_barrier
	s_setprio 1
	s_waitcnt lgkmcnt(0)
	v_mfma_f32_16x16x32_bf16 v[124:127], v[160:163], v[192:195], v[124:127]
	v_mfma_f32_16x16x32_bf16 v[120:123], v[168:171], v[192:195], v[120:123]
	v_mfma_f32_16x16x32_bf16 v[116:119], v[160:163], v[200:203], v[116:119]
	v_mfma_f32_16x16x32_bf16 v[108:111], v[168:171], v[200:203], v[108:111]
	v_mfma_f32_16x16x32_bf16 v[100:103], v[160:163], v[208:211], v[100:103]
	v_mfma_f32_16x16x32_bf16 v[92:95], v[168:171], v[208:211], v[92:95]
	v_mfma_f32_16x16x32_bf16 v[84:87], v[160:163], v[216:219], v[84:87]
	v_mfma_f32_16x16x32_bf16 v[76:79], v[168:171], v[216:219], v[76:79]
	v_mfma_f32_16x16x32_bf16 v[124:127], v[164:167], v[196:199], v[124:127]
	v_mfma_f32_16x16x32_bf16 v[120:123], v[172:175], v[196:199], v[120:123]
	v_mfma_f32_16x16x32_bf16 v[116:119], v[164:167], v[204:207], v[116:119]
	v_mfma_f32_16x16x32_bf16 v[108:111], v[172:175], v[204:207], v[108:111]
	v_mfma_f32_16x16x32_bf16 v[100:103], v[164:167], v[212:215], v[100:103]
	v_mfma_f32_16x16x32_bf16 v[92:95], v[172:175], v[212:215], v[92:95]
	v_mfma_f32_16x16x32_bf16 v[84:87], v[164:167], v[220:223], v[84:87]
	v_mfma_f32_16x16x32_bf16 v[76:79], v[172:175], v[220:223], v[76:79]
	s_setprio 0
	s_setprio 1
	v_mfma_f32_16x16x32_bf16 v[112:115], v[176:179], v[192:195], v[112:115]
	v_mfma_f32_16x16x32_bf16 v[104:107], v[184:187], v[192:195], v[104:107]
	v_mfma_f32_16x16x32_bf16 v[96:99], v[176:179], v[200:203], v[96:99]
	v_mfma_f32_16x16x32_bf16 v[88:91], v[184:187], v[200:203], v[88:91]
	v_mfma_f32_16x16x32_bf16 v[80:83], v[176:179], v[208:211], v[80:83]
	v_mfma_f32_16x16x32_bf16 v[72:75], v[184:187], v[208:211], v[72:75]
	v_mfma_f32_16x16x32_bf16 v[68:71], v[176:179], v[216:219], v[68:71]
	v_mfma_f32_16x16x32_bf16 v[64:67], v[184:187], v[216:219], v[64:67]
	v_mfma_f32_16x16x32_bf16 v[112:115], v[180:183], v[196:199], v[112:115]
	v_mfma_f32_16x16x32_bf16 v[104:107], v[188:191], v[196:199], v[104:107]
	v_mfma_f32_16x16x32_bf16 v[96:99], v[180:183], v[204:207], v[96:99]
	v_mfma_f32_16x16x32_bf16 v[88:91], v[188:191], v[204:207], v[88:91]
	v_mfma_f32_16x16x32_bf16 v[80:83], v[180:183], v[212:215], v[80:83]
	v_mfma_f32_16x16x32_bf16 v[72:75], v[188:191], v[212:215], v[72:75]
	v_mfma_f32_16x16x32_bf16 v[68:71], v[180:183], v[220:223], v[68:71]
	v_mfma_f32_16x16x32_bf16 v[64:67], v[188:191], v[220:223], v[64:67]
	s_setprio 0
	s_barrier
	s_add_i32 s44, s38, s30
	s_add_u32 s98, s24, s8
	s_addc_u32 s99, s25, s9
	s_mov_b32 m0, s44
	ds_read_b128 v[192:195], v158 offset:16384
	ds_read_b128 v[196:199], v158 offset:17408
	ds_read_b128 v[200:203], v158 offset:18432
	ds_read_b128 v[204:207], v158 offset:19456
	ds_read_b128 v[208:211], v158 offset:20480
	ds_read_b128 v[212:215], v158 offset:21504
	ds_read_b128 v[216:219], v158 offset:22528
	ds_read_b128 v[220:223], v158 offset:23552
	global_load_lds_dwordx4 v132, s[24:25]
	s_add_i32 m0, s44, 0x2000
	s_add_u32 s44, s24, 0x40000
	s_addc_u32 s45, s25, 0
	s_add_i32 s46, s39, s30
	global_load_lds_dwordx4 v128, s[24:25]
	s_mov_b32 m0, s46
	s_add_u32 s100, s26, s8
	s_addc_u32 s101, s27, s9
	global_load_lds_dwordx4 v132, s[44:45]
	s_add_i32 m0, s46, 0x2000
	s_nop 0
	global_load_lds_dwordx4 v128, s[44:45]
	s_mov_b32 m0, s21
	s_nop 0
	global_load_lds_dwordx4 v134, s[26:27]
	s_mov_b32 m0, s31
	s_nop 0
	global_load_lds_dwordx4 v130, s[26:27]
	s_waitcnt vmcnt(8)
	s_waitcnt lgkmcnt(0)
	s_barrier
	s_setprio 1
	s_waitcnt lgkmcnt(0)
	v_mfma_f32_16x16x32_bf16 v[60:63], v[160:163], v[192:195], v[60:63]
	v_mfma_f32_16x16x32_bf16 v[56:59], v[168:171], v[192:195], v[56:59]
	v_mfma_f32_16x16x32_bf16 v[52:55], v[160:163], v[200:203], v[52:55]
	v_mfma_f32_16x16x32_bf16 v[44:47], v[168:171], v[200:203], v[44:47]
	v_mfma_f32_16x16x32_bf16 v[36:39], v[160:163], v[208:211], v[36:39]
	v_mfma_f32_16x16x32_bf16 v[28:31], v[168:171], v[208:211], v[28:31]
	v_mfma_f32_16x16x32_bf16 v[20:23], v[160:163], v[216:219], v[20:23]
	v_mfma_f32_16x16x32_bf16 v[12:15], v[168:171], v[216:219], v[12:15]
	v_mfma_f32_16x16x32_bf16 v[60:63], v[164:167], v[196:199], v[60:63]
	v_mfma_f32_16x16x32_bf16 v[56:59], v[172:175], v[196:199], v[56:59]
	v_mfma_f32_16x16x32_bf16 v[52:55], v[164:167], v[204:207], v[52:55]
	v_mfma_f32_16x16x32_bf16 v[44:47], v[172:175], v[204:207], v[44:47]
	v_mfma_f32_16x16x32_bf16 v[36:39], v[164:167], v[212:215], v[36:39]
	v_mfma_f32_16x16x32_bf16 v[28:31], v[172:175], v[212:215], v[28:31]
	v_mfma_f32_16x16x32_bf16 v[20:23], v[164:167], v[220:223], v[20:23]
	v_mfma_f32_16x16x32_bf16 v[12:15], v[172:175], v[220:223], v[12:15]
	s_setprio 0
	s_setprio 1
	v_mfma_f32_16x16x32_bf16 v[48:51], v[176:179], v[192:195], v[48:51]
	v_mfma_f32_16x16x32_bf16 v[40:43], v[184:187], v[192:195], v[40:43]
	v_mfma_f32_16x16x32_bf16 v[32:35], v[176:179], v[200:203], v[32:35]
	v_mfma_f32_16x16x32_bf16 v[24:27], v[184:187], v[200:203], v[24:27]
	v_mfma_f32_16x16x32_bf16 v[16:19], v[176:179], v[208:211], v[16:19]
	v_mfma_f32_16x16x32_bf16 v[8:11], v[184:187], v[208:211], v[8:11]
	v_mfma_f32_16x16x32_bf16 v[4:7], v[176:179], v[216:219], v[4:7]
	v_mfma_f32_16x16x32_bf16 v[0:3], v[184:187], v[216:219], v[0:3]
	v_mfma_f32_16x16x32_bf16 v[48:51], v[180:183], v[196:199], v[48:51]
	v_mfma_f32_16x16x32_bf16 v[40:43], v[188:191], v[196:199], v[40:43]
	v_mfma_f32_16x16x32_bf16 v[32:35], v[180:183], v[204:207], v[32:35]
	v_mfma_f32_16x16x32_bf16 v[24:27], v[188:191], v[204:207], v[24:27]
	v_mfma_f32_16x16x32_bf16 v[16:19], v[180:183], v[212:215], v[16:19]
	v_mfma_f32_16x16x32_bf16 v[8:11], v[188:191], v[212:215], v[8:11]
	v_mfma_f32_16x16x32_bf16 v[4:7], v[180:183], v[220:223], v[4:7]
	v_mfma_f32_16x16x32_bf16 v[0:3], v[188:191], v[220:223], v[0:3]
	s_setprio 0
	s_barrier
	s_add_i32 s44, 0, 0x18000
	v_add_u32_e32 v159, s44, v147
	s_add_i32 s45, 0, 0x1c000
	ds_read_b128 v[160:163], v159
	ds_read_b128 v[164:167], v159 offset:1024
	ds_read_b128 v[168:171], v159 offset:2048
	ds_read_b128 v[172:175], v159 offset:3072
	v_add_u32_e32 v159, s45, v147
	ds_read_b128 v[176:179], v159
	ds_read_b128 v[180:183], v159 offset:1024
	ds_read_b128 v[184:187], v159 offset:2048
	ds_read_b128 v[188:191], v159 offset:3072
	s_add_u32 s26, s26, 0x40000
	s_addc_u32 s27, s27, 0
	s_mov_b32 m0, s33
	ds_read_b128 v[192:195], v158 offset:32768
	ds_read_b128 v[196:199], v158 offset:33792
	ds_read_b128 v[200:203], v158 offset:34816
	ds_read_b128 v[204:207], v158 offset:35840
	ds_read_b128 v[208:211], v158 offset:36864
	ds_read_b128 v[212:215], v158 offset:37888
	ds_read_b128 v[216:219], v158 offset:38912
	ds_read_b128 v[220:223], v158 offset:39936
	global_load_lds_dwordx4 v134, s[26:27]
	s_mov_b32 m0, s34
	s_nop 0
	global_load_lds_dwordx4 v130, s[26:27]
	s_waitcnt vmcnt(8)
	s_waitcnt lgkmcnt(0)
	s_barrier
	s_setprio 1
	s_waitcnt lgkmcnt(0)
	v_mfma_f32_16x16x32_bf16 v[124:127], v[160:163], v[192:195], v[124:127]
	v_mfma_f32_16x16x32_bf16 v[120:123], v[168:171], v[192:195], v[120:123]
	v_mfma_f32_16x16x32_bf16 v[116:119], v[160:163], v[200:203], v[116:119]
	v_mfma_f32_16x16x32_bf16 v[108:111], v[168:171], v[200:203], v[108:111]
	v_mfma_f32_16x16x32_bf16 v[100:103], v[160:163], v[208:211], v[100:103]
	v_mfma_f32_16x16x32_bf16 v[92:95], v[168:171], v[208:211], v[92:95]
	v_mfma_f32_16x16x32_bf16 v[84:87], v[160:163], v[216:219], v[84:87]
	v_mfma_f32_16x16x32_bf16 v[76:79], v[168:171], v[216:219], v[76:79]
	v_mfma_f32_16x16x32_bf16 v[124:127], v[164:167], v[196:199], v[124:127]
	v_mfma_f32_16x16x32_bf16 v[120:123], v[172:175], v[196:199], v[120:123]
	v_mfma_f32_16x16x32_bf16 v[116:119], v[164:167], v[204:207], v[116:119]
	v_mfma_f32_16x16x32_bf16 v[108:111], v[172:175], v[204:207], v[108:111]
	v_mfma_f32_16x16x32_bf16 v[100:103], v[164:167], v[212:215], v[100:103]
	v_mfma_f32_16x16x32_bf16 v[92:95], v[172:175], v[212:215], v[92:95]
	v_mfma_f32_16x16x32_bf16 v[84:87], v[164:167], v[220:223], v[84:87]
	v_mfma_f32_16x16x32_bf16 v[76:79], v[172:175], v[220:223], v[76:79]
	s_setprio 0
	s_setprio 1
	v_mfma_f32_16x16x32_bf16 v[112:115], v[176:179], v[192:195], v[112:115]
	v_mfma_f32_16x16x32_bf16 v[104:107], v[184:187], v[192:195], v[104:107]
	v_mfma_f32_16x16x32_bf16 v[96:99], v[176:179], v[200:203], v[96:99]
	v_mfma_f32_16x16x32_bf16 v[88:91], v[184:187], v[200:203], v[88:91]
	v_mfma_f32_16x16x32_bf16 v[80:83], v[176:179], v[208:211], v[80:83]
	v_mfma_f32_16x16x32_bf16 v[72:75], v[184:187], v[208:211], v[72:75]
	v_mfma_f32_16x16x32_bf16 v[68:71], v[176:179], v[216:219], v[68:71]
	v_mfma_f32_16x16x32_bf16 v[64:67], v[184:187], v[216:219], v[64:67]
	v_mfma_f32_16x16x32_bf16 v[112:115], v[180:183], v[196:199], v[112:115]
	v_mfma_f32_16x16x32_bf16 v[104:107], v[188:191], v[196:199], v[104:107]
	v_mfma_f32_16x16x32_bf16 v[96:99], v[180:183], v[204:207], v[96:99]
	v_mfma_f32_16x16x32_bf16 v[88:91], v[188:191], v[204:207], v[88:91]
	v_mfma_f32_16x16x32_bf16 v[80:83], v[180:183], v[212:215], v[80:83]
	v_mfma_f32_16x16x32_bf16 v[72:75], v[188:191], v[212:215], v[72:75]
	v_mfma_f32_16x16x32_bf16 v[68:71], v[180:183], v[220:223], v[68:71]
	v_mfma_f32_16x16x32_bf16 v[64:67], v[188:191], v[220:223], v[64:67]
	s_setprio 0
	s_barrier
	s_add_i32 s26, s44, s30
	s_mov_b32 m0, s26
	ds_read_b128 v[192:195], v158 offset:49152
	ds_read_b128 v[196:199], v158 offset:50176
	ds_read_b128 v[200:203], v158 offset:51200
	ds_read_b128 v[204:207], v158 offset:52224
	ds_read_b128 v[208:211], v158 offset:53248
	ds_read_b128 v[212:215], v158 offset:54272
	ds_read_b128 v[216:219], v158 offset:55296
	ds_read_b128 v[220:223], v158 offset:56320
	global_load_lds_dwordx4 v132, s[98:99]
	s_add_i32 m0, s26, 0x2000
	s_add_u32 s24, s24, 0x40080
	s_addc_u32 s25, s25, 0
	s_add_i32 s26, s45, s30
	global_load_lds_dwordx4 v128, s[98:99]
	s_mov_b32 m0, s26
	s_nop 0
	global_load_lds_dwordx4 v132, s[24:25]
	s_add_i32 m0, s26, 0x2000
	s_nop 0
	global_load_lds_dwordx4 v128, s[24:25]
	s_mov_b32 m0, s36
	s_nop 0
	global_load_lds_dwordx4 v134, s[100:101]
	s_mov_b32 m0, s37
	s_nop 0
	global_load_lds_dwordx4 v130, s[100:101]
	s_waitcnt vmcnt(8)
	s_waitcnt lgkmcnt(0)
	s_barrier
	s_setprio 1
	s_waitcnt lgkmcnt(0)
	v_mfma_f32_16x16x32_bf16 v[60:63], v[160:163], v[192:195], v[60:63]
	v_mfma_f32_16x16x32_bf16 v[56:59], v[168:171], v[192:195], v[56:59]
	v_mfma_f32_16x16x32_bf16 v[52:55], v[160:163], v[200:203], v[52:55]
	v_mfma_f32_16x16x32_bf16 v[44:47], v[168:171], v[200:203], v[44:47]
	v_mfma_f32_16x16x32_bf16 v[36:39], v[160:163], v[208:211], v[36:39]
	v_mfma_f32_16x16x32_bf16 v[28:31], v[168:171], v[208:211], v[28:31]
	v_mfma_f32_16x16x32_bf16 v[20:23], v[160:163], v[216:219], v[20:23]
	v_mfma_f32_16x16x32_bf16 v[12:15], v[168:171], v[216:219], v[12:15]
	v_mfma_f32_16x16x32_bf16 v[60:63], v[164:167], v[196:199], v[60:63]
	v_mfma_f32_16x16x32_bf16 v[56:59], v[172:175], v[196:199], v[56:59]
	v_mfma_f32_16x16x32_bf16 v[52:55], v[164:167], v[204:207], v[52:55]
	v_mfma_f32_16x16x32_bf16 v[44:47], v[172:175], v[204:207], v[44:47]
	v_mfma_f32_16x16x32_bf16 v[36:39], v[164:167], v[212:215], v[36:39]
	v_mfma_f32_16x16x32_bf16 v[28:31], v[172:175], v[212:215], v[28:31]
	v_mfma_f32_16x16x32_bf16 v[20:23], v[164:167], v[220:223], v[20:23]
	v_mfma_f32_16x16x32_bf16 v[12:15], v[172:175], v[220:223], v[12:15]
	s_setprio 0
	s_setprio 1
	v_mfma_f32_16x16x32_bf16 v[48:51], v[176:179], v[192:195], v[48:51]
	v_mfma_f32_16x16x32_bf16 v[40:43], v[184:187], v[192:195], v[40:43]
	v_mfma_f32_16x16x32_bf16 v[32:35], v[176:179], v[200:203], v[32:35]
	v_mfma_f32_16x16x32_bf16 v[24:27], v[184:187], v[200:203], v[24:27]
	v_mfma_f32_16x16x32_bf16 v[16:19], v[176:179], v[208:211], v[16:19]
	v_mfma_f32_16x16x32_bf16 v[8:11], v[184:187], v[208:211], v[8:11]
	v_mfma_f32_16x16x32_bf16 v[4:7], v[176:179], v[216:219], v[4:7]
	v_mfma_f32_16x16x32_bf16 v[0:3], v[184:187], v[216:219], v[0:3]
	v_mfma_f32_16x16x32_bf16 v[48:51], v[180:183], v[196:199], v[48:51]
	v_mfma_f32_16x16x32_bf16 v[40:43], v[188:191], v[196:199], v[40:43]
	v_mfma_f32_16x16x32_bf16 v[32:35], v[180:183], v[204:207], v[32:35]
	v_mfma_f32_16x16x32_bf16 v[24:27], v[188:191], v[204:207], v[24:27]
	v_mfma_f32_16x16x32_bf16 v[16:19], v[180:183], v[212:215], v[16:19]
	v_mfma_f32_16x16x32_bf16 v[8:11], v[188:191], v[212:215], v[8:11]
	v_mfma_f32_16x16x32_bf16 v[4:7], v[180:183], v[220:223], v[4:7]
	v_mfma_f32_16x16x32_bf16 v[0:3], v[188:191], v[220:223], v[0:3]
	s_setprio 0
	s_barrier
	s_add_i32 s43, s43, 2
	s_add_u32 s22, s22, 0x100
	s_addc_u32 s23, s23, 0
	s_add_u32 s41, s41, 0x100
	s_addc_u32 s42, s42, 0
	s_cmp_gt_u32 s43, 13
	s_cbranch_scc0 .LBB0_970
	s_and_b64 vcc, exec, s[10:11]
	s_cbranch_vccz .LBB0_973
	s_barrier

.LBB0_1097:
	ds_read_b128 v[144:147], v151
	ds_read_b128 v[154:157], v151 offset:1024
	ds_read_b128 v[158:161], v151 offset:2048
	ds_read_b128 v[162:165], v151 offset:3072
	ds_read_b128 v[166:169], v152
	ds_read_b128 v[170:173], v152 offset:1024
	ds_read_b128 v[174:177], v152 offset:2048
	ds_read_b128 v[178:181], v152 offset:3072
	s_add_u32 s26, s24, 0xfffc0080
	s_addc_u32 s27, s25, -1
	s_cmp_eq_u32 s44, 12
	s_cselect_b32 s29, s4, s27
	s_cselect_b32 s28, s5, s26
	s_cselect_b32 s27, s15, s43
	s_cselect_b32 s26, s17, s42
	s_add_i32 m0, s23, 0xc000
	ds_read_b128 v[182:185], v153
	ds_read_b128 v[186:189], v153 offset:1024
	ds_read_b128 v[190:193], v153 offset:2048
	ds_read_b128 v[194:197], v153 offset:3072
	ds_read_b128 v[198:201], v153 offset:4096
	ds_read_b128 v[202:205], v153 offset:5120
	ds_read_b128 v[206:209], v153 offset:6144
	ds_read_b128 v[210:213], v153 offset:7168
	global_load_lds_dwordx4 v136, s[24:25]
	s_add_i32 m0, s23, 0xe000
	s_nop 0
	global_load_lds_dwordx4 v138, s[24:25]
	s_waitcnt vmcnt(8)
	s_waitcnt lgkmcnt(0)
	s_barrier
	s_setprio 1
	s_waitcnt lgkmcnt(0)
	v_mfma_f32_16x16x32_bf16 v[124:127], v[144:147], v[182:185], v[124:127]
	v_mfma_f32_16x16x32_bf16 v[120:123], v[158:161], v[182:185], v[120:123]
	v_mfma_f32_16x16x32_bf16 v[108:111], v[144:147], v[190:193], v[108:111]
	v_mfma_f32_16x16x32_bf16 v[104:107], v[158:161], v[190:193], v[104:107]
	v_mfma_f32_16x16x32_bf16 v[92:95], v[144:147], v[198:201], v[92:95]
	v_mfma_f32_16x16x32_bf16 v[88:91], v[158:161], v[198:201], v[88:91]
	v_mfma_f32_16x16x32_bf16 v[76:79], v[144:147], v[206:209], v[76:79]
	v_mfma_f32_16x16x32_bf16 v[72:75], v[158:161], v[206:209], v[72:75]
	v_mfma_f32_16x16x32_bf16 v[124:127], v[154:157], v[186:189], v[124:127]
	v_mfma_f32_16x16x32_bf16 v[120:123], v[162:165], v[186:189], v[120:123]
	v_mfma_f32_16x16x32_bf16 v[108:111], v[154:157], v[194:197], v[108:111]
	v_mfma_f32_16x16x32_bf16 v[104:107], v[162:165], v[194:197], v[104:107]
	v_mfma_f32_16x16x32_bf16 v[92:95], v[154:157], v[202:205], v[92:95]
	v_mfma_f32_16x16x32_bf16 v[88:91], v[162:165], v[202:205], v[88:91]
	v_mfma_f32_16x16x32_bf16 v[76:79], v[154:157], v[210:213], v[76:79]
	v_mfma_f32_16x16x32_bf16 v[72:75], v[162:165], v[210:213], v[72:75]
	s_setprio 0
	s_setprio 1
	v_mfma_f32_16x16x32_bf16 v[116:119], v[166:169], v[182:185], v[116:119]
	v_mfma_f32_16x16x32_bf16 v[112:115], v[174:177], v[182:185], v[112:115]
	v_mfma_f32_16x16x32_bf16 v[100:103], v[166:169], v[190:193], v[100:103]
	v_mfma_f32_16x16x32_bf16 v[96:99], v[174:177], v[190:193], v[96:99]
	v_mfma_f32_16x16x32_bf16 v[84:87], v[166:169], v[198:201], v[84:87]
	v_mfma_f32_16x16x32_bf16 v[80:83], v[174:177], v[198:201], v[80:83]
	v_mfma_f32_16x16x32_bf16 v[68:71], v[166:169], v[206:209], v[68:71]
	v_mfma_f32_16x16x32_bf16 v[64:67], v[174:177], v[206:209], v[64:67]
	v_mfma_f32_16x16x32_bf16 v[116:119], v[170:173], v[186:189], v[116:119]
	v_mfma_f32_16x16x32_bf16 v[112:115], v[178:181], v[186:189], v[112:115]
	v_mfma_f32_16x16x32_bf16 v[100:103], v[170:173], v[194:197], v[100:103]
	v_mfma_f32_16x16x32_bf16 v[96:99], v[178:181], v[194:197], v[96:99]
	v_mfma_f32_16x16x32_bf16 v[84:87], v[170:173], v[202:205], v[84:87]
	v_mfma_f32_16x16x32_bf16 v[80:83], v[178:181], v[202:205], v[80:83]
	v_mfma_f32_16x16x32_bf16 v[68:71], v[170:173], v[210:213], v[68:71]
	v_mfma_f32_16x16x32_bf16 v[64:67], v[178:181], v[210:213], v[64:67]
	s_setprio 0
	s_barrier
	s_add_i32 s45, s39, s31
	s_add_u32 s98, s26, s8
	s_addc_u32 s99, s27, s9
	s_mov_b32 m0, s45
	ds_read_b128 v[182:185], v153 offset:16384
	ds_read_b128 v[186:189], v153 offset:17408
	ds_read_b128 v[190:193], v153 offset:18432
	ds_read_b128 v[194:197], v153 offset:19456
	ds_read_b128 v[198:201], v153 offset:20480
	ds_read_b128 v[202:205], v153 offset:21504
	ds_read_b128 v[206:209], v153 offset:22528
	ds_read_b128 v[210:213], v153 offset:23552
	global_load_lds_dwordx4 v132, s[26:27]
	s_add_i32 m0, s45, 0x2000
	s_add_u32 s46, s26, 0x40000
	s_addc_u32 s47, s27, 0
	s_add_i32 s45, s40, s31
	global_load_lds_dwordx4 v128, s[26:27]
	s_mov_b32 m0, s45
	s_add_u32 s100, s28, s8
	s_addc_u32 s101, s29, s9
	global_load_lds_dwordx4 v132, s[46:47]
	s_add_i32 m0, s45, 0x2000
	s_nop 0
	global_load_lds_dwordx4 v128, s[46:47]
	s_mov_b32 m0, s23
	s_nop 0
	global_load_lds_dwordx4 v134, s[28:29]
	s_mov_b32 m0, s33
	s_nop 0
	global_load_lds_dwordx4 v130, s[28:29]
	s_waitcnt vmcnt(8)
	s_waitcnt lgkmcnt(0)
	s_barrier
	s_setprio 1
	s_waitcnt lgkmcnt(0)
	v_mfma_f32_16x16x32_bf16 v[60:63], v[144:147], v[182:185], v[60:63]
	v_mfma_f32_16x16x32_bf16 v[56:59], v[158:161], v[182:185], v[56:59]
	v_mfma_f32_16x16x32_bf16 v[44:47], v[144:147], v[190:193], v[44:47]
	v_mfma_f32_16x16x32_bf16 v[40:43], v[158:161], v[190:193], v[40:43]
	v_mfma_f32_16x16x32_bf16 v[28:31], v[144:147], v[198:201], v[28:31]
	v_mfma_f32_16x16x32_bf16 v[24:27], v[158:161], v[198:201], v[24:27]
	v_mfma_f32_16x16x32_bf16 v[12:15], v[144:147], v[206:209], v[12:15]
	v_mfma_f32_16x16x32_bf16 v[8:11], v[158:161], v[206:209], v[8:11]
	v_mfma_f32_16x16x32_bf16 v[60:63], v[154:157], v[186:189], v[60:63]
	v_mfma_f32_16x16x32_bf16 v[56:59], v[162:165], v[186:189], v[56:59]
	v_mfma_f32_16x16x32_bf16 v[44:47], v[154:157], v[194:197], v[44:47]
	v_mfma_f32_16x16x32_bf16 v[40:43], v[162:165], v[194:197], v[40:43]
	v_mfma_f32_16x16x32_bf16 v[28:31], v[154:157], v[202:205], v[28:31]
	v_mfma_f32_16x16x32_bf16 v[24:27], v[162:165], v[202:205], v[24:27]
	v_mfma_f32_16x16x32_bf16 v[12:15], v[154:157], v[210:213], v[12:15]
	v_mfma_f32_16x16x32_bf16 v[8:11], v[162:165], v[210:213], v[8:11]
	s_setprio 0
	s_setprio 1
	v_mfma_f32_16x16x32_bf16 v[52:55], v[166:169], v[182:185], v[52:55]
	v_mfma_f32_16x16x32_bf16 v[48:51], v[174:177], v[182:185], v[48:51]
	v_mfma_f32_16x16x32_bf16 v[36:39], v[166:169], v[190:193], v[36:39]
	v_mfma_f32_16x16x32_bf16 v[32:35], v[174:177], v[190:193], v[32:35]
	v_mfma_f32_16x16x32_bf16 v[20:23], v[166:169], v[198:201], v[20:23]
	v_mfma_f32_16x16x32_bf16 v[16:19], v[174:177], v[198:201], v[16:19]
	v_mfma_f32_16x16x32_bf16 v[4:7], v[166:169], v[206:209], v[4:7]
	v_mfma_f32_16x16x32_bf16 v[0:3], v[174:177], v[206:209], v[0:3]
	v_mfma_f32_16x16x32_bf16 v[52:55], v[170:173], v[186:189], v[52:55]
	v_mfma_f32_16x16x32_bf16 v[48:51], v[178:181], v[186:189], v[48:51]
	v_mfma_f32_16x16x32_bf16 v[36:39], v[170:173], v[194:197], v[36:39]
	v_mfma_f32_16x16x32_bf16 v[32:35], v[178:181], v[194:197], v[32:35]
	v_mfma_f32_16x16x32_bf16 v[20:23], v[170:173], v[202:205], v[20:23]
	v_mfma_f32_16x16x32_bf16 v[16:19], v[178:181], v[202:205], v[16:19]
	v_mfma_f32_16x16x32_bf16 v[4:7], v[170:173], v[210:213], v[4:7]
	v_mfma_f32_16x16x32_bf16 v[0:3], v[178:181], v[210:213], v[0:3]
	s_setprio 0
	s_barrier
	s_add_i32 s45, 0, 0x18000
	s_add_i32 s46, 0, 0x1c000
	v_add_u32_e32 v162, s45, v149
	v_add_u32_e32 v178, s46, v149
	ds_read_b128 v[144:147], v162
	ds_read_b128 v[154:157], v162 offset:1024
	ds_read_b128 v[158:161], v162 offset:2048
	ds_read_b128 v[162:165], v162 offset:3072
	ds_read_b128 v[166:169], v178
	ds_read_b128 v[170:173], v178 offset:1024
	ds_read_b128 v[174:177], v178 offset:2048
	ds_read_b128 v[178:181], v178 offset:3072
	s_add_u32 s28, s28, 0x40000
	s_addc_u32 s29, s29, 0
	s_mov_b32 m0, s34
	ds_read_b128 v[182:185], v153 offset:32768
	ds_read_b128 v[186:189], v153 offset:33792
	ds_read_b128 v[190:193], v153 offset:34816
	ds_read_b128 v[194:197], v153 offset:35840
	ds_read_b128 v[198:201], v153 offset:36864
	ds_read_b128 v[202:205], v153 offset:37888
	ds_read_b128 v[206:209], v153 offset:38912
	ds_read_b128 v[210:213], v153 offset:39936
	global_load_lds_dwordx4 v134, s[28:29]
	s_mov_b32 m0, s35
	s_nop 0
	global_load_lds_dwordx4 v130, s[28:29]
	s_waitcnt vmcnt(8)
	s_waitcnt lgkmcnt(0)
	s_barrier
	s_setprio 1
	s_waitcnt lgkmcnt(0)
	v_mfma_f32_16x16x32_bf16 v[124:127], v[144:147], v[182:185], v[124:127]
	v_mfma_f32_16x16x32_bf16 v[120:123], v[158:161], v[182:185], v[120:123]
	v_mfma_f32_16x16x32_bf16 v[108:111], v[144:147], v[190:193], v[108:111]
	v_mfma_f32_16x16x32_bf16 v[104:107], v[158:161], v[190:193], v[104:107]
	v_mfma_f32_16x16x32_bf16 v[92:95], v[144:147], v[198:201], v[92:95]
	v_mfma_f32_16x16x32_bf16 v[88:91], v[158:161], v[198:201], v[88:91]
	v_mfma_f32_16x16x32_bf16 v[76:79], v[144:147], v[206:209], v[76:79]
	v_mfma_f32_16x16x32_bf16 v[72:75], v[158:161], v[206:209], v[72:75]
	v_mfma_f32_16x16x32_bf16 v[124:127], v[154:157], v[186:189], v[124:127]
	v_mfma_f32_16x16x32_bf16 v[120:123], v[162:165], v[186:189], v[120:123]
	v_mfma_f32_16x16x32_bf16 v[108:111], v[154:157], v[194:197], v[108:111]
	v_mfma_f32_16x16x32_bf16 v[104:107], v[162:165], v[194:197], v[104:107]
	v_mfma_f32_16x16x32_bf16 v[92:95], v[154:157], v[202:205], v[92:95]
	v_mfma_f32_16x16x32_bf16 v[88:91], v[162:165], v[202:205], v[88:91]
	v_mfma_f32_16x16x32_bf16 v[76:79], v[154:157], v[210:213], v[76:79]
	v_mfma_f32_16x16x32_bf16 v[72:75], v[162:165], v[210:213], v[72:75]
	s_setprio 0
	s_setprio 1
	v_mfma_f32_16x16x32_bf16 v[116:119], v[166:169], v[182:185], v[116:119]
	v_mfma_f32_16x16x32_bf16 v[112:115], v[174:177], v[182:185], v[112:115]
	v_mfma_f32_16x16x32_bf16 v[100:103], v[166:169], v[190:193], v[100:103]
	v_mfma_f32_16x16x32_bf16 v[96:99], v[174:177], v[190:193], v[96:99]
	v_mfma_f32_16x16x32_bf16 v[84:87], v[166:169], v[198:201], v[84:87]
	v_mfma_f32_16x16x32_bf16 v[80:83], v[174:177], v[198:201], v[80:83]
	v_mfma_f32_16x16x32_bf16 v[68:71], v[166:169], v[206:209], v[68:71]
	v_mfma_f32_16x16x32_bf16 v[64:67], v[174:177], v[206:209], v[64:67]
	v_mfma_f32_16x16x32_bf16 v[116:119], v[170:173], v[186:189], v[116:119]
	v_mfma_f32_16x16x32_bf16 v[112:115], v[178:181], v[186:189], v[112:115]
	v_mfma_f32_16x16x32_bf16 v[100:103], v[170:173], v[194:197], v[100:103]
	v_mfma_f32_16x16x32_bf16 v[96:99], v[178:181], v[194:197], v[96:99]
	v_mfma_f32_16x16x32_bf16 v[84:87], v[170:173], v[202:205], v[84:87]
	v_mfma_f32_16x16x32_bf16 v[80:83], v[178:181], v[202:205], v[80:83]
	v_mfma_f32_16x16x32_bf16 v[68:71], v[170:173], v[210:213], v[68:71]
	v_mfma_f32_16x16x32_bf16 v[64:67], v[178:181], v[210:213], v[64:67]
	s_setprio 0
	s_barrier
	s_add_i32 s28, s45, s31
	s_mov_b32 m0, s28
	ds_read_b128 v[182:185], v153 offset:49152
	ds_read_b128 v[186:189], v153 offset:50176
	ds_read_b128 v[190:193], v153 offset:51200
	ds_read_b128 v[194:197], v153 offset:52224
	ds_read_b128 v[198:201], v153 offset:53248
	ds_read_b128 v[202:205], v153 offset:54272
	ds_read_b128 v[206:209], v153 offset:55296
	ds_read_b128 v[210:213], v153 offset:56320
	global_load_lds_dwordx4 v132, s[98:99]
	s_add_i32 m0, s28, 0x2000
	s_add_u32 s26, s26, 0x40080
	s_addc_u32 s27, s27, 0
	s_add_i32 s28, s46, s31
	global_load_lds_dwordx4 v128, s[98:99]
	s_mov_b32 m0, s28
	s_nop 0
	global_load_lds_dwordx4 v132, s[26:27]
	s_add_i32 m0, s28, 0x2000
	s_nop 0
	global_load_lds_dwordx4 v128, s[26:27]
	s_mov_b32 m0, s37
	s_nop 0
	global_load_lds_dwordx4 v134, s[100:101]
	s_mov_b32 m0, s38
	s_nop 0
	global_load_lds_dwordx4 v130, s[100:101]
	s_waitcnt vmcnt(8)
	s_waitcnt lgkmcnt(0)
	s_barrier
	s_setprio 1
	s_waitcnt lgkmcnt(0)
	v_mfma_f32_16x16x32_bf16 v[60:63], v[144:147], v[182:185], v[60:63]
	v_mfma_f32_16x16x32_bf16 v[56:59], v[158:161], v[182:185], v[56:59]
	v_mfma_f32_16x16x32_bf16 v[44:47], v[144:147], v[190:193], v[44:47]
	v_mfma_f32_16x16x32_bf16 v[40:43], v[158:161], v[190:193], v[40:43]
	v_mfma_f32_16x16x32_bf16 v[28:31], v[144:147], v[198:201], v[28:31]
	v_mfma_f32_16x16x32_bf16 v[24:27], v[158:161], v[198:201], v[24:27]
	v_mfma_f32_16x16x32_bf16 v[12:15], v[144:147], v[206:209], v[12:15]
	v_mfma_f32_16x16x32_bf16 v[8:11], v[158:161], v[206:209], v[8:11]
	v_mfma_f32_16x16x32_bf16 v[60:63], v[154:157], v[186:189], v[60:63]
	v_mfma_f32_16x16x32_bf16 v[56:59], v[162:165], v[186:189], v[56:59]
	v_mfma_f32_16x16x32_bf16 v[44:47], v[154:157], v[194:197], v[44:47]
	v_mfma_f32_16x16x32_bf16 v[40:43], v[162:165], v[194:197], v[40:43]
	v_mfma_f32_16x16x32_bf16 v[28:31], v[154:157], v[202:205], v[28:31]
	v_mfma_f32_16x16x32_bf16 v[24:27], v[162:165], v[202:205], v[24:27]
	v_mfma_f32_16x16x32_bf16 v[12:15], v[154:157], v[210:213], v[12:15]
	v_mfma_f32_16x16x32_bf16 v[8:11], v[162:165], v[210:213], v[8:11]
	s_setprio 0
	s_setprio 1
	v_mfma_f32_16x16x32_bf16 v[52:55], v[166:169], v[182:185], v[52:55]
	v_mfma_f32_16x16x32_bf16 v[48:51], v[174:177], v[182:185], v[48:51]
	v_mfma_f32_16x16x32_bf16 v[36:39], v[166:169], v[190:193], v[36:39]
	v_mfma_f32_16x16x32_bf16 v[32:35], v[174:177], v[190:193], v[32:35]
	v_mfma_f32_16x16x32_bf16 v[20:23], v[166:169], v[198:201], v[20:23]
	v_mfma_f32_16x16x32_bf16 v[16:19], v[174:177], v[198:201], v[16:19]
	v_mfma_f32_16x16x32_bf16 v[4:7], v[166:169], v[206:209], v[4:7]
	v_mfma_f32_16x16x32_bf16 v[0:3], v[174:177], v[206:209], v[0:3]
	v_mfma_f32_16x16x32_bf16 v[52:55], v[170:173], v[186:189], v[52:55]
	v_mfma_f32_16x16x32_bf16 v[48:51], v[178:181], v[186:189], v[48:51]
	v_mfma_f32_16x16x32_bf16 v[36:39], v[170:173], v[194:197], v[36:39]
	v_mfma_f32_16x16x32_bf16 v[32:35], v[178:181], v[194:197], v[32:35]
	v_mfma_f32_16x16x32_bf16 v[20:23], v[170:173], v[202:205], v[20:23]
	v_mfma_f32_16x16x32_bf16 v[16:19], v[178:181], v[202:205], v[16:19]
	v_mfma_f32_16x16x32_bf16 v[4:7], v[170:173], v[210:213], v[4:7]
	v_mfma_f32_16x16x32_bf16 v[0:3], v[178:181], v[210:213], v[0:3]
	s_setprio 0
	s_barrier
	s_add_i32 s44, s44, 2
	s_add_u32 s24, s24, 0x100
	s_addc_u32 s25, s25, 0
	s_add_u32 s42, s42, 0x100
	s_addc_u32 s43, s43, 0
	s_cmp_gt_u32 s44, 13
	s_cbranch_scc0 .LBB0_1097
	s_and_b64 vcc, exec, s[10:11]
	s_cbranch_vccz .LBB0_1100
	s_barrier

.LBB0_1234:
	ds_read_b128 v[150:153], v157
	ds_read_b128 v[160:163], v157 offset:1024
	ds_read_b128 v[164:167], v157 offset:2048
	ds_read_b128 v[168:171], v157 offset:3072
	ds_read_b128 v[172:175], v158
	ds_read_b128 v[176:179], v158 offset:1024
	ds_read_b128 v[180:183], v158 offset:2048
	ds_read_b128 v[184:187], v158 offset:3072
	s_add_u32 s30, s28, 0xfffc0080
	s_addc_u32 s31, s29, -1
	s_cmp_eq_u32 s46, 12
	s_cselect_b32 s35, s4, s31
	s_cselect_b32 s34, s5, s30
	s_cselect_b32 s31, s17, s27
	s_cselect_b32 s30, s19, s25
	s_add_i32 m0, s37, 0xc000
	ds_read_b128 v[188:191], v159
	ds_read_b128 v[192:195], v159 offset:1024
	ds_read_b128 v[196:199], v159 offset:2048
	ds_read_b128 v[200:203], v159 offset:3072
	ds_read_b128 v[204:207], v159 offset:4096
	ds_read_b128 v[208:211], v159 offset:5120
	ds_read_b128 v[212:215], v159 offset:6144
	ds_read_b128 v[216:219], v159 offset:7168
	global_load_lds_dwordx4 v142, s[28:29]
	s_add_i32 m0, s37, 0xe000
	s_nop 0
	global_load_lds_dwordx4 v144, s[28:29]
	s_waitcnt vmcnt(8)
	s_waitcnt lgkmcnt(0)
	s_barrier
	s_setprio 1
	s_waitcnt lgkmcnt(0)
	v_mfma_f32_16x16x32_bf16 v[124:127], v[150:153], v[188:191], v[124:127]
	v_mfma_f32_16x16x32_bf16 v[120:123], v[164:167], v[188:191], v[120:123]
	v_mfma_f32_16x16x32_bf16 v[108:111], v[150:153], v[196:199], v[108:111]
	v_mfma_f32_16x16x32_bf16 v[104:107], v[164:167], v[196:199], v[104:107]
	v_mfma_f32_16x16x32_bf16 v[92:95], v[150:153], v[204:207], v[92:95]
	v_mfma_f32_16x16x32_bf16 v[88:91], v[164:167], v[204:207], v[88:91]
	v_mfma_f32_16x16x32_bf16 v[76:79], v[150:153], v[212:215], v[76:79]
	v_mfma_f32_16x16x32_bf16 v[72:75], v[164:167], v[212:215], v[72:75]
	v_mfma_f32_16x16x32_bf16 v[124:127], v[160:163], v[192:195], v[124:127]
	v_mfma_f32_16x16x32_bf16 v[120:123], v[168:171], v[192:195], v[120:123]
	v_mfma_f32_16x16x32_bf16 v[108:111], v[160:163], v[200:203], v[108:111]
	v_mfma_f32_16x16x32_bf16 v[104:107], v[168:171], v[200:203], v[104:107]
	v_mfma_f32_16x16x32_bf16 v[92:95], v[160:163], v[208:211], v[92:95]
	v_mfma_f32_16x16x32_bf16 v[88:91], v[168:171], v[208:211], v[88:91]
	v_mfma_f32_16x16x32_bf16 v[76:79], v[160:163], v[216:219], v[76:79]
	v_mfma_f32_16x16x32_bf16 v[72:75], v[168:171], v[216:219], v[72:75]
	s_setprio 0
	s_setprio 1
	v_mfma_f32_16x16x32_bf16 v[116:119], v[172:175], v[188:191], v[116:119]
	v_mfma_f32_16x16x32_bf16 v[112:115], v[180:183], v[188:191], v[112:115]
	v_mfma_f32_16x16x32_bf16 v[100:103], v[172:175], v[196:199], v[100:103]
	v_mfma_f32_16x16x32_bf16 v[96:99], v[180:183], v[196:199], v[96:99]
	v_mfma_f32_16x16x32_bf16 v[84:87], v[172:175], v[204:207], v[84:87]
	v_mfma_f32_16x16x32_bf16 v[80:83], v[180:183], v[204:207], v[80:83]
	v_mfma_f32_16x16x32_bf16 v[68:71], v[172:175], v[212:215], v[68:71]
	v_mfma_f32_16x16x32_bf16 v[64:67], v[180:183], v[212:215], v[64:67]
	v_mfma_f32_16x16x32_bf16 v[116:119], v[176:179], v[192:195], v[116:119]
	v_mfma_f32_16x16x32_bf16 v[112:115], v[184:187], v[192:195], v[112:115]
	v_mfma_f32_16x16x32_bf16 v[100:103], v[176:179], v[200:203], v[100:103]
	v_mfma_f32_16x16x32_bf16 v[96:99], v[184:187], v[200:203], v[96:99]
	v_mfma_f32_16x16x32_bf16 v[84:87], v[176:179], v[208:211], v[84:87]
	v_mfma_f32_16x16x32_bf16 v[80:83], v[184:187], v[208:211], v[80:83]
	v_mfma_f32_16x16x32_bf16 v[68:71], v[176:179], v[216:219], v[68:71]
	v_mfma_f32_16x16x32_bf16 v[64:67], v[184:187], v[216:219], v[64:67]
	s_setprio 0
	s_barrier
	s_add_i32 s47, s44, s36
	s_add_u32 s98, s30, s10
	s_addc_u32 s99, s31, s11
	s_mov_b32 m0, s47
	ds_read_b128 v[188:191], v159 offset:16384
	ds_read_b128 v[192:195], v159 offset:17408
	ds_read_b128 v[196:199], v159 offset:18432
	ds_read_b128 v[200:203], v159 offset:19456
	ds_read_b128 v[204:207], v159 offset:20480
	ds_read_b128 v[208:211], v159 offset:21504
	ds_read_b128 v[212:215], v159 offset:22528
	ds_read_b128 v[216:219], v159 offset:23552
	global_load_lds_dwordx4 v130, s[30:31]
	s_add_i32 m0, s47, 0x2000
	s_add_u32 s50, s30, 0x40000
	s_addc_u32 s51, s31, 0
	s_add_i32 s47, s45, s36
	global_load_lds_dwordx4 v134, s[30:31]
	s_mov_b32 m0, s47
	s_add_u32 s100, s34, s10
	s_addc_u32 s101, s35, s11
	global_load_lds_dwordx4 v130, s[50:51]
	s_add_i32 m0, s47, 0x2000
	s_nop 0
	global_load_lds_dwordx4 v134, s[50:51]
	s_mov_b32 m0, s37
	s_nop 0
	global_load_lds_dwordx4 v128, s[34:35]
	s_mov_b32 m0, s38
	s_nop 0
	global_load_lds_dwordx4 v132, s[34:35]
	s_waitcnt vmcnt(8)
	s_waitcnt lgkmcnt(0)
	s_barrier
	s_setprio 1
	s_waitcnt lgkmcnt(0)
	v_mfma_f32_16x16x32_bf16 v[60:63], v[150:153], v[188:191], v[60:63]
	v_mfma_f32_16x16x32_bf16 v[56:59], v[164:167], v[188:191], v[56:59]
	v_mfma_f32_16x16x32_bf16 v[44:47], v[150:153], v[196:199], v[44:47]
	v_mfma_f32_16x16x32_bf16 v[40:43], v[164:167], v[196:199], v[40:43]
	v_mfma_f32_16x16x32_bf16 v[28:31], v[150:153], v[204:207], v[28:31]
	v_mfma_f32_16x16x32_bf16 v[24:27], v[164:167], v[204:207], v[24:27]
	v_mfma_f32_16x16x32_bf16 v[12:15], v[150:153], v[212:215], v[12:15]
	v_mfma_f32_16x16x32_bf16 v[8:11], v[164:167], v[212:215], v[8:11]
	v_mfma_f32_16x16x32_bf16 v[60:63], v[160:163], v[192:195], v[60:63]
	v_mfma_f32_16x16x32_bf16 v[56:59], v[168:171], v[192:195], v[56:59]
	v_mfma_f32_16x16x32_bf16 v[44:47], v[160:163], v[200:203], v[44:47]
	v_mfma_f32_16x16x32_bf16 v[40:43], v[168:171], v[200:203], v[40:43]
	v_mfma_f32_16x16x32_bf16 v[28:31], v[160:163], v[208:211], v[28:31]
	v_mfma_f32_16x16x32_bf16 v[24:27], v[168:171], v[208:211], v[24:27]
	v_mfma_f32_16x16x32_bf16 v[12:15], v[160:163], v[216:219], v[12:15]
	v_mfma_f32_16x16x32_bf16 v[8:11], v[168:171], v[216:219], v[8:11]
	s_setprio 0
	s_setprio 1
	v_mfma_f32_16x16x32_bf16 v[52:55], v[172:175], v[188:191], v[52:55]
	v_mfma_f32_16x16x32_bf16 v[48:51], v[180:183], v[188:191], v[48:51]
	v_mfma_f32_16x16x32_bf16 v[36:39], v[172:175], v[196:199], v[36:39]
	v_mfma_f32_16x16x32_bf16 v[32:35], v[180:183], v[196:199], v[32:35]
	v_mfma_f32_16x16x32_bf16 v[20:23], v[172:175], v[204:207], v[20:23]
	v_mfma_f32_16x16x32_bf16 v[16:19], v[180:183], v[204:207], v[16:19]
	v_mfma_f32_16x16x32_bf16 v[4:7], v[172:175], v[212:215], v[4:7]
	v_mfma_f32_16x16x32_bf16 v[0:3], v[180:183], v[212:215], v[0:3]
	v_mfma_f32_16x16x32_bf16 v[52:55], v[176:179], v[192:195], v[52:55]
	v_mfma_f32_16x16x32_bf16 v[48:51], v[184:187], v[192:195], v[48:51]
	v_mfma_f32_16x16x32_bf16 v[36:39], v[176:179], v[200:203], v[36:39]
	v_mfma_f32_16x16x32_bf16 v[32:35], v[184:187], v[200:203], v[32:35]
	v_mfma_f32_16x16x32_bf16 v[20:23], v[176:179], v[208:211], v[20:23]
	v_mfma_f32_16x16x32_bf16 v[16:19], v[184:187], v[208:211], v[16:19]
	v_mfma_f32_16x16x32_bf16 v[4:7], v[176:179], v[216:219], v[4:7]
	v_mfma_f32_16x16x32_bf16 v[0:3], v[184:187], v[216:219], v[0:3]
	s_setprio 0
	s_barrier
	s_add_i32 s47, 0, 0x18000
	v_add_u32_e32 v136, s47, v155
	s_add_i32 s49, 0, 0x1c000
	ds_read_b128 v[150:153], v136
	ds_read_b128 v[160:163], v136 offset:1024
	ds_read_b128 v[164:167], v136 offset:2048
	ds_read_b128 v[168:171], v136 offset:3072
	v_add_u32_e32 v136, s49, v155
	ds_read_b128 v[172:175], v136
	ds_read_b128 v[176:179], v136 offset:1024
	ds_read_b128 v[180:183], v136 offset:2048
	ds_read_b128 v[184:187], v136 offset:3072
	s_add_u32 s34, s34, 0x40000
	s_addc_u32 s35, s35, 0
	s_mov_b32 m0, s39
	ds_read_b128 v[188:191], v159 offset:32768
	ds_read_b128 v[192:195], v159 offset:33792
	ds_read_b128 v[196:199], v159 offset:34816
	ds_read_b128 v[200:203], v159 offset:35840
	ds_read_b128 v[204:207], v159 offset:36864
	ds_read_b128 v[208:211], v159 offset:37888
	ds_read_b128 v[212:215], v159 offset:38912
	ds_read_b128 v[216:219], v159 offset:39936
	global_load_lds_dwordx4 v128, s[34:35]
	s_mov_b32 m0, s40
	s_nop 0
	global_load_lds_dwordx4 v132, s[34:35]
	s_waitcnt vmcnt(8)
	s_waitcnt lgkmcnt(0)
	s_barrier
	s_setprio 1
	s_waitcnt lgkmcnt(0)
	v_mfma_f32_16x16x32_bf16 v[124:127], v[150:153], v[188:191], v[124:127]
	v_mfma_f32_16x16x32_bf16 v[120:123], v[164:167], v[188:191], v[120:123]
	v_mfma_f32_16x16x32_bf16 v[108:111], v[150:153], v[196:199], v[108:111]
	v_mfma_f32_16x16x32_bf16 v[104:107], v[164:167], v[196:199], v[104:107]
	v_mfma_f32_16x16x32_bf16 v[92:95], v[150:153], v[204:207], v[92:95]
	v_mfma_f32_16x16x32_bf16 v[88:91], v[164:167], v[204:207], v[88:91]
	v_mfma_f32_16x16x32_bf16 v[76:79], v[150:153], v[212:215], v[76:79]
	v_mfma_f32_16x16x32_bf16 v[72:75], v[164:167], v[212:215], v[72:75]
	v_mfma_f32_16x16x32_bf16 v[124:127], v[160:163], v[192:195], v[124:127]
	v_mfma_f32_16x16x32_bf16 v[120:123], v[168:171], v[192:195], v[120:123]
	v_mfma_f32_16x16x32_bf16 v[108:111], v[160:163], v[200:203], v[108:111]
	v_mfma_f32_16x16x32_bf16 v[104:107], v[168:171], v[200:203], v[104:107]
	v_mfma_f32_16x16x32_bf16 v[92:95], v[160:163], v[208:211], v[92:95]
	v_mfma_f32_16x16x32_bf16 v[88:91], v[168:171], v[208:211], v[88:91]
	v_mfma_f32_16x16x32_bf16 v[76:79], v[160:163], v[216:219], v[76:79]
	v_mfma_f32_16x16x32_bf16 v[72:75], v[168:171], v[216:219], v[72:75]
	s_setprio 0
	s_setprio 1
	v_mfma_f32_16x16x32_bf16 v[116:119], v[172:175], v[188:191], v[116:119]
	v_mfma_f32_16x16x32_bf16 v[112:115], v[180:183], v[188:191], v[112:115]
	v_mfma_f32_16x16x32_bf16 v[100:103], v[172:175], v[196:199], v[100:103]
	v_mfma_f32_16x16x32_bf16 v[96:99], v[180:183], v[196:199], v[96:99]
	v_mfma_f32_16x16x32_bf16 v[84:87], v[172:175], v[204:207], v[84:87]
	v_mfma_f32_16x16x32_bf16 v[80:83], v[180:183], v[204:207], v[80:83]
	v_mfma_f32_16x16x32_bf16 v[68:71], v[172:175], v[212:215], v[68:71]
	v_mfma_f32_16x16x32_bf16 v[64:67], v[180:183], v[212:215], v[64:67]
	v_mfma_f32_16x16x32_bf16 v[116:119], v[176:179], v[192:195], v[116:119]
	v_mfma_f32_16x16x32_bf16 v[112:115], v[184:187], v[192:195], v[112:115]
	v_mfma_f32_16x16x32_bf16 v[100:103], v[176:179], v[200:203], v[100:103]
	v_mfma_f32_16x16x32_bf16 v[96:99], v[184:187], v[200:203], v[96:99]
	v_mfma_f32_16x16x32_bf16 v[84:87], v[176:179], v[208:211], v[84:87]
	v_mfma_f32_16x16x32_bf16 v[80:83], v[184:187], v[208:211], v[80:83]
	v_mfma_f32_16x16x32_bf16 v[68:71], v[176:179], v[216:219], v[68:71]
	v_mfma_f32_16x16x32_bf16 v[64:67], v[184:187], v[216:219], v[64:67]
	s_setprio 0
	s_barrier
	s_add_i32 s34, s47, s36
	s_mov_b32 m0, s34
	ds_read_b128 v[188:191], v159 offset:49152
	ds_read_b128 v[192:195], v159 offset:50176
	ds_read_b128 v[196:199], v159 offset:51200
	ds_read_b128 v[200:203], v159 offset:52224
	ds_read_b128 v[204:207], v159 offset:53248
	ds_read_b128 v[208:211], v159 offset:54272
	ds_read_b128 v[212:215], v159 offset:55296
	ds_read_b128 v[216:219], v159 offset:56320
	global_load_lds_dwordx4 v130, s[98:99]
	s_add_i32 m0, s34, 0x2000
	s_add_u32 s30, s30, 0x40080
	s_addc_u32 s31, s31, 0
	s_add_i32 s34, s49, s36
	global_load_lds_dwordx4 v134, s[98:99]
	s_mov_b32 m0, s34
	s_nop 0
	global_load_lds_dwordx4 v130, s[30:31]
	s_add_i32 m0, s34, 0x2000
	s_nop 0
	global_load_lds_dwordx4 v134, s[30:31]
	s_mov_b32 m0, s42
	s_nop 0
	global_load_lds_dwordx4 v128, s[100:101]
	s_mov_b32 m0, s43
	s_nop 0
	global_load_lds_dwordx4 v132, s[100:101]
	s_waitcnt vmcnt(8)
	s_waitcnt lgkmcnt(0)
	s_barrier
	s_setprio 1
	s_waitcnt lgkmcnt(0)
	v_mfma_f32_16x16x32_bf16 v[60:63], v[150:153], v[188:191], v[60:63]
	v_mfma_f32_16x16x32_bf16 v[56:59], v[164:167], v[188:191], v[56:59]
	v_mfma_f32_16x16x32_bf16 v[44:47], v[150:153], v[196:199], v[44:47]
	v_mfma_f32_16x16x32_bf16 v[40:43], v[164:167], v[196:199], v[40:43]
	v_mfma_f32_16x16x32_bf16 v[28:31], v[150:153], v[204:207], v[28:31]
	v_mfma_f32_16x16x32_bf16 v[24:27], v[164:167], v[204:207], v[24:27]
	v_mfma_f32_16x16x32_bf16 v[12:15], v[150:153], v[212:215], v[12:15]
	v_mfma_f32_16x16x32_bf16 v[8:11], v[164:167], v[212:215], v[8:11]
	v_mfma_f32_16x16x32_bf16 v[60:63], v[160:163], v[192:195], v[60:63]
	v_mfma_f32_16x16x32_bf16 v[56:59], v[168:171], v[192:195], v[56:59]
	v_mfma_f32_16x16x32_bf16 v[44:47], v[160:163], v[200:203], v[44:47]
	v_mfma_f32_16x16x32_bf16 v[40:43], v[168:171], v[200:203], v[40:43]
	v_mfma_f32_16x16x32_bf16 v[28:31], v[160:163], v[208:211], v[28:31]
	v_mfma_f32_16x16x32_bf16 v[24:27], v[168:171], v[208:211], v[24:27]
	v_mfma_f32_16x16x32_bf16 v[12:15], v[160:163], v[216:219], v[12:15]
	v_mfma_f32_16x16x32_bf16 v[8:11], v[168:171], v[216:219], v[8:11]
	s_setprio 0
	s_setprio 1
	v_mfma_f32_16x16x32_bf16 v[52:55], v[172:175], v[188:191], v[52:55]
	v_mfma_f32_16x16x32_bf16 v[48:51], v[180:183], v[188:191], v[48:51]
	v_mfma_f32_16x16x32_bf16 v[36:39], v[172:175], v[196:199], v[36:39]
	v_mfma_f32_16x16x32_bf16 v[32:35], v[180:183], v[196:199], v[32:35]
	v_mfma_f32_16x16x32_bf16 v[20:23], v[172:175], v[204:207], v[20:23]
	v_mfma_f32_16x16x32_bf16 v[16:19], v[180:183], v[204:207], v[16:19]
	v_mfma_f32_16x16x32_bf16 v[4:7], v[172:175], v[212:215], v[4:7]
	v_mfma_f32_16x16x32_bf16 v[0:3], v[180:183], v[212:215], v[0:3]
	v_mfma_f32_16x16x32_bf16 v[52:55], v[176:179], v[192:195], v[52:55]
	v_mfma_f32_16x16x32_bf16 v[48:51], v[184:187], v[192:195], v[48:51]
	v_mfma_f32_16x16x32_bf16 v[36:39], v[176:179], v[200:203], v[36:39]
	v_mfma_f32_16x16x32_bf16 v[32:35], v[184:187], v[200:203], v[32:35]
	v_mfma_f32_16x16x32_bf16 v[20:23], v[176:179], v[208:211], v[20:23]
	v_mfma_f32_16x16x32_bf16 v[16:19], v[184:187], v[208:211], v[16:19]
	v_mfma_f32_16x16x32_bf16 v[4:7], v[176:179], v[216:219], v[4:7]
	v_mfma_f32_16x16x32_bf16 v[0:3], v[184:187], v[216:219], v[0:3]
	s_setprio 0
	s_barrier
	s_add_i32 s46, s46, 2
	s_add_u32 s28, s28, 0x100
	s_addc_u32 s29, s29, 0
	s_add_u32 s25, s25, 0x100
	s_addc_u32 s27, s27, 0
	s_cmp_gt_u32 s46, 13
	s_cbranch_scc0 .LBB0_1234
	s_bitcmp1_b32 s24, 2
	s_cbranch_scc1 .Lrope_skip1
	s_cmp_eq_u64 s[6:7], 0
	s_cbranch_scc1 .Lrope_skip1
	v_lshl_add_u32 v224, s26, 8, v154
	v_lshlrev_b32_e32 v224, 5, v224
	v_and_b32_e32 v224, 0x3ffe0, v224
	v_mov_b32_e32 v225, 0
	v_lshl_add_u64 v[216:217], v[138:139], 0, v[224:225]
	v_lshl_add_u64 v[218:219], v[140:141], 0, v[224:225]
	v_add_u32_e32 v224, 0x1000, v224
	v_lshl_add_u64 v[220:221], v[138:139], 0, v[224:225]
	v_lshl_add_u64 v[222:223], v[140:141], 0, v[224:225]
	global_load_dwordx4 v[184:187], v[216:217], off
	global_load_dwordx4 v[188:191], v[218:219], off
	global_load_dwordx4 v[192:195], v[216:217], off offset:512
	global_load_dwordx4 v[196:199], v[218:219], off offset:512
	global_load_dwordx4 v[200:203], v[216:217], off offset:1024
	global_load_dwordx4 v[204:207], v[218:219], off offset:1024
	global_load_dwordx4 v[208:211], v[216:217], off offset:1536
	global_load_dwordx4 v[212:215], v[218:219], off offset:1536

.LBB0_1680:
	s_add_u32 s31, s24, s30
	s_addc_u32 s38, s25, 0
	s_add_u32 s36, s31, 0x100
	s_addc_u32 s37, s38, 0
	s_and_b64 s[34:35], s[28:29], exec
	s_cselect_b32 s35, s4, s37
	s_cselect_b32 s34, s5, s36
	s_add_u32 s30, s22, s30
	s_addc_u32 s36, s23, 0
	s_add_u32 s30, s30, 0x100
	s_addc_u32 s36, s36, 0
	s_and_b64 s[28:29], s[28:29], exec
	s_cselect_b32 s37, s13, s36
	s_cselect_b32 s36, s15, s30
	s_add_u32 s44, s31, 0x10080
	ds_read_b128 v[156:159], v152
	ds_read_b128 v[160:163], v152 offset:1024
	ds_read_b128 v[164:167], v152 offset:2048
	ds_read_b128 v[168:171], v152 offset:3072
	ds_read_b128 v[172:175], v153
	ds_read_b128 v[176:179], v153 offset:1024
	ds_read_b128 v[180:183], v153 offset:2048
	ds_read_b128 v[184:187], v153 offset:3072
	s_addc_u32 s45, s38, 0
	s_add_i32 s70, s60, s43
	s_add_i32 m0, s21, 0xc000
	s_add_i32 s52, s21, 0xe000
	s_add_i32 s67, s70, 0x2000
	s_add_u32 s38, s36, 0x10000
	s_addc_u32 s39, s37, 0
	s_add_i32 s69, s61, s43
	s_add_i32 s68, s69, 0x2000
	s_add_i32 s66, 0, 0x18000
	s_add_i32 s65, 0, 0x1c000
	s_add_u32 s30, s34, 0x10000
	s_addc_u32 s31, s35, 0
	s_add_i32 s64, s66, s43
	s_add_i32 s63, s64, 0x2000
	s_add_u32 s28, s36, 0x10080
	s_addc_u32 s29, s37, 0
	s_add_i32 s72, s65, s43
	s_add_i32 s71, s72, 0x2000
	ds_read_b128 v[188:191], v154
	ds_read_b128 v[192:195], v154 offset:1024
	ds_read_b128 v[196:199], v154 offset:2048
	ds_read_b128 v[200:203], v154 offset:3072
	ds_read_b128 v[204:207], v154 offset:4096
	ds_read_b128 v[208:211], v154 offset:5120
	ds_read_b128 v[212:215], v154 offset:6144
	ds_read_b128 v[216:219], v154 offset:7168
	global_load_lds_dwordx4 v134, s[44:45]
	s_mov_b32 m0, s52
	s_nop 0
	global_load_lds_dwordx4 v130, s[44:45]
	s_waitcnt vmcnt(8)
	s_waitcnt lgkmcnt(0)
	s_barrier
	s_setprio 1
	s_waitcnt lgkmcnt(0)
	v_mfma_f32_16x16x32_bf16 v[124:127], v[156:159], v[188:191], v[124:127]
	v_mfma_f32_16x16x32_bf16 v[120:123], v[164:167], v[188:191], v[120:123]
	v_mfma_f32_16x16x32_bf16 v[116:119], v[156:159], v[196:199], v[116:119]
	v_mfma_f32_16x16x32_bf16 v[108:111], v[164:167], v[196:199], v[108:111]
	v_mfma_f32_16x16x32_bf16 v[100:103], v[156:159], v[204:207], v[100:103]
	v_mfma_f32_16x16x32_bf16 v[92:95], v[164:167], v[204:207], v[92:95]
	v_mfma_f32_16x16x32_bf16 v[84:87], v[156:159], v[212:215], v[84:87]
	v_mfma_f32_16x16x32_bf16 v[76:79], v[164:167], v[212:215], v[76:79]
	v_mfma_f32_16x16x32_bf16 v[124:127], v[160:163], v[192:195], v[124:127]
	v_mfma_f32_16x16x32_bf16 v[120:123], v[168:171], v[192:195], v[120:123]
	v_mfma_f32_16x16x32_bf16 v[116:119], v[160:163], v[200:203], v[116:119]
	v_mfma_f32_16x16x32_bf16 v[108:111], v[168:171], v[200:203], v[108:111]
	v_mfma_f32_16x16x32_bf16 v[100:103], v[160:163], v[208:211], v[100:103]
	v_mfma_f32_16x16x32_bf16 v[92:95], v[168:171], v[208:211], v[92:95]
	v_mfma_f32_16x16x32_bf16 v[84:87], v[160:163], v[216:219], v[84:87]
	v_mfma_f32_16x16x32_bf16 v[76:79], v[168:171], v[216:219], v[76:79]
	s_setprio 0
	s_setprio 1
	v_mfma_f32_16x16x32_bf16 v[112:115], v[172:175], v[188:191], v[112:115]
	v_mfma_f32_16x16x32_bf16 v[104:107], v[180:183], v[188:191], v[104:107]
	v_mfma_f32_16x16x32_bf16 v[96:99], v[172:175], v[196:199], v[96:99]
	v_mfma_f32_16x16x32_bf16 v[88:91], v[180:183], v[196:199], v[88:91]
	v_mfma_f32_16x16x32_bf16 v[80:83], v[172:175], v[204:207], v[80:83]
	v_mfma_f32_16x16x32_bf16 v[72:75], v[180:183], v[204:207], v[72:75]
	v_mfma_f32_16x16x32_bf16 v[68:71], v[172:175], v[212:215], v[68:71]
	v_mfma_f32_16x16x32_bf16 v[64:67], v[180:183], v[212:215], v[64:67]
	v_mfma_f32_16x16x32_bf16 v[112:115], v[176:179], v[192:195], v[112:115]
	v_mfma_f32_16x16x32_bf16 v[104:107], v[184:187], v[192:195], v[104:107]
	v_mfma_f32_16x16x32_bf16 v[96:99], v[176:179], v[200:203], v[96:99]
	v_mfma_f32_16x16x32_bf16 v[88:91], v[184:187], v[200:203], v[88:91]
	v_mfma_f32_16x16x32_bf16 v[80:83], v[176:179], v[208:211], v[80:83]
	v_mfma_f32_16x16x32_bf16 v[72:75], v[184:187], v[208:211], v[72:75]
	v_mfma_f32_16x16x32_bf16 v[68:71], v[176:179], v[216:219], v[68:71]
	v_mfma_f32_16x16x32_bf16 v[64:67], v[184:187], v[216:219], v[64:67]
	s_setprio 0
	s_barrier
	s_mov_b32 m0, s70
	s_add_u32 s98, s36, s8
	s_addc_u32 s99, s37, s9
	ds_read_b128 v[188:191], v154 offset:16384
	ds_read_b128 v[192:195], v154 offset:17408
	ds_read_b128 v[196:199], v154 offset:18432
	ds_read_b128 v[200:203], v154 offset:19456
	ds_read_b128 v[204:207], v154 offset:20480
	ds_read_b128 v[208:211], v154 offset:21504
	ds_read_b128 v[212:215], v154 offset:22528
	ds_read_b128 v[216:219], v154 offset:23552
	global_load_lds_dwordx4 v132, s[36:37]
	s_mov_b32 m0, s67
	s_nop 0
	global_load_lds_dwordx4 v128, s[36:37]
	s_mov_b32 m0, s69
	s_add_u32 s100, s34, s8
	s_addc_u32 s101, s35, s9
	global_load_lds_dwordx4 v132, s[38:39]
	s_mov_b32 m0, s68
	s_nop 0
	global_load_lds_dwordx4 v128, s[38:39]
	s_mov_b32 m0, s21
	s_nop 0
	global_load_lds_dwordx4 v134, s[34:35]
	s_mov_b32 m0, s46
	s_nop 0
	global_load_lds_dwordx4 v130, s[34:35]
	s_waitcnt vmcnt(8)
	s_waitcnt lgkmcnt(0)
	s_barrier
	s_setprio 1
	s_waitcnt lgkmcnt(0)
	v_mfma_f32_16x16x32_bf16 v[60:63], v[156:159], v[188:191], v[60:63]
	v_mfma_f32_16x16x32_bf16 v[56:59], v[164:167], v[188:191], v[56:59]
	v_mfma_f32_16x16x32_bf16 v[52:55], v[156:159], v[196:199], v[52:55]
	v_mfma_f32_16x16x32_bf16 v[44:47], v[164:167], v[196:199], v[44:47]
	v_mfma_f32_16x16x32_bf16 v[36:39], v[156:159], v[204:207], v[36:39]
	v_mfma_f32_16x16x32_bf16 v[28:31], v[164:167], v[204:207], v[28:31]
	v_mfma_f32_16x16x32_bf16 v[20:23], v[156:159], v[212:215], v[20:23]
	v_mfma_f32_16x16x32_bf16 v[12:15], v[164:167], v[212:215], v[12:15]
	v_mfma_f32_16x16x32_bf16 v[60:63], v[160:163], v[192:195], v[60:63]
	v_mfma_f32_16x16x32_bf16 v[56:59], v[168:171], v[192:195], v[56:59]
	v_mfma_f32_16x16x32_bf16 v[52:55], v[160:163], v[200:203], v[52:55]
	v_mfma_f32_16x16x32_bf16 v[44:47], v[168:171], v[200:203], v[44:47]
	v_mfma_f32_16x16x32_bf16 v[36:39], v[160:163], v[208:211], v[36:39]
	v_mfma_f32_16x16x32_bf16 v[28:31], v[168:171], v[208:211], v[28:31]
	v_mfma_f32_16x16x32_bf16 v[20:23], v[160:163], v[216:219], v[20:23]
	v_mfma_f32_16x16x32_bf16 v[12:15], v[168:171], v[216:219], v[12:15]
	s_setprio 0
	s_setprio 1
	v_mfma_f32_16x16x32_bf16 v[48:51], v[172:175], v[188:191], v[48:51]
	v_mfma_f32_16x16x32_bf16 v[40:43], v[180:183], v[188:191], v[40:43]
	v_mfma_f32_16x16x32_bf16 v[32:35], v[172:175], v[196:199], v[32:35]
	v_mfma_f32_16x16x32_bf16 v[24:27], v[180:183], v[196:199], v[24:27]
	v_mfma_f32_16x16x32_bf16 v[16:19], v[172:175], v[204:207], v[16:19]
	v_mfma_f32_16x16x32_bf16 v[8:11], v[180:183], v[204:207], v[8:11]
	v_mfma_f32_16x16x32_bf16 v[4:7], v[172:175], v[212:215], v[4:7]
	v_mfma_f32_16x16x32_bf16 v[0:3], v[180:183], v[212:215], v[0:3]
	v_mfma_f32_16x16x32_bf16 v[48:51], v[176:179], v[192:195], v[48:51]
	v_mfma_f32_16x16x32_bf16 v[40:43], v[184:187], v[192:195], v[40:43]
	v_mfma_f32_16x16x32_bf16 v[32:35], v[176:179], v[200:203], v[32:35]
	v_mfma_f32_16x16x32_bf16 v[24:27], v[184:187], v[200:203], v[24:27]
	v_mfma_f32_16x16x32_bf16 v[16:19], v[176:179], v[208:211], v[16:19]
	v_mfma_f32_16x16x32_bf16 v[8:11], v[184:187], v[208:211], v[8:11]
	v_mfma_f32_16x16x32_bf16 v[4:7], v[176:179], v[216:219], v[4:7]
	v_mfma_f32_16x16x32_bf16 v[0:3], v[184:187], v[216:219], v[0:3]
	s_setprio 0
	s_barrier
	v_add_u32_e32 v155, s66, v143
	ds_read_b128 v[156:159], v155
	ds_read_b128 v[160:163], v155 offset:1024
	ds_read_b128 v[164:167], v155 offset:2048
	ds_read_b128 v[168:171], v155 offset:3072
	v_add_u32_e32 v155, s65, v143
	ds_read_b128 v[172:175], v155
	ds_read_b128 v[176:179], v155 offset:1024
	ds_read_b128 v[180:183], v155 offset:2048
	ds_read_b128 v[184:187], v155 offset:3072
	s_mov_b32 m0, s47
	ds_read_b128 v[188:191], v154 offset:32768
	ds_read_b128 v[192:195], v154 offset:33792
	ds_read_b128 v[196:199], v154 offset:34816
	ds_read_b128 v[200:203], v154 offset:35840
	ds_read_b128 v[204:207], v154 offset:36864
	ds_read_b128 v[208:211], v154 offset:37888
	ds_read_b128 v[212:215], v154 offset:38912
	ds_read_b128 v[216:219], v154 offset:39936
	global_load_lds_dwordx4 v134, s[30:31]
	s_mov_b32 m0, s48
	s_nop 0
	global_load_lds_dwordx4 v130, s[30:31]
	s_waitcnt vmcnt(8)
	s_waitcnt lgkmcnt(0)
	s_barrier
	s_setprio 1
	s_waitcnt lgkmcnt(0)
	v_mfma_f32_16x16x32_bf16 v[124:127], v[156:159], v[188:191], v[124:127]
	v_mfma_f32_16x16x32_bf16 v[120:123], v[164:167], v[188:191], v[120:123]
	v_mfma_f32_16x16x32_bf16 v[116:119], v[156:159], v[196:199], v[116:119]
	v_mfma_f32_16x16x32_bf16 v[108:111], v[164:167], v[196:199], v[108:111]
	v_mfma_f32_16x16x32_bf16 v[100:103], v[156:159], v[204:207], v[100:103]
	v_mfma_f32_16x16x32_bf16 v[92:95], v[164:167], v[204:207], v[92:95]
	v_mfma_f32_16x16x32_bf16 v[84:87], v[156:159], v[212:215], v[84:87]
	v_mfma_f32_16x16x32_bf16 v[76:79], v[164:167], v[212:215], v[76:79]
	v_mfma_f32_16x16x32_bf16 v[124:127], v[160:163], v[192:195], v[124:127]
	v_mfma_f32_16x16x32_bf16 v[120:123], v[168:171], v[192:195], v[120:123]
	v_mfma_f32_16x16x32_bf16 v[116:119], v[160:163], v[200:203], v[116:119]
	v_mfma_f32_16x16x32_bf16 v[108:111], v[168:171], v[200:203], v[108:111]
	v_mfma_f32_16x16x32_bf16 v[100:103], v[160:163], v[208:211], v[100:103]
	v_mfma_f32_16x16x32_bf16 v[92:95], v[168:171], v[208:211], v[92:95]
	v_mfma_f32_16x16x32_bf16 v[84:87], v[160:163], v[216:219], v[84:87]
	v_mfma_f32_16x16x32_bf16 v[76:79], v[168:171], v[216:219], v[76:79]
	s_setprio 0
	s_setprio 1
	v_mfma_f32_16x16x32_bf16 v[112:115], v[172:175], v[188:191], v[112:115]
	v_mfma_f32_16x16x32_bf16 v[104:107], v[180:183], v[188:191], v[104:107]
	v_mfma_f32_16x16x32_bf16 v[96:99], v[172:175], v[196:199], v[96:99]
	v_mfma_f32_16x16x32_bf16 v[88:91], v[180:183], v[196:199], v[88:91]
	v_mfma_f32_16x16x32_bf16 v[80:83], v[172:175], v[204:207], v[80:83]
	v_mfma_f32_16x16x32_bf16 v[72:75], v[180:183], v[204:207], v[72:75]
	v_mfma_f32_16x16x32_bf16 v[68:71], v[172:175], v[212:215], v[68:71]
	v_mfma_f32_16x16x32_bf16 v[64:67], v[180:183], v[212:215], v[64:67]
	v_mfma_f32_16x16x32_bf16 v[112:115], v[176:179], v[192:195], v[112:115]
	v_mfma_f32_16x16x32_bf16 v[104:107], v[184:187], v[192:195], v[104:107]
	v_mfma_f32_16x16x32_bf16 v[96:99], v[176:179], v[200:203], v[96:99]
	v_mfma_f32_16x16x32_bf16 v[88:91], v[184:187], v[200:203], v[88:91]
	v_mfma_f32_16x16x32_bf16 v[80:83], v[176:179], v[208:211], v[80:83]
	v_mfma_f32_16x16x32_bf16 v[72:75], v[184:187], v[208:211], v[72:75]
	v_mfma_f32_16x16x32_bf16 v[68:71], v[176:179], v[216:219], v[68:71]
	v_mfma_f32_16x16x32_bf16 v[64:67], v[184:187], v[216:219], v[64:67]
	s_setprio 0
	s_barrier
	s_mov_b32 m0, s64
	ds_read_b128 v[188:191], v154 offset:49152
	ds_read_b128 v[192:195], v154 offset:50176
	ds_read_b128 v[196:199], v154 offset:51200
	ds_read_b128 v[200:203], v154 offset:52224
	ds_read_b128 v[204:207], v154 offset:53248
	ds_read_b128 v[208:211], v154 offset:54272
	ds_read_b128 v[212:215], v154 offset:55296
	ds_read_b128 v[216:219], v154 offset:56320
	global_load_lds_dwordx4 v132, s[98:99]
	s_mov_b32 m0, s63
	s_nop 0
	global_load_lds_dwordx4 v128, s[98:99]
	s_mov_b32 m0, s72
	s_nop 0
	global_load_lds_dwordx4 v132, s[28:29]
	s_mov_b32 m0, s71
	s_nop 0
	global_load_lds_dwordx4 v128, s[28:29]
	s_mov_b32 m0, s50
	s_nop 0
	global_load_lds_dwordx4 v134, s[100:101]
	s_mov_b32 m0, s51
	s_nop 0
	global_load_lds_dwordx4 v130, s[100:101]
	s_waitcnt vmcnt(8)
	s_waitcnt lgkmcnt(0)
	s_barrier
	s_setprio 1
	s_waitcnt lgkmcnt(0)
	v_mfma_f32_16x16x32_bf16 v[60:63], v[156:159], v[188:191], v[60:63]
	v_mfma_f32_16x16x32_bf16 v[56:59], v[164:167], v[188:191], v[56:59]
	v_mfma_f32_16x16x32_bf16 v[52:55], v[156:159], v[196:199], v[52:55]
	v_mfma_f32_16x16x32_bf16 v[44:47], v[164:167], v[196:199], v[44:47]
	v_mfma_f32_16x16x32_bf16 v[36:39], v[156:159], v[204:207], v[36:39]
	v_mfma_f32_16x16x32_bf16 v[28:31], v[164:167], v[204:207], v[28:31]
	v_mfma_f32_16x16x32_bf16 v[20:23], v[156:159], v[212:215], v[20:23]
	v_mfma_f32_16x16x32_bf16 v[12:15], v[164:167], v[212:215], v[12:15]
	v_mfma_f32_16x16x32_bf16 v[60:63], v[160:163], v[192:195], v[60:63]
	v_mfma_f32_16x16x32_bf16 v[56:59], v[168:171], v[192:195], v[56:59]
	v_mfma_f32_16x16x32_bf16 v[52:55], v[160:163], v[200:203], v[52:55]
	v_mfma_f32_16x16x32_bf16 v[44:47], v[168:171], v[200:203], v[44:47]
	v_mfma_f32_16x16x32_bf16 v[36:39], v[160:163], v[208:211], v[36:39]
	v_mfma_f32_16x16x32_bf16 v[28:31], v[168:171], v[208:211], v[28:31]
	v_mfma_f32_16x16x32_bf16 v[20:23], v[160:163], v[216:219], v[20:23]
	v_mfma_f32_16x16x32_bf16 v[12:15], v[168:171], v[216:219], v[12:15]
	s_setprio 0
	s_setprio 1
	v_mfma_f32_16x16x32_bf16 v[48:51], v[172:175], v[188:191], v[48:51]
	v_mfma_f32_16x16x32_bf16 v[40:43], v[180:183], v[188:191], v[40:43]
	v_mfma_f32_16x16x32_bf16 v[32:35], v[172:175], v[196:199], v[32:35]
	v_mfma_f32_16x16x32_bf16 v[24:27], v[180:183], v[196:199], v[24:27]
	v_mfma_f32_16x16x32_bf16 v[16:19], v[172:175], v[204:207], v[16:19]
	v_mfma_f32_16x16x32_bf16 v[8:11], v[180:183], v[204:207], v[8:11]
	v_mfma_f32_16x16x32_bf16 v[4:7], v[172:175], v[212:215], v[4:7]
	v_mfma_f32_16x16x32_bf16 v[0:3], v[180:183], v[212:215], v[0:3]
	v_mfma_f32_16x16x32_bf16 v[48:51], v[176:179], v[192:195], v[48:51]
	v_mfma_f32_16x16x32_bf16 v[40:43], v[184:187], v[192:195], v[40:43]
	v_mfma_f32_16x16x32_bf16 v[32:35], v[176:179], v[200:203], v[32:35]
	v_mfma_f32_16x16x32_bf16 v[24:27], v[184:187], v[200:203], v[24:27]
	v_mfma_f32_16x16x32_bf16 v[16:19], v[176:179], v[208:211], v[16:19]
	v_mfma_f32_16x16x32_bf16 v[8:11], v[184:187], v[208:211], v[8:11]
	v_mfma_f32_16x16x32_bf16 v[4:7], v[176:179], v[216:219], v[4:7]
	v_mfma_f32_16x16x32_bf16 v[0:3], v[184:187], v[216:219], v[0:3]
	s_setprio 0
	s_barrier
	s_movk_i32 s30, 0x100
	s_andn2_b64 vcc, exec, s[26:27]
	s_mov_b64 s[28:29], -1
	s_mov_b64 s[26:27], 0
	s_cbranch_vccz .LBB0_1680
	s_and_b64 vcc, exec, s[10:11]
	s_cbranch_vccz .LBB0_1683
	s_barrier

.LBB0_1700:
	ds_read_b128 v[144:147], v151
	ds_read_b128 v[154:157], v151 offset:1024
	ds_read_b128 v[158:161], v151 offset:2048
	ds_read_b128 v[162:165], v151 offset:3072
	ds_read_b128 v[166:169], v152
	ds_read_b128 v[170:173], v152 offset:1024
	ds_read_b128 v[174:177], v152 offset:2048
	ds_read_b128 v[178:181], v152 offset:3072
	s_add_u32 s24, s22, 0xfffc0080
	s_addc_u32 s25, s23, -1
	s_cmp_eq_u32 s44, 12
	s_cselect_b32 s27, s15, s25
	s_cselect_b32 s26, s40, s24
	s_cselect_b32 s25, s13, s43
	s_cselect_b32 s24, s41, s42
	s_add_i32 m0, s21, 0xc000
	ds_read_b128 v[182:185], v153
	ds_read_b128 v[186:189], v153 offset:1024
	ds_read_b128 v[190:193], v153 offset:2048
	ds_read_b128 v[194:197], v153 offset:3072
	ds_read_b128 v[198:201], v153 offset:4096
	ds_read_b128 v[202:205], v153 offset:5120
	ds_read_b128 v[206:209], v153 offset:6144
	ds_read_b128 v[210:213], v153 offset:7168
	global_load_lds_dwordx4 v136, s[22:23]
	s_add_i32 m0, s21, 0xe000
	s_nop 0
	global_load_lds_dwordx4 v138, s[22:23]
	s_waitcnt vmcnt(8)
	s_waitcnt lgkmcnt(0)
	s_barrier
	s_setprio 1
	s_waitcnt lgkmcnt(0)
	v_mfma_f32_16x16x32_bf16 v[124:127], v[144:147], v[182:185], v[124:127]
	v_mfma_f32_16x16x32_bf16 v[120:123], v[158:161], v[182:185], v[120:123]
	v_mfma_f32_16x16x32_bf16 v[108:111], v[144:147], v[190:193], v[108:111]
	v_mfma_f32_16x16x32_bf16 v[104:107], v[158:161], v[190:193], v[104:107]
	v_mfma_f32_16x16x32_bf16 v[92:95], v[144:147], v[198:201], v[92:95]
	v_mfma_f32_16x16x32_bf16 v[88:91], v[158:161], v[198:201], v[88:91]
	v_mfma_f32_16x16x32_bf16 v[76:79], v[144:147], v[206:209], v[76:79]
	v_mfma_f32_16x16x32_bf16 v[72:75], v[158:161], v[206:209], v[72:75]
	v_mfma_f32_16x16x32_bf16 v[124:127], v[154:157], v[186:189], v[124:127]
	v_mfma_f32_16x16x32_bf16 v[120:123], v[162:165], v[186:189], v[120:123]
	v_mfma_f32_16x16x32_bf16 v[108:111], v[154:157], v[194:197], v[108:111]
	v_mfma_f32_16x16x32_bf16 v[104:107], v[162:165], v[194:197], v[104:107]
	v_mfma_f32_16x16x32_bf16 v[92:95], v[154:157], v[202:205], v[92:95]
	v_mfma_f32_16x16x32_bf16 v[88:91], v[162:165], v[202:205], v[88:91]
	v_mfma_f32_16x16x32_bf16 v[76:79], v[154:157], v[210:213], v[76:79]
	v_mfma_f32_16x16x32_bf16 v[72:75], v[162:165], v[210:213], v[72:75]
	s_setprio 0
	s_setprio 1
	v_mfma_f32_16x16x32_bf16 v[116:119], v[166:169], v[182:185], v[116:119]
	v_mfma_f32_16x16x32_bf16 v[112:115], v[174:177], v[182:185], v[112:115]
	v_mfma_f32_16x16x32_bf16 v[100:103], v[166:169], v[190:193], v[100:103]
	v_mfma_f32_16x16x32_bf16 v[96:99], v[174:177], v[190:193], v[96:99]
	v_mfma_f32_16x16x32_bf16 v[84:87], v[166:169], v[198:201], v[84:87]
	v_mfma_f32_16x16x32_bf16 v[80:83], v[174:177], v[198:201], v[80:83]
	v_mfma_f32_16x16x32_bf16 v[68:71], v[166:169], v[206:209], v[68:71]
	v_mfma_f32_16x16x32_bf16 v[64:67], v[174:177], v[206:209], v[64:67]
	v_mfma_f32_16x16x32_bf16 v[116:119], v[170:173], v[186:189], v[116:119]
	v_mfma_f32_16x16x32_bf16 v[112:115], v[178:181], v[186:189], v[112:115]
	v_mfma_f32_16x16x32_bf16 v[100:103], v[170:173], v[194:197], v[100:103]
	v_mfma_f32_16x16x32_bf16 v[96:99], v[178:181], v[194:197], v[96:99]
	v_mfma_f32_16x16x32_bf16 v[84:87], v[170:173], v[202:205], v[84:87]
	v_mfma_f32_16x16x32_bf16 v[80:83], v[178:181], v[202:205], v[80:83]
	v_mfma_f32_16x16x32_bf16 v[68:71], v[170:173], v[210:213], v[68:71]
	v_mfma_f32_16x16x32_bf16 v[64:67], v[178:181], v[210:213], v[64:67]
	s_setprio 0
	s_barrier
	s_add_i32 s45, s37, s29
	s_add_u32 s98, s24, s6
	s_addc_u32 s99, s25, s7
	s_mov_b32 m0, s45
	ds_read_b128 v[182:185], v153 offset:16384
	ds_read_b128 v[186:189], v153 offset:17408
	ds_read_b128 v[190:193], v153 offset:18432
	ds_read_b128 v[194:197], v153 offset:19456
	ds_read_b128 v[198:201], v153 offset:20480
	ds_read_b128 v[202:205], v153 offset:21504
	ds_read_b128 v[206:209], v153 offset:22528
	ds_read_b128 v[210:213], v153 offset:23552
	global_load_lds_dwordx4 v132, s[24:25]
	s_add_i32 m0, s45, 0x2000
	s_add_u32 s46, s24, 0x40000
	s_addc_u32 s47, s25, 0
	s_add_i32 s45, s38, s29
	global_load_lds_dwordx4 v128, s[24:25]
	s_mov_b32 m0, s45
	s_add_u32 s100, s26, s6
	s_addc_u32 s101, s27, s7
	global_load_lds_dwordx4 v132, s[46:47]
	s_add_i32 m0, s45, 0x2000
	s_nop 0
	global_load_lds_dwordx4 v128, s[46:47]
	s_mov_b32 m0, s21
	s_nop 0
	global_load_lds_dwordx4 v134, s[26:27]
	s_mov_b32 m0, s30
	s_nop 0
	global_load_lds_dwordx4 v130, s[26:27]
	s_waitcnt vmcnt(8)
	s_waitcnt lgkmcnt(0)
	s_barrier
	s_setprio 1
	s_waitcnt lgkmcnt(0)
	v_mfma_f32_16x16x32_bf16 v[60:63], v[144:147], v[182:185], v[60:63]
	v_mfma_f32_16x16x32_bf16 v[56:59], v[158:161], v[182:185], v[56:59]
	v_mfma_f32_16x16x32_bf16 v[44:47], v[144:147], v[190:193], v[44:47]
	v_mfma_f32_16x16x32_bf16 v[40:43], v[158:161], v[190:193], v[40:43]
	v_mfma_f32_16x16x32_bf16 v[28:31], v[144:147], v[198:201], v[28:31]
	v_mfma_f32_16x16x32_bf16 v[24:27], v[158:161], v[198:201], v[24:27]
	v_mfma_f32_16x16x32_bf16 v[12:15], v[144:147], v[206:209], v[12:15]
	v_mfma_f32_16x16x32_bf16 v[8:11], v[158:161], v[206:209], v[8:11]
	v_mfma_f32_16x16x32_bf16 v[60:63], v[154:157], v[186:189], v[60:63]
	v_mfma_f32_16x16x32_bf16 v[56:59], v[162:165], v[186:189], v[56:59]
	v_mfma_f32_16x16x32_bf16 v[44:47], v[154:157], v[194:197], v[44:47]
	v_mfma_f32_16x16x32_bf16 v[40:43], v[162:165], v[194:197], v[40:43]
	v_mfma_f32_16x16x32_bf16 v[28:31], v[154:157], v[202:205], v[28:31]
	v_mfma_f32_16x16x32_bf16 v[24:27], v[162:165], v[202:205], v[24:27]
	v_mfma_f32_16x16x32_bf16 v[12:15], v[154:157], v[210:213], v[12:15]
	v_mfma_f32_16x16x32_bf16 v[8:11], v[162:165], v[210:213], v[8:11]
	s_setprio 0
	s_setprio 1
	v_mfma_f32_16x16x32_bf16 v[52:55], v[166:169], v[182:185], v[52:55]
	v_mfma_f32_16x16x32_bf16 v[48:51], v[174:177], v[182:185], v[48:51]
	v_mfma_f32_16x16x32_bf16 v[36:39], v[166:169], v[190:193], v[36:39]
	v_mfma_f32_16x16x32_bf16 v[32:35], v[174:177], v[190:193], v[32:35]
	v_mfma_f32_16x16x32_bf16 v[20:23], v[166:169], v[198:201], v[20:23]
	v_mfma_f32_16x16x32_bf16 v[16:19], v[174:177], v[198:201], v[16:19]
	v_mfma_f32_16x16x32_bf16 v[4:7], v[166:169], v[206:209], v[4:7]
	v_mfma_f32_16x16x32_bf16 v[0:3], v[174:177], v[206:209], v[0:3]
	v_mfma_f32_16x16x32_bf16 v[52:55], v[170:173], v[186:189], v[52:55]
	v_mfma_f32_16x16x32_bf16 v[48:51], v[178:181], v[186:189], v[48:51]
	v_mfma_f32_16x16x32_bf16 v[36:39], v[170:173], v[194:197], v[36:39]
	v_mfma_f32_16x16x32_bf16 v[32:35], v[178:181], v[194:197], v[32:35]
	v_mfma_f32_16x16x32_bf16 v[20:23], v[170:173], v[202:205], v[20:23]
	v_mfma_f32_16x16x32_bf16 v[16:19], v[178:181], v[202:205], v[16:19]
	v_mfma_f32_16x16x32_bf16 v[4:7], v[170:173], v[210:213], v[4:7]
	v_mfma_f32_16x16x32_bf16 v[0:3], v[178:181], v[210:213], v[0:3]
	s_setprio 0
	s_barrier
	s_add_i32 s45, 0, 0x18000
	s_add_i32 s46, 0, 0x1c000
	v_add_u32_e32 v162, s45, v149
	v_add_u32_e32 v178, s46, v149
	ds_read_b128 v[144:147], v162
	ds_read_b128 v[154:157], v162 offset:1024
	ds_read_b128 v[158:161], v162 offset:2048
	ds_read_b128 v[162:165], v162 offset:3072
	ds_read_b128 v[166:169], v178
	ds_read_b128 v[170:173], v178 offset:1024
	ds_read_b128 v[174:177], v178 offset:2048
	ds_read_b128 v[178:181], v178 offset:3072
	s_add_u32 s26, s26, 0x40000
	s_addc_u32 s27, s27, 0
	s_mov_b32 m0, s31
	ds_read_b128 v[182:185], v153 offset:32768
	ds_read_b128 v[186:189], v153 offset:33792
	ds_read_b128 v[190:193], v153 offset:34816
	ds_read_b128 v[194:197], v153 offset:35840
	ds_read_b128 v[198:201], v153 offset:36864
	ds_read_b128 v[202:205], v153 offset:37888
	ds_read_b128 v[206:209], v153 offset:38912
	ds_read_b128 v[210:213], v153 offset:39936
	global_load_lds_dwordx4 v134, s[26:27]
	s_mov_b32 m0, s33
	s_nop 0
	global_load_lds_dwordx4 v130, s[26:27]
	s_waitcnt vmcnt(8)
	s_waitcnt lgkmcnt(0)
	s_barrier
	s_setprio 1
	s_waitcnt lgkmcnt(0)
	v_mfma_f32_16x16x32_bf16 v[124:127], v[144:147], v[182:185], v[124:127]
	v_mfma_f32_16x16x32_bf16 v[120:123], v[158:161], v[182:185], v[120:123]
	v_mfma_f32_16x16x32_bf16 v[108:111], v[144:147], v[190:193], v[108:111]
	v_mfma_f32_16x16x32_bf16 v[104:107], v[158:161], v[190:193], v[104:107]
	v_mfma_f32_16x16x32_bf16 v[92:95], v[144:147], v[198:201], v[92:95]
	v_mfma_f32_16x16x32_bf16 v[88:91], v[158:161], v[198:201], v[88:91]
	v_mfma_f32_16x16x32_bf16 v[76:79], v[144:147], v[206:209], v[76:79]
	v_mfma_f32_16x16x32_bf16 v[72:75], v[158:161], v[206:209], v[72:75]
	v_mfma_f32_16x16x32_bf16 v[124:127], v[154:157], v[186:189], v[124:127]
	v_mfma_f32_16x16x32_bf16 v[120:123], v[162:165], v[186:189], v[120:123]
	v_mfma_f32_16x16x32_bf16 v[108:111], v[154:157], v[194:197], v[108:111]
	v_mfma_f32_16x16x32_bf16 v[104:107], v[162:165], v[194:197], v[104:107]
	v_mfma_f32_16x16x32_bf16 v[92:95], v[154:157], v[202:205], v[92:95]
	v_mfma_f32_16x16x32_bf16 v[88:91], v[162:165], v[202:205], v[88:91]
	v_mfma_f32_16x16x32_bf16 v[76:79], v[154:157], v[210:213], v[76:79]
	v_mfma_f32_16x16x32_bf16 v[72:75], v[162:165], v[210:213], v[72:75]
	s_setprio 0
	s_setprio 1
	v_mfma_f32_16x16x32_bf16 v[116:119], v[166:169], v[182:185], v[116:119]
	v_mfma_f32_16x16x32_bf16 v[112:115], v[174:177], v[182:185], v[112:115]
	v_mfma_f32_16x16x32_bf16 v[100:103], v[166:169], v[190:193], v[100:103]
	v_mfma_f32_16x16x32_bf16 v[96:99], v[174:177], v[190:193], v[96:99]
	v_mfma_f32_16x16x32_bf16 v[84:87], v[166:169], v[198:201], v[84:87]
	v_mfma_f32_16x16x32_bf16 v[80:83], v[174:177], v[198:201], v[80:83]
	v_mfma_f32_16x16x32_bf16 v[68:71], v[166:169], v[206:209], v[68:71]
	v_mfma_f32_16x16x32_bf16 v[64:67], v[174:177], v[206:209], v[64:67]
	v_mfma_f32_16x16x32_bf16 v[116:119], v[170:173], v[186:189], v[116:119]
	v_mfma_f32_16x16x32_bf16 v[112:115], v[178:181], v[186:189], v[112:115]
	v_mfma_f32_16x16x32_bf16 v[100:103], v[170:173], v[194:197], v[100:103]
	v_mfma_f32_16x16x32_bf16 v[96:99], v[178:181], v[194:197], v[96:99]
	v_mfma_f32_16x16x32_bf16 v[84:87], v[170:173], v[202:205], v[84:87]
	v_mfma_f32_16x16x32_bf16 v[80:83], v[178:181], v[202:205], v[80:83]
	v_mfma_f32_16x16x32_bf16 v[68:71], v[170:173], v[210:213], v[68:71]
	v_mfma_f32_16x16x32_bf16 v[64:67], v[178:181], v[210:213], v[64:67]
	s_setprio 0
	s_barrier
	s_add_i32 s26, s45, s29
	s_mov_b32 m0, s26
	ds_read_b128 v[182:185], v153 offset:49152
	ds_read_b128 v[186:189], v153 offset:50176
	ds_read_b128 v[190:193], v153 offset:51200
	ds_read_b128 v[194:197], v153 offset:52224
	ds_read_b128 v[198:201], v153 offset:53248
	ds_read_b128 v[202:205], v153 offset:54272
	ds_read_b128 v[206:209], v153 offset:55296
	ds_read_b128 v[210:213], v153 offset:56320
	global_load_lds_dwordx4 v132, s[98:99]
	s_add_i32 m0, s26, 0x2000
	s_add_u32 s24, s24, 0x40080
	s_addc_u32 s25, s25, 0
	s_add_i32 s26, s46, s29
	global_load_lds_dwordx4 v128, s[98:99]
	s_mov_b32 m0, s26
	s_nop 0
	global_load_lds_dwordx4 v132, s[24:25]
	s_add_i32 m0, s26, 0x2000
	s_nop 0
	global_load_lds_dwordx4 v128, s[24:25]
	s_mov_b32 m0, s35
	s_nop 0
	global_load_lds_dwordx4 v134, s[100:101]
	s_mov_b32 m0, s36
	s_nop 0
	global_load_lds_dwordx4 v130, s[100:101]
	s_waitcnt vmcnt(8)
	s_waitcnt lgkmcnt(0)
	s_barrier
	s_setprio 1
	s_waitcnt lgkmcnt(0)
	v_mfma_f32_16x16x32_bf16 v[60:63], v[144:147], v[182:185], v[60:63]
	v_mfma_f32_16x16x32_bf16 v[56:59], v[158:161], v[182:185], v[56:59]
	v_mfma_f32_16x16x32_bf16 v[44:47], v[144:147], v[190:193], v[44:47]
	v_mfma_f32_16x16x32_bf16 v[40:43], v[158:161], v[190:193], v[40:43]
	v_mfma_f32_16x16x32_bf16 v[28:31], v[144:147], v[198:201], v[28:31]
	v_mfma_f32_16x16x32_bf16 v[24:27], v[158:161], v[198:201], v[24:27]
	v_mfma_f32_16x16x32_bf16 v[12:15], v[144:147], v[206:209], v[12:15]
	v_mfma_f32_16x16x32_bf16 v[8:11], v[158:161], v[206:209], v[8:11]
	v_mfma_f32_16x16x32_bf16 v[60:63], v[154:157], v[186:189], v[60:63]
	v_mfma_f32_16x16x32_bf16 v[56:59], v[162:165], v[186:189], v[56:59]
	v_mfma_f32_16x16x32_bf16 v[44:47], v[154:157], v[194:197], v[44:47]
	v_mfma_f32_16x16x32_bf16 v[40:43], v[162:165], v[194:197], v[40:43]
	v_mfma_f32_16x16x32_bf16 v[28:31], v[154:157], v[202:205], v[28:31]
	v_mfma_f32_16x16x32_bf16 v[24:27], v[162:165], v[202:205], v[24:27]
	v_mfma_f32_16x16x32_bf16 v[12:15], v[154:157], v[210:213], v[12:15]
	v_mfma_f32_16x16x32_bf16 v[8:11], v[162:165], v[210:213], v[8:11]
	s_setprio 0
	s_setprio 1
	v_mfma_f32_16x16x32_bf16 v[52:55], v[166:169], v[182:185], v[52:55]
	v_mfma_f32_16x16x32_bf16 v[48:51], v[174:177], v[182:185], v[48:51]
	v_mfma_f32_16x16x32_bf16 v[36:39], v[166:169], v[190:193], v[36:39]
	v_mfma_f32_16x16x32_bf16 v[32:35], v[174:177], v[190:193], v[32:35]
	v_mfma_f32_16x16x32_bf16 v[20:23], v[166:169], v[198:201], v[20:23]
	v_mfma_f32_16x16x32_bf16 v[16:19], v[174:177], v[198:201], v[16:19]
	v_mfma_f32_16x16x32_bf16 v[4:7], v[166:169], v[206:209], v[4:7]
	v_mfma_f32_16x16x32_bf16 v[0:3], v[174:177], v[206:209], v[0:3]
	v_mfma_f32_16x16x32_bf16 v[52:55], v[170:173], v[186:189], v[52:55]
	v_mfma_f32_16x16x32_bf16 v[48:51], v[178:181], v[186:189], v[48:51]
	v_mfma_f32_16x16x32_bf16 v[36:39], v[170:173], v[194:197], v[36:39]
	v_mfma_f32_16x16x32_bf16 v[32:35], v[178:181], v[194:197], v[32:35]
	v_mfma_f32_16x16x32_bf16 v[20:23], v[170:173], v[202:205], v[20:23]
	v_mfma_f32_16x16x32_bf16 v[16:19], v[178:181], v[202:205], v[16:19]
	v_mfma_f32_16x16x32_bf16 v[4:7], v[170:173], v[210:213], v[4:7]
	v_mfma_f32_16x16x32_bf16 v[0:3], v[178:181], v[210:213], v[0:3]
	s_setprio 0
	s_barrier
	s_add_i32 s44, s44, 2
	s_add_u32 s22, s22, 0x100
	s_addc_u32 s23, s23, 0
	s_add_u32 s42, s42, 0x100
	s_addc_u32 s43, s43, 0
	s_cmp_gt_u32 s44, 13
	s_cbranch_scc0 .LBB0_1700
	s_and_b64 vcc, exec, s[8:9]
	s_cbranch_vccz .LBB0_1703
	s_barrier
